# GEMM epilogue stores lane-coalesced with 4 data ds_bpermutes per store and the address formed arithmetically (no address bpermute); K-loop opening barrier 2 MFMAs down
# speedup vs baseline: 1.0083x; 1.0062x over previous
; __device__ __forceinline__ unsigned cvt_pk_bf16(float lo, float hi) { unsigned r; asm volatile("v_cvt_pk_bf16_f32 %0, %1, %2" : "=v"(r) : "v"(lo), "v"(hi)); return r; }
; #define EPI_FENCE() asm volatile("" ::: "memory")
; __device__ __forceinline__ float gelu_tanh(float x) {
;     const float y = x * (0.7978845608028654f + 0.7978845608028654f * 0.044715f * x * x);
;     const float e = __builtin_amdgcn_exp2f(-2.0f * 1.4426950408889634f * y);
;     return x * __builtin_amdgcn_rcpf(1.0f + e);
; }
;     __device__ __forceinline__ void operator()(const f32x4 (&acc)[2][2][4][2], const Unit& u, int wr, int wc, int fr, int fq) const {
;     ...
;         } else {
;             EPI_FENCE();
; #pragma unroll
;             for (int i = 0; i < 8; ++i) {
;                 const int ai = i >> 2, m = i & 3; bf16_t* rowp = Z + (size_t)(row0 + ai * HALF + m * 16) * 5120 + col0;
; #pragma unroll
;                 for (int bj = 0; bj < 2; ++bj) {
;                     f32x4 v0 = acc[ai][bj][m][0] * rs[i], v1 = acc[ai][bj][m][1] * rs[i];
;                     if (kind == 2) {
; #pragma unroll
;                         for (int e = 0; e < 4; ++e) { v0[e] = gelu_tanh(v0[e]); v1[e] = gelu_tanh(v1[e]); }
;                     }
;                     u32x4 w; w.x = cvt_pk_bf16(v0[0], v0[1]); w.y = cvt_pk_bf16(v0[2], v0[3]); w.z = cvt_pk_bf16(v1[0], v1[1]); w.w = cvt_pk_bf16(v1[2], v1[3]);
;                     *(u32x4*)(rowp + bj * HALF) = w;
.LBB0_122:
	v_mbcnt_lo_u32_b32 v244, -1, 0
	v_mbcnt_hi_u32_b32 v244, -1, v244
	v_lshrrev_b32_e32 v242, 2, v244
	v_and_b32_e32 v245, 15, v244
	v_sub_u32_e32 v242, v242, v245
	v_mov_b32_e32 v245, 0x2800
	v_mul_i32_i24_e32 v242, v242, v245
	v_and_b32_e32 v245, 3, v244
	v_lshrrev_b32_e32 v244, 4, v244
	v_sub_u32_e32 v245, v245, v244
	v_lshl_add_u32 v242, v245, 4, v242
	v_ashrrev_i32_e32 v243, 31, v242
	s_cmp_gt_i32 s41, 11
	s_cselect_b64 s[2:3], -1, 0
	s_and_b32 s4, s41, -4
	s_cmp_eq_u32 s4, 4
	s_cselect_b64 s[4:5], -1, 0
	s_cmp_eq_u32 s33, s26
	s_cselect_b32 s15, 0x200, s56
	s_cmp_lg_u32 s33, s25
	s_cselect_b32 s15, s15, 0x100
	s_cmp_lg_u32 s33, s24
	s_cselect_b32 s15, s15, 0
	v_lshl_add_u32 v130, s15, 2, v204
	ds_read2_b32 v[186:187], v130 offset1:16
	ds_read2_b32 v[184:185], v130 offset0:32 offset1:48
	ds_read2_b32 v[182:183], v130 offset0:128 offset1:144
	ds_read2_b32 v[180:181], v130 offset0:160 offset1:176
	v_lshl_add_u32 v188, s41, 8, v203
	s_or_b64 s[22:23], s[2:3], s[4:5]
	v_lshl_add_u32 v206, s33, 8, v1
	v_ashrrev_i32_e32 v189, 31, v188
	s_mov_b64 s[4:5], -1
	s_and_b64 vcc, exec, s[22:23]
	s_cbranch_vccz .LBB0_156
	v_cndmask_b32_e64 v130, 0, 1, s[2:3]
	s_waitcnt lgkmcnt(0)
	v_pk_mul_f32 v[132:133], v[128:129], v[186:187] op_sel_hi:[1,0]
	v_pk_mul_f32 v[136:137], v[126:127], v[186:187] op_sel_hi:[1,0]
	v_pk_mul_f32 v[134:135], v[124:125], v[186:187] op_sel_hi:[1,0]
	v_cmp_ne_u32_e64 s[4:5], 1, v130
	s_andn2_b64 vcc, exec, s[2:3]
	v_pk_mul_f32 v[138:139], v[122:123], v[186:187] op_sel_hi:[1,0]
	s_cbranch_vccnz .LBB0_125
	v_mul_f32_e32 v131, 0x3d122279, v138
	v_fmaak_f32 v131, v138, v131, 0x3f4c422a
	v_mul_f32_e32 v131, v138, v131
	v_mul_f32_e32 v131, 0xc038aa3b, v131
	v_exp_f32_e32 v131, v131
	v_mul_f32_e32 v130, 0x3d122279, v136
	v_fmaak_f32 v130, v136, v130, 0x3f4c422a
	v_mul_f32_e32 v130, v136, v130
	v_add_f32_e32 v131, 1.0, v131
	v_rcp_f32_e32 v140, v131
	v_mul_f32_e32 v131, 0x3d122279, v137
	v_fmaak_f32 v131, v137, v131, 0x3f4c422a
	v_mul_f32_e32 v131, v137, v131
	v_mul_f32_e32 v130, 0xc038aa3b, v130
	v_mul_f32_e32 v131, 0xc038aa3b, v131
	v_exp_f32_e32 v130, v130
	v_exp_f32_e32 v131, v131
	v_mul_f32_e32 v143, 0x3d122279, v134
	v_fmaak_f32 v143, v134, v143, 0x3f4c422a
	v_mul_f32_e32 v143, v134, v143
	v_mul_f32_e32 v143, 0xc038aa3b, v143
	v_add_f32_e32 v130, 1.0, v130
	v_add_f32_e32 v131, 1.0, v131
	v_exp_f32_e32 v143, v143
	v_rcp_f32_e32 v130, v130
	v_rcp_f32_e32 v131, v131
	v_mul_f32_e32 v141, 0x3d122279, v139
	v_add_f32_e32 v143, 1.0, v143
	v_mul_f32_e32 v142, 0x3d122279, v132
	v_rcp_f32_e32 v144, v143
	v_mul_f32_e32 v143, 0x3d122279, v133
	v_pk_mul_f32 v[136:137], v[136:137], v[130:131]
	v_mul_f32_e32 v130, 0x3d122279, v135
	v_fmaak_f32 v141, v139, v141, 0x3f4c422a
	v_fmaak_f32 v142, v132, v142, 0x3f4c422a
	v_fmaak_f32 v143, v133, v143, 0x3f4c422a
	v_fmaak_f32 v130, v135, v130, 0x3f4c422a
	v_mul_f32_e32 v141, v139, v141
	v_mul_f32_e32 v142, v132, v142
	v_mul_f32_e32 v143, v133, v143
	v_mul_f32_e32 v130, v135, v130
	v_mul_f32_e32 v141, 0xc038aa3b, v141
	v_mul_f32_e32 v142, 0xc038aa3b, v142
	v_mul_f32_e32 v143, 0xc038aa3b, v143
	v_mul_f32_e32 v130, 0xc038aa3b, v130
	v_exp_f32_e32 v141, v141
	v_exp_f32_e32 v142, v142
	v_exp_f32_e32 v143, v143
	v_exp_f32_e32 v130, v130
	v_add_f32_e32 v141, 1.0, v141
	v_add_f32_e32 v142, 1.0, v142
	v_add_f32_e32 v143, 1.0, v143
	v_add_f32_e32 v130, 1.0, v130
	v_rcp_f32_e32 v141, v141
	v_rcp_f32_e32 v142, v142
	v_rcp_f32_e32 v143, v143
	v_rcp_f32_e32 v145, v130
	v_pk_mul_f32 v[138:139], v[138:139], v[140:141]
	v_pk_mul_f32 v[132:133], v[132:133], v[142:143]
	v_pk_mul_f32 v[134:135], v[134:135], v[144:145]
.LBB0_125:
	v_mov_b64_e32 v[130:131], s[8:9]
	v_mad_i64_i32 v[130:131], s[2:3], v206, s59, v[130:131]
	v_mov_b32_e32 v140, v186
	v_mov_b32_e32 v141, v186
	v_lshl_add_u64 v[130:131], v[188:189], 1, v[130:131]
	v_cvt_pk_bf16_f32 v136, v136, v137
	v_cvt_pk_bf16_f32 v137, v132, v133
	v_cvt_pk_bf16_f32 v138, v138, v139
	v_cvt_pk_bf16_f32 v139, v134, v135
	v_mov_b32_e32 v134, v186
	v_mov_b32_e32 v135, v186
	ds_bpermute_b32 v226, v255, v136
	ds_bpermute_b32 v227, v255, v137
	ds_bpermute_b32 v228, v255, v138
	ds_bpermute_b32 v229, v255, v139
	v_lshl_add_u64 v[224:225], v[130:131], 0, v[242:243]
	s_waitcnt lgkmcnt(0)
	global_store_dwordx4 v[224:225], v[226:229], off
	v_pk_mul_f32 v[132:133], v[120:121], v[134:135]
	v_pk_mul_f32 v[134:135], v[116:117], v[134:135]
	v_pk_mul_f32 v[136:137], v[118:119], v[140:141]
	s_and_b64 vcc, exec, s[4:5]
	v_pk_mul_f32 v[138:139], v[114:115], v[140:141]
	s_cbranch_vccnz .LBB0_127
	v_mul_f32_e32 v141, 0x3d122279, v138
	v_fmaak_f32 v141, v138, v141, 0x3f4c422a
	v_mul_f32_e32 v141, v138, v141
	v_mul_f32_e32 v141, 0xc038aa3b, v141
	v_exp_f32_e32 v141, v141
	v_mul_f32_e32 v140, 0x3d122279, v136
	v_fmaak_f32 v140, v136, v140, 0x3f4c422a
	v_mul_f32_e32 v140, v136, v140
	v_add_f32_e32 v141, 1.0, v141
	v_rcp_f32_e32 v142, v141
	v_mul_f32_e32 v141, 0x3d122279, v137
	v_fmaak_f32 v141, v137, v141, 0x3f4c422a
	v_mul_f32_e32 v141, v137, v141
	v_mul_f32_e32 v140, 0xc038aa3b, v140
	v_mul_f32_e32 v141, 0xc038aa3b, v141
	v_exp_f32_e32 v140, v140
	v_exp_f32_e32 v141, v141
	v_mul_f32_e32 v145, 0x3d122279, v134
	v_fmaak_f32 v145, v134, v145, 0x3f4c422a
	v_mul_f32_e32 v145, v134, v145
	v_mul_f32_e32 v145, 0xc038aa3b, v145
	v_add_f32_e32 v140, 1.0, v140
	v_add_f32_e32 v141, 1.0, v141
	v_exp_f32_e32 v145, v145
	v_rcp_f32_e32 v140, v140
	v_rcp_f32_e32 v141, v141
	v_mul_f32_e32 v143, 0x3d122279, v139
	v_add_f32_e32 v145, 1.0, v145
	v_mul_f32_e32 v144, 0x3d122279, v132
	v_rcp_f32_e32 v146, v145
	v_mul_f32_e32 v145, 0x3d122279, v133
	v_pk_mul_f32 v[136:137], v[136:137], v[140:141]
	v_mul_f32_e32 v140, 0x3d122279, v135
	v_fmaak_f32 v143, v139, v143, 0x3f4c422a
	v_fmaak_f32 v144, v132, v144, 0x3f4c422a
	v_fmaak_f32 v145, v133, v145, 0x3f4c422a
	v_fmaak_f32 v140, v135, v140, 0x3f4c422a
	v_mul_f32_e32 v143, v139, v143
	v_mul_f32_e32 v144, v132, v144
	v_mul_f32_e32 v145, v133, v145
	v_mul_f32_e32 v140, v135, v140
	v_mul_f32_e32 v143, 0xc038aa3b, v143
	v_mul_f32_e32 v144, 0xc038aa3b, v144
	v_mul_f32_e32 v145, 0xc038aa3b, v145
	v_mul_f32_e32 v140, 0xc038aa3b, v140
	v_exp_f32_e32 v143, v143
	v_exp_f32_e32 v144, v144
	v_exp_f32_e32 v145, v145
	v_exp_f32_e32 v140, v140
	v_add_f32_e32 v143, 1.0, v143
	v_add_f32_e32 v144, 1.0, v144
	v_add_f32_e32 v145, 1.0, v145
	v_add_f32_e32 v140, 1.0, v140
	v_rcp_f32_e32 v143, v143
	v_rcp_f32_e32 v144, v144
	v_rcp_f32_e32 v145, v145
	v_rcp_f32_e32 v147, v140
	v_pk_mul_f32 v[138:139], v[138:139], v[142:143]
	v_pk_mul_f32 v[132:133], v[132:133], v[144:145]
	v_pk_mul_f32 v[134:135], v[134:135], v[146:147]
; __device__ __forceinline__ unsigned cvt_pk_bf16(float lo, float hi) { unsigned r; asm volatile("v_cvt_pk_bf16_f32 %0, %1, %2" : "=v"(r) : "v"(lo), "v"(hi)); return r; }
; #define EPI_FENCE() asm volatile("" ::: "memory")
; __device__ __forceinline__ float gelu_tanh(float x) {
;     const float y = x * (0.7978845608028654f + 0.7978845608028654f * 0.044715f * x * x);
;     const float e = __builtin_amdgcn_exp2f(-2.0f * 1.4426950408889634f * y);
;     return x * __builtin_amdgcn_rcpf(1.0f + e);
; }
;     __device__ __forceinline__ void operator()(const f32x4 (&acc)[2][2][4][2], const Unit& u, int wr, int wc, int fr, int fq) const {
;     ...
;         } else {
;             EPI_FENCE();
; #pragma unroll
;             for (int i = 0; i < 8; ++i) {
;                 const int ai = i >> 2, m = i & 3; bf16_t* rowp = Z + (size_t)(row0 + ai * HALF + m * 16) * 5120 + col0;
; #pragma unroll
;                 for (int bj = 0; bj < 2; ++bj) {
;                     f32x4 v0 = acc[ai][bj][m][0] * rs[i], v1 = acc[ai][bj][m][1] * rs[i];
;                     if (kind == 2) {
; #pragma unroll
;                         for (int e = 0; e < 4; ++e) { v0[e] = gelu_tanh(v0[e]); v1[e] = gelu_tanh(v1[e]); }
;                     }
;                     u32x4 w; w.x = cvt_pk_bf16(v0[0], v0[1]); w.y = cvt_pk_bf16(v0[2], v0[3]); w.z = cvt_pk_bf16(v1[0], v1[1]); w.w = cvt_pk_bf16(v1[2], v1[3]);
;                     *(u32x4*)(rowp + bj * HALF) = w;
.LBB0_127:
	v_cvt_pk_bf16_f32 v136, v136, v137
	v_cvt_pk_bf16_f32 v137, v132, v133
	v_cvt_pk_bf16_f32 v138, v138, v139
	s_nop 0
	v_cvt_pk_bf16_f32 v139, v134, v135
	ds_bpermute_b32 v226, v255, v136
	ds_bpermute_b32 v227, v255, v137
	ds_bpermute_b32 v228, v255, v138
	ds_bpermute_b32 v229, v255, v139
	v_lshl_add_u64 v[224:225], v[130:131], 0, v[242:243]
	s_waitcnt lgkmcnt(0)
	global_store_dwordx4 v[224:225], v[226:229], off offset:256
	v_mov_b32_e32 v130, v187
	v_pk_mul_f32 v[132:133], v[112:113], v[130:131] op_sel_hi:[1,0]
	v_pk_mul_f32 v[136:137], v[110:111], v[130:131] op_sel_hi:[1,0]
	v_pk_mul_f32 v[134:135], v[108:109], v[130:131] op_sel_hi:[1,0]
	s_and_b64 vcc, exec, s[4:5]
	v_pk_mul_f32 v[138:139], v[106:107], v[130:131] op_sel_hi:[1,0]
	s_cbranch_vccnz .LBB0_129
	v_mul_f32_e32 v131, 0x3d122279, v138
	v_fmaak_f32 v131, v138, v131, 0x3f4c422a
	v_mul_f32_e32 v131, v138, v131
	v_mul_f32_e32 v131, 0xc038aa3b, v131
	v_exp_f32_e32 v131, v131
	v_mul_f32_e32 v130, 0x3d122279, v136
	v_fmaak_f32 v130, v136, v130, 0x3f4c422a
	v_mul_f32_e32 v130, v136, v130
	v_add_f32_e32 v131, 1.0, v131
	v_rcp_f32_e32 v140, v131
	v_mul_f32_e32 v131, 0x3d122279, v137
	v_fmaak_f32 v131, v137, v131, 0x3f4c422a
	v_mul_f32_e32 v131, v137, v131
	v_mul_f32_e32 v130, 0xc038aa3b, v130
	v_mul_f32_e32 v131, 0xc038aa3b, v131
	v_exp_f32_e32 v130, v130
	v_exp_f32_e32 v131, v131
	v_mul_f32_e32 v143, 0x3d122279, v134
	v_fmaak_f32 v143, v134, v143, 0x3f4c422a
	v_mul_f32_e32 v143, v134, v143
	v_mul_f32_e32 v143, 0xc038aa3b, v143
	v_add_f32_e32 v130, 1.0, v130
	v_add_f32_e32 v131, 1.0, v131
	v_exp_f32_e32 v143, v143
	v_rcp_f32_e32 v130, v130
	v_rcp_f32_e32 v131, v131
	v_mul_f32_e32 v141, 0x3d122279, v139
	v_add_f32_e32 v143, 1.0, v143
	v_mul_f32_e32 v142, 0x3d122279, v132
	v_rcp_f32_e32 v144, v143
	v_mul_f32_e32 v143, 0x3d122279, v133
	v_pk_mul_f32 v[136:137], v[136:137], v[130:131]
	v_mul_f32_e32 v130, 0x3d122279, v135
	v_fmaak_f32 v141, v139, v141, 0x3f4c422a
	v_fmaak_f32 v142, v132, v142, 0x3f4c422a
	v_fmaak_f32 v143, v133, v143, 0x3f4c422a
	v_fmaak_f32 v130, v135, v130, 0x3f4c422a
	v_mul_f32_e32 v141, v139, v141
	v_mul_f32_e32 v142, v132, v142
	v_mul_f32_e32 v143, v133, v143
	v_mul_f32_e32 v130, v135, v130
	v_mul_f32_e32 v141, 0xc038aa3b, v141
	v_mul_f32_e32 v142, 0xc038aa3b, v142
	v_mul_f32_e32 v143, 0xc038aa3b, v143
	v_mul_f32_e32 v130, 0xc038aa3b, v130
	v_exp_f32_e32 v141, v141
	v_exp_f32_e32 v142, v142
	v_exp_f32_e32 v143, v143
	v_exp_f32_e32 v130, v130
	v_add_f32_e32 v141, 1.0, v141
	v_add_f32_e32 v142, 1.0, v142
	v_add_f32_e32 v143, 1.0, v143
	v_add_f32_e32 v130, 1.0, v130
	v_rcp_f32_e32 v141, v141
	v_rcp_f32_e32 v142, v142
	v_rcp_f32_e32 v143, v143
	v_rcp_f32_e32 v145, v130
	v_pk_mul_f32 v[138:139], v[138:139], v[140:141]
	v_pk_mul_f32 v[132:133], v[132:133], v[142:143]
	v_pk_mul_f32 v[134:135], v[134:135], v[144:145]
.LBB0_129:
	v_or_b32_e32 v142, 16, v206
	v_mov_b64_e32 v[130:131], s[8:9]
	v_mad_i64_i32 v[130:131], s[2:3], v142, s59, v[130:131]
	v_mov_b32_e32 v140, v187
	v_mov_b32_e32 v141, v187
	v_lshl_add_u64 v[130:131], v[188:189], 1, v[130:131]
	v_cvt_pk_bf16_f32 v136, v136, v137
	v_cvt_pk_bf16_f32 v137, v132, v133
	v_cvt_pk_bf16_f32 v138, v138, v139
	v_cvt_pk_bf16_f32 v139, v134, v135
	v_mov_b32_e32 v134, v187
	v_mov_b32_e32 v135, v187
	ds_bpermute_b32 v226, v255, v136
	ds_bpermute_b32 v227, v255, v137
	ds_bpermute_b32 v228, v255, v138
	ds_bpermute_b32 v229, v255, v139
	v_lshl_add_u64 v[224:225], v[130:131], 0, v[242:243]
	s_waitcnt lgkmcnt(0)
	global_store_dwordx4 v[224:225], v[226:229], off
	v_pk_mul_f32 v[132:133], v[104:105], v[134:135]
	v_pk_mul_f32 v[134:135], v[100:101], v[134:135]
	v_pk_mul_f32 v[136:137], v[102:103], v[140:141]
	s_and_b64 vcc, exec, s[4:5]
	v_pk_mul_f32 v[138:139], v[98:99], v[140:141]
	s_cbranch_vccnz .LBB0_131
	v_mul_f32_e32 v141, 0x3d122279, v138
	v_fmaak_f32 v141, v138, v141, 0x3f4c422a
	v_mul_f32_e32 v141, v138, v141
	v_mul_f32_e32 v141, 0xc038aa3b, v141
	v_exp_f32_e32 v141, v141
	v_mul_f32_e32 v140, 0x3d122279, v136
	v_fmaak_f32 v140, v136, v140, 0x3f4c422a
	v_mul_f32_e32 v140, v136, v140
	v_add_f32_e32 v141, 1.0, v141
	v_rcp_f32_e32 v142, v141
	v_mul_f32_e32 v141, 0x3d122279, v137
	v_fmaak_f32 v141, v137, v141, 0x3f4c422a
	v_mul_f32_e32 v141, v137, v141
	v_mul_f32_e32 v140, 0xc038aa3b, v140
	v_mul_f32_e32 v141, 0xc038aa3b, v141
	v_exp_f32_e32 v140, v140
	v_exp_f32_e32 v141, v141
	v_mul_f32_e32 v145, 0x3d122279, v134
	v_fmaak_f32 v145, v134, v145, 0x3f4c422a
	v_mul_f32_e32 v145, v134, v145
	v_mul_f32_e32 v145, 0xc038aa3b, v145
	v_add_f32_e32 v140, 1.0, v140
	v_add_f32_e32 v141, 1.0, v141
	v_exp_f32_e32 v145, v145
	v_rcp_f32_e32 v140, v140
	v_rcp_f32_e32 v141, v141
	v_mul_f32_e32 v143, 0x3d122279, v139
	v_add_f32_e32 v145, 1.0, v145
	v_mul_f32_e32 v144, 0x3d122279, v132
	v_rcp_f32_e32 v146, v145
	v_mul_f32_e32 v145, 0x3d122279, v133
	v_pk_mul_f32 v[136:137], v[136:137], v[140:141]
	v_mul_f32_e32 v140, 0x3d122279, v135
	v_fmaak_f32 v143, v139, v143, 0x3f4c422a
	v_fmaak_f32 v144, v132, v144, 0x3f4c422a
	v_fmaak_f32 v145, v133, v145, 0x3f4c422a
	v_fmaak_f32 v140, v135, v140, 0x3f4c422a
	v_mul_f32_e32 v143, v139, v143
	v_mul_f32_e32 v144, v132, v144
	v_mul_f32_e32 v145, v133, v145
	v_mul_f32_e32 v140, v135, v140
	v_mul_f32_e32 v143, 0xc038aa3b, v143
	v_mul_f32_e32 v144, 0xc038aa3b, v144
	v_mul_f32_e32 v145, 0xc038aa3b, v145
	v_mul_f32_e32 v140, 0xc038aa3b, v140
	v_exp_f32_e32 v143, v143
	v_exp_f32_e32 v144, v144
	v_exp_f32_e32 v145, v145
	v_exp_f32_e32 v140, v140
	v_add_f32_e32 v143, 1.0, v143
	v_add_f32_e32 v144, 1.0, v144
	v_add_f32_e32 v145, 1.0, v145
	v_add_f32_e32 v140, 1.0, v140
	v_rcp_f32_e32 v143, v143
	v_rcp_f32_e32 v144, v144
	v_rcp_f32_e32 v145, v145
	v_rcp_f32_e32 v147, v140
	v_pk_mul_f32 v[138:139], v[138:139], v[142:143]
	v_pk_mul_f32 v[132:133], v[132:133], v[144:145]
	v_pk_mul_f32 v[134:135], v[134:135], v[146:147]
; __device__ __forceinline__ unsigned cvt_pk_bf16(float lo, float hi) { unsigned r; asm volatile("v_cvt_pk_bf16_f32 %0, %1, %2" : "=v"(r) : "v"(lo), "v"(hi)); return r; }
; #define EPI_FENCE() asm volatile("" ::: "memory")
; __device__ __forceinline__ float gelu_tanh(float x) {
;     const float y = x * (0.7978845608028654f + 0.7978845608028654f * 0.044715f * x * x);
;     const float e = __builtin_amdgcn_exp2f(-2.0f * 1.4426950408889634f * y);
;     return x * __builtin_amdgcn_rcpf(1.0f + e);
; }
;     __device__ __forceinline__ void operator()(const f32x4 (&acc)[2][2][4][2], const Unit& u, int wr, int wc, int fr, int fq) const {
;     ...
;         } else {
;             EPI_FENCE();
; #pragma unroll
;             for (int i = 0; i < 8; ++i) {
;                 const int ai = i >> 2, m = i & 3; bf16_t* rowp = Z + (size_t)(row0 + ai * HALF + m * 16) * 5120 + col0;
; #pragma unroll
;                 for (int bj = 0; bj < 2; ++bj) {
;                     f32x4 v0 = acc[ai][bj][m][0] * rs[i], v1 = acc[ai][bj][m][1] * rs[i];
;                     if (kind == 2) {
; #pragma unroll
;                         for (int e = 0; e < 4; ++e) { v0[e] = gelu_tanh(v0[e]); v1[e] = gelu_tanh(v1[e]); }
;                     }
;                     u32x4 w; w.x = cvt_pk_bf16(v0[0], v0[1]); w.y = cvt_pk_bf16(v0[2], v0[3]); w.z = cvt_pk_bf16(v1[0], v1[1]); w.w = cvt_pk_bf16(v1[2], v1[3]);
;                     *(u32x4*)(rowp + bj * HALF) = w;
.LBB0_131:
	v_cvt_pk_bf16_f32 v136, v136, v137
	v_cvt_pk_bf16_f32 v137, v132, v133
	v_cvt_pk_bf16_f32 v138, v138, v139
	s_nop 0
	v_cvt_pk_bf16_f32 v139, v134, v135
	ds_bpermute_b32 v226, v255, v136
	ds_bpermute_b32 v227, v255, v137
	ds_bpermute_b32 v228, v255, v138
	ds_bpermute_b32 v229, v255, v139
	v_lshl_add_u64 v[224:225], v[130:131], 0, v[242:243]
	s_waitcnt lgkmcnt(0)
	global_store_dwordx4 v[224:225], v[226:229], off offset:256
	v_pk_mul_f32 v[132:133], v[96:97], v[184:185] op_sel_hi:[1,0]
	v_pk_mul_f32 v[134:135], v[92:93], v[184:185] op_sel_hi:[1,0]
	v_pk_mul_f32 v[136:137], v[94:95], v[184:185] op_sel_hi:[1,0]
	s_and_b64 vcc, exec, s[4:5]
	v_pk_mul_f32 v[138:139], v[90:91], v[184:185] op_sel_hi:[1,0]
	s_cbranch_vccnz .LBB0_133
	v_mul_f32_e32 v131, 0x3d122279, v138
	v_fmaak_f32 v131, v138, v131, 0x3f4c422a
	v_mul_f32_e32 v131, v138, v131
	v_mul_f32_e32 v131, 0xc038aa3b, v131
	v_exp_f32_e32 v131, v131
	v_mul_f32_e32 v130, 0x3d122279, v136
	v_fmaak_f32 v130, v136, v130, 0x3f4c422a
	v_mul_f32_e32 v130, v136, v130
	v_add_f32_e32 v131, 1.0, v131
	v_rcp_f32_e32 v140, v131
	v_mul_f32_e32 v131, 0x3d122279, v137
	v_fmaak_f32 v131, v137, v131, 0x3f4c422a
	v_mul_f32_e32 v131, v137, v131
	v_mul_f32_e32 v130, 0xc038aa3b, v130
	v_mul_f32_e32 v131, 0xc038aa3b, v131
	v_exp_f32_e32 v130, v130
	v_exp_f32_e32 v131, v131
	v_mul_f32_e32 v143, 0x3d122279, v134
	v_fmaak_f32 v143, v134, v143, 0x3f4c422a
	v_mul_f32_e32 v143, v134, v143
	v_mul_f32_e32 v143, 0xc038aa3b, v143
	v_add_f32_e32 v130, 1.0, v130
	v_add_f32_e32 v131, 1.0, v131
	v_exp_f32_e32 v143, v143
	v_rcp_f32_e32 v130, v130
	v_rcp_f32_e32 v131, v131
	v_mul_f32_e32 v141, 0x3d122279, v139
	v_add_f32_e32 v143, 1.0, v143
	v_mul_f32_e32 v142, 0x3d122279, v132
	v_rcp_f32_e32 v144, v143
	v_mul_f32_e32 v143, 0x3d122279, v133
	v_pk_mul_f32 v[136:137], v[136:137], v[130:131]
	v_mul_f32_e32 v130, 0x3d122279, v135
	v_fmaak_f32 v141, v139, v141, 0x3f4c422a
	v_fmaak_f32 v142, v132, v142, 0x3f4c422a
	v_fmaak_f32 v143, v133, v143, 0x3f4c422a
	v_fmaak_f32 v130, v135, v130, 0x3f4c422a
	v_mul_f32_e32 v141, v139, v141
	v_mul_f32_e32 v142, v132, v142
	v_mul_f32_e32 v143, v133, v143
	v_mul_f32_e32 v130, v135, v130
	v_mul_f32_e32 v141, 0xc038aa3b, v141
	v_mul_f32_e32 v142, 0xc038aa3b, v142
	v_mul_f32_e32 v143, 0xc038aa3b, v143
	v_mul_f32_e32 v130, 0xc038aa3b, v130
	v_exp_f32_e32 v141, v141
	v_exp_f32_e32 v142, v142
	v_exp_f32_e32 v143, v143
	v_exp_f32_e32 v130, v130
	v_add_f32_e32 v141, 1.0, v141
	v_add_f32_e32 v142, 1.0, v142
	v_add_f32_e32 v143, 1.0, v143
	v_add_f32_e32 v130, 1.0, v130
	v_rcp_f32_e32 v141, v141
	v_rcp_f32_e32 v142, v142
	v_rcp_f32_e32 v143, v143
	v_rcp_f32_e32 v145, v130
	v_pk_mul_f32 v[138:139], v[138:139], v[140:141]
	v_pk_mul_f32 v[132:133], v[132:133], v[142:143]
	v_pk_mul_f32 v[134:135], v[134:135], v[144:145]
.LBB0_133:
	v_or_b32_e32 v142, 32, v206
	v_mov_b64_e32 v[130:131], s[8:9]
	v_mad_i64_i32 v[130:131], s[2:3], v142, s59, v[130:131]
	v_mov_b32_e32 v140, v184
	v_mov_b32_e32 v141, v184
	v_lshl_add_u64 v[130:131], v[188:189], 1, v[130:131]
	v_cvt_pk_bf16_f32 v136, v136, v137
	v_cvt_pk_bf16_f32 v137, v132, v133
	v_cvt_pk_bf16_f32 v138, v138, v139
	v_cvt_pk_bf16_f32 v139, v134, v135
	v_mov_b32_e32 v134, v184
	v_mov_b32_e32 v135, v184
	ds_bpermute_b32 v226, v255, v136
	ds_bpermute_b32 v227, v255, v137
	ds_bpermute_b32 v228, v255, v138
	ds_bpermute_b32 v229, v255, v139
	v_lshl_add_u64 v[224:225], v[130:131], 0, v[242:243]
	s_waitcnt lgkmcnt(0)
	global_store_dwordx4 v[224:225], v[226:229], off
	v_pk_mul_f32 v[132:133], v[88:89], v[134:135]
	v_pk_mul_f32 v[134:135], v[84:85], v[134:135]
	v_pk_mul_f32 v[136:137], v[86:87], v[140:141]
	s_and_b64 vcc, exec, s[4:5]
	v_pk_mul_f32 v[138:139], v[82:83], v[140:141]
	s_cbranch_vccnz .LBB0_135
	v_mul_f32_e32 v141, 0x3d122279, v138
	v_fmaak_f32 v141, v138, v141, 0x3f4c422a
	v_mul_f32_e32 v141, v138, v141
	v_mul_f32_e32 v141, 0xc038aa3b, v141
	v_exp_f32_e32 v141, v141
	v_mul_f32_e32 v140, 0x3d122279, v136
	v_fmaak_f32 v140, v136, v140, 0x3f4c422a
	v_mul_f32_e32 v140, v136, v140
	v_add_f32_e32 v141, 1.0, v141
	v_rcp_f32_e32 v142, v141
	v_mul_f32_e32 v141, 0x3d122279, v137
	v_fmaak_f32 v141, v137, v141, 0x3f4c422a
	v_mul_f32_e32 v141, v137, v141
	v_mul_f32_e32 v140, 0xc038aa3b, v140
	v_mul_f32_e32 v141, 0xc038aa3b, v141
	v_exp_f32_e32 v140, v140
	v_exp_f32_e32 v141, v141
	v_mul_f32_e32 v145, 0x3d122279, v134
	v_fmaak_f32 v145, v134, v145, 0x3f4c422a
	v_mul_f32_e32 v145, v134, v145
	v_mul_f32_e32 v145, 0xc038aa3b, v145
	v_add_f32_e32 v140, 1.0, v140
	v_add_f32_e32 v141, 1.0, v141
	v_exp_f32_e32 v145, v145
	v_rcp_f32_e32 v140, v140
	v_rcp_f32_e32 v141, v141
	v_mul_f32_e32 v143, 0x3d122279, v139
	v_add_f32_e32 v145, 1.0, v145
	v_mul_f32_e32 v144, 0x3d122279, v132
	v_rcp_f32_e32 v146, v145
	v_mul_f32_e32 v145, 0x3d122279, v133
	v_pk_mul_f32 v[136:137], v[136:137], v[140:141]
	v_mul_f32_e32 v140, 0x3d122279, v135
	v_fmaak_f32 v143, v139, v143, 0x3f4c422a
	v_fmaak_f32 v144, v132, v144, 0x3f4c422a
	v_fmaak_f32 v145, v133, v145, 0x3f4c422a
	v_fmaak_f32 v140, v135, v140, 0x3f4c422a
	v_mul_f32_e32 v143, v139, v143
	v_mul_f32_e32 v144, v132, v144
	v_mul_f32_e32 v145, v133, v145
	v_mul_f32_e32 v140, v135, v140
	v_mul_f32_e32 v143, 0xc038aa3b, v143
	v_mul_f32_e32 v144, 0xc038aa3b, v144
	v_mul_f32_e32 v145, 0xc038aa3b, v145
	v_mul_f32_e32 v140, 0xc038aa3b, v140
	v_exp_f32_e32 v143, v143
	v_exp_f32_e32 v144, v144
	v_exp_f32_e32 v145, v145
	v_exp_f32_e32 v140, v140
	v_add_f32_e32 v143, 1.0, v143
	v_add_f32_e32 v144, 1.0, v144
	v_add_f32_e32 v145, 1.0, v145
	v_add_f32_e32 v140, 1.0, v140
	v_rcp_f32_e32 v143, v143
	v_rcp_f32_e32 v144, v144
	v_rcp_f32_e32 v145, v145
	v_rcp_f32_e32 v147, v140
	v_pk_mul_f32 v[138:139], v[138:139], v[142:143]
	v_pk_mul_f32 v[132:133], v[132:133], v[144:145]
	v_pk_mul_f32 v[134:135], v[134:135], v[146:147]
; __device__ __forceinline__ unsigned cvt_pk_bf16(float lo, float hi) { unsigned r; asm volatile("v_cvt_pk_bf16_f32 %0, %1, %2" : "=v"(r) : "v"(lo), "v"(hi)); return r; }
; #define EPI_FENCE() asm volatile("" ::: "memory")
; __device__ __forceinline__ float gelu_tanh(float x) {
;     const float y = x * (0.7978845608028654f + 0.7978845608028654f * 0.044715f * x * x);
;     const float e = __builtin_amdgcn_exp2f(-2.0f * 1.4426950408889634f * y);
;     return x * __builtin_amdgcn_rcpf(1.0f + e);
; }
;     __device__ __forceinline__ void operator()(const f32x4 (&acc)[2][2][4][2], const Unit& u, int wr, int wc, int fr, int fq) const {
;     ...
;         } else {
;             EPI_FENCE();
; #pragma unroll
;             for (int i = 0; i < 8; ++i) {
;                 const int ai = i >> 2, m = i & 3; bf16_t* rowp = Z + (size_t)(row0 + ai * HALF + m * 16) * 5120 + col0;
; #pragma unroll
;                 for (int bj = 0; bj < 2; ++bj) {
;                     f32x4 v0 = acc[ai][bj][m][0] * rs[i], v1 = acc[ai][bj][m][1] * rs[i];
;                     if (kind == 2) {
; #pragma unroll
;                         for (int e = 0; e < 4; ++e) { v0[e] = gelu_tanh(v0[e]); v1[e] = gelu_tanh(v1[e]); }
;                     }
;                     u32x4 w; w.x = cvt_pk_bf16(v0[0], v0[1]); w.y = cvt_pk_bf16(v0[2], v0[3]); w.z = cvt_pk_bf16(v1[0], v1[1]); w.w = cvt_pk_bf16(v1[2], v1[3]);
;                     *(u32x4*)(rowp + bj * HALF) = w;
.LBB0_135:
	v_cvt_pk_bf16_f32 v136, v136, v137
	v_cvt_pk_bf16_f32 v137, v132, v133
	v_cvt_pk_bf16_f32 v138, v138, v139
	s_nop 0
	v_cvt_pk_bf16_f32 v139, v134, v135
	ds_bpermute_b32 v226, v255, v136
	ds_bpermute_b32 v227, v255, v137
	ds_bpermute_b32 v228, v255, v138
	ds_bpermute_b32 v229, v255, v139
	v_lshl_add_u64 v[224:225], v[130:131], 0, v[242:243]
	s_waitcnt lgkmcnt(0)
	global_store_dwordx4 v[224:225], v[226:229], off offset:256
	v_mov_b32_e32 v130, v185
	v_pk_mul_f32 v[132:133], v[80:81], v[130:131] op_sel_hi:[1,0]
	v_pk_mul_f32 v[136:137], v[78:79], v[130:131] op_sel_hi:[1,0]
	v_pk_mul_f32 v[134:135], v[76:77], v[130:131] op_sel_hi:[1,0]
	s_and_b64 vcc, exec, s[4:5]
	v_pk_mul_f32 v[138:139], v[74:75], v[130:131] op_sel_hi:[1,0]
	s_cbranch_vccnz .LBB0_137
	v_mul_f32_e32 v131, 0x3d122279, v138
	v_fmaak_f32 v131, v138, v131, 0x3f4c422a
	v_mul_f32_e32 v131, v138, v131
	v_mul_f32_e32 v131, 0xc038aa3b, v131
	v_exp_f32_e32 v131, v131
	v_mul_f32_e32 v130, 0x3d122279, v136
	v_fmaak_f32 v130, v136, v130, 0x3f4c422a
	v_mul_f32_e32 v130, v136, v130
	v_add_f32_e32 v131, 1.0, v131
	v_rcp_f32_e32 v140, v131
	v_mul_f32_e32 v131, 0x3d122279, v137
	v_fmaak_f32 v131, v137, v131, 0x3f4c422a
	v_mul_f32_e32 v131, v137, v131
	v_mul_f32_e32 v130, 0xc038aa3b, v130
	v_mul_f32_e32 v131, 0xc038aa3b, v131
	v_exp_f32_e32 v130, v130
	v_exp_f32_e32 v131, v131
	v_mul_f32_e32 v143, 0x3d122279, v134
	v_fmaak_f32 v143, v134, v143, 0x3f4c422a
	v_mul_f32_e32 v143, v134, v143
	v_mul_f32_e32 v143, 0xc038aa3b, v143
	v_add_f32_e32 v130, 1.0, v130
	v_add_f32_e32 v131, 1.0, v131
	v_exp_f32_e32 v143, v143
	v_rcp_f32_e32 v130, v130
	v_rcp_f32_e32 v131, v131
	v_mul_f32_e32 v141, 0x3d122279, v139
	v_add_f32_e32 v143, 1.0, v143
	v_mul_f32_e32 v142, 0x3d122279, v132
	v_rcp_f32_e32 v144, v143
	v_mul_f32_e32 v143, 0x3d122279, v133
	v_pk_mul_f32 v[136:137], v[136:137], v[130:131]
	v_mul_f32_e32 v130, 0x3d122279, v135
	v_fmaak_f32 v141, v139, v141, 0x3f4c422a
	v_fmaak_f32 v142, v132, v142, 0x3f4c422a
	v_fmaak_f32 v143, v133, v143, 0x3f4c422a
	v_fmaak_f32 v130, v135, v130, 0x3f4c422a
	v_mul_f32_e32 v141, v139, v141
	v_mul_f32_e32 v142, v132, v142
	v_mul_f32_e32 v143, v133, v143
	v_mul_f32_e32 v130, v135, v130
	v_mul_f32_e32 v141, 0xc038aa3b, v141
	v_mul_f32_e32 v142, 0xc038aa3b, v142
	v_mul_f32_e32 v143, 0xc038aa3b, v143
	v_mul_f32_e32 v130, 0xc038aa3b, v130
	v_exp_f32_e32 v141, v141
	v_exp_f32_e32 v142, v142
	v_exp_f32_e32 v143, v143
	v_exp_f32_e32 v130, v130
	v_add_f32_e32 v141, 1.0, v141
	v_add_f32_e32 v142, 1.0, v142
	v_add_f32_e32 v143, 1.0, v143
	v_add_f32_e32 v130, 1.0, v130
	v_rcp_f32_e32 v141, v141
	v_rcp_f32_e32 v142, v142
	v_rcp_f32_e32 v143, v143
	v_rcp_f32_e32 v145, v130
	v_pk_mul_f32 v[138:139], v[138:139], v[140:141]
	v_pk_mul_f32 v[132:133], v[132:133], v[142:143]
	v_pk_mul_f32 v[134:135], v[134:135], v[144:145]
.LBB0_137:
	v_or_b32_e32 v142, 48, v206
	v_mov_b64_e32 v[130:131], s[8:9]
	v_mad_i64_i32 v[130:131], s[2:3], v142, s59, v[130:131]
	v_mov_b32_e32 v140, v185
	v_mov_b32_e32 v141, v185
	v_lshl_add_u64 v[130:131], v[188:189], 1, v[130:131]
	v_cvt_pk_bf16_f32 v136, v136, v137
	v_cvt_pk_bf16_f32 v137, v132, v133
	v_cvt_pk_bf16_f32 v138, v138, v139
	v_cvt_pk_bf16_f32 v139, v134, v135
	v_mov_b32_e32 v134, v185
	v_mov_b32_e32 v135, v185
	ds_bpermute_b32 v226, v255, v136
	ds_bpermute_b32 v227, v255, v137
	ds_bpermute_b32 v228, v255, v138
	ds_bpermute_b32 v229, v255, v139
	v_lshl_add_u64 v[224:225], v[130:131], 0, v[242:243]
	s_waitcnt lgkmcnt(0)
	global_store_dwordx4 v[224:225], v[226:229], off
	v_pk_mul_f32 v[132:133], v[72:73], v[134:135]
	v_pk_mul_f32 v[134:135], v[68:69], v[134:135]
	v_pk_mul_f32 v[136:137], v[70:71], v[140:141]
	s_and_b64 vcc, exec, s[4:5]
	v_pk_mul_f32 v[138:139], v[66:67], v[140:141]
	s_cbranch_vccnz .LBB0_139
	v_mul_f32_e32 v141, 0x3d122279, v138
	v_fmaak_f32 v141, v138, v141, 0x3f4c422a
	v_mul_f32_e32 v141, v138, v141
	v_mul_f32_e32 v141, 0xc038aa3b, v141
	v_exp_f32_e32 v141, v141
	v_mul_f32_e32 v140, 0x3d122279, v136
	v_fmaak_f32 v140, v136, v140, 0x3f4c422a
	v_mul_f32_e32 v140, v136, v140
	v_add_f32_e32 v141, 1.0, v141
	v_rcp_f32_e32 v142, v141
	v_mul_f32_e32 v141, 0x3d122279, v137
	v_fmaak_f32 v141, v137, v141, 0x3f4c422a
	v_mul_f32_e32 v141, v137, v141
	v_mul_f32_e32 v140, 0xc038aa3b, v140
	v_mul_f32_e32 v141, 0xc038aa3b, v141
	v_exp_f32_e32 v140, v140
	v_exp_f32_e32 v141, v141
	v_mul_f32_e32 v145, 0x3d122279, v134
	v_fmaak_f32 v145, v134, v145, 0x3f4c422a
	v_mul_f32_e32 v145, v134, v145
	v_mul_f32_e32 v145, 0xc038aa3b, v145
	v_add_f32_e32 v140, 1.0, v140
	v_add_f32_e32 v141, 1.0, v141
	v_exp_f32_e32 v145, v145
	v_rcp_f32_e32 v140, v140
	v_rcp_f32_e32 v141, v141
	v_mul_f32_e32 v143, 0x3d122279, v139
	v_add_f32_e32 v145, 1.0, v145
	v_mul_f32_e32 v144, 0x3d122279, v132
	v_rcp_f32_e32 v146, v145
	v_mul_f32_e32 v145, 0x3d122279, v133
	v_pk_mul_f32 v[136:137], v[136:137], v[140:141]
	v_mul_f32_e32 v140, 0x3d122279, v135
	v_fmaak_f32 v143, v139, v143, 0x3f4c422a
	v_fmaak_f32 v144, v132, v144, 0x3f4c422a
	v_fmaak_f32 v145, v133, v145, 0x3f4c422a
	v_fmaak_f32 v140, v135, v140, 0x3f4c422a
	v_mul_f32_e32 v143, v139, v143
	v_mul_f32_e32 v144, v132, v144
	v_mul_f32_e32 v145, v133, v145
	v_mul_f32_e32 v140, v135, v140
	v_mul_f32_e32 v143, 0xc038aa3b, v143
	v_mul_f32_e32 v144, 0xc038aa3b, v144
	v_mul_f32_e32 v145, 0xc038aa3b, v145
	v_mul_f32_e32 v140, 0xc038aa3b, v140
	v_exp_f32_e32 v143, v143
	v_exp_f32_e32 v144, v144
	v_exp_f32_e32 v145, v145
	v_exp_f32_e32 v140, v140
	v_add_f32_e32 v143, 1.0, v143
	v_add_f32_e32 v144, 1.0, v144
	v_add_f32_e32 v145, 1.0, v145
	v_add_f32_e32 v140, 1.0, v140
	v_rcp_f32_e32 v143, v143
	v_rcp_f32_e32 v144, v144
	v_rcp_f32_e32 v145, v145
	v_rcp_f32_e32 v147, v140
	v_pk_mul_f32 v[138:139], v[138:139], v[142:143]
	v_pk_mul_f32 v[132:133], v[132:133], v[144:145]
	v_pk_mul_f32 v[134:135], v[134:135], v[146:147]
; __device__ __forceinline__ unsigned cvt_pk_bf16(float lo, float hi) { unsigned r; asm volatile("v_cvt_pk_bf16_f32 %0, %1, %2" : "=v"(r) : "v"(lo), "v"(hi)); return r; }
; #define EPI_FENCE() asm volatile("" ::: "memory")
; __device__ __forceinline__ float gelu_tanh(float x) {
;     const float y = x * (0.7978845608028654f + 0.7978845608028654f * 0.044715f * x * x);
;     const float e = __builtin_amdgcn_exp2f(-2.0f * 1.4426950408889634f * y);
;     return x * __builtin_amdgcn_rcpf(1.0f + e);
; }
;     __device__ __forceinline__ void operator()(const f32x4 (&acc)[2][2][4][2], const Unit& u, int wr, int wc, int fr, int fq) const {
;     ...
;         } else {
;             EPI_FENCE();
; #pragma unroll
;             for (int i = 0; i < 8; ++i) {
;                 const int ai = i >> 2, m = i & 3; bf16_t* rowp = Z + (size_t)(row0 + ai * HALF + m * 16) * 5120 + col0;
; #pragma unroll
;                 for (int bj = 0; bj < 2; ++bj) {
;                     f32x4 v0 = acc[ai][bj][m][0] * rs[i], v1 = acc[ai][bj][m][1] * rs[i];
;                     if (kind == 2) {
; #pragma unroll
;                         for (int e = 0; e < 4; ++e) { v0[e] = gelu_tanh(v0[e]); v1[e] = gelu_tanh(v1[e]); }
;                     }
;                     u32x4 w; w.x = cvt_pk_bf16(v0[0], v0[1]); w.y = cvt_pk_bf16(v0[2], v0[3]); w.z = cvt_pk_bf16(v1[0], v1[1]); w.w = cvt_pk_bf16(v1[2], v1[3]);
;                     *(u32x4*)(rowp + bj * HALF) = w;
.LBB0_139:
	v_cvt_pk_bf16_f32 v136, v136, v137
	v_cvt_pk_bf16_f32 v137, v132, v133
	v_cvt_pk_bf16_f32 v138, v138, v139
	s_nop 0
	v_cvt_pk_bf16_f32 v139, v134, v135
	ds_bpermute_b32 v226, v255, v136
	ds_bpermute_b32 v227, v255, v137
	ds_bpermute_b32 v228, v255, v138
	ds_bpermute_b32 v229, v255, v139
	v_lshl_add_u64 v[224:225], v[130:131], 0, v[242:243]
	s_waitcnt lgkmcnt(0)
	global_store_dwordx4 v[224:225], v[226:229], off offset:256
	v_pk_mul_f32 v[132:133], v[64:65], v[182:183] op_sel_hi:[1,0]
	v_pk_mul_f32 v[134:135], v[60:61], v[182:183] op_sel_hi:[1,0]
	v_pk_mul_f32 v[136:137], v[62:63], v[182:183] op_sel_hi:[1,0]
	s_and_b64 vcc, exec, s[4:5]
	v_pk_mul_f32 v[138:139], v[58:59], v[182:183] op_sel_hi:[1,0]
	s_cbranch_vccnz .LBB0_141
	v_mul_f32_e32 v131, 0x3d122279, v138
	v_fmaak_f32 v131, v138, v131, 0x3f4c422a
	v_mul_f32_e32 v131, v138, v131
	v_mul_f32_e32 v131, 0xc038aa3b, v131
	v_exp_f32_e32 v131, v131
	v_mul_f32_e32 v130, 0x3d122279, v136
	v_fmaak_f32 v130, v136, v130, 0x3f4c422a
	v_mul_f32_e32 v130, v136, v130
	v_add_f32_e32 v131, 1.0, v131
	v_rcp_f32_e32 v140, v131
	v_mul_f32_e32 v131, 0x3d122279, v137
	v_fmaak_f32 v131, v137, v131, 0x3f4c422a
	v_mul_f32_e32 v131, v137, v131
	v_mul_f32_e32 v130, 0xc038aa3b, v130
	v_mul_f32_e32 v131, 0xc038aa3b, v131
	v_exp_f32_e32 v130, v130
	v_exp_f32_e32 v131, v131
	v_mul_f32_e32 v143, 0x3d122279, v134
	v_fmaak_f32 v143, v134, v143, 0x3f4c422a
	v_mul_f32_e32 v143, v134, v143
	v_mul_f32_e32 v143, 0xc038aa3b, v143
	v_add_f32_e32 v130, 1.0, v130
	v_add_f32_e32 v131, 1.0, v131
	v_exp_f32_e32 v143, v143
	v_rcp_f32_e32 v130, v130
	v_rcp_f32_e32 v131, v131
	v_mul_f32_e32 v141, 0x3d122279, v139
	v_add_f32_e32 v143, 1.0, v143
	v_mul_f32_e32 v142, 0x3d122279, v132
	v_rcp_f32_e32 v144, v143
	v_mul_f32_e32 v143, 0x3d122279, v133
	v_pk_mul_f32 v[136:137], v[136:137], v[130:131]
	v_mul_f32_e32 v130, 0x3d122279, v135
	v_fmaak_f32 v141, v139, v141, 0x3f4c422a
	v_fmaak_f32 v142, v132, v142, 0x3f4c422a
	v_fmaak_f32 v143, v133, v143, 0x3f4c422a
	v_fmaak_f32 v130, v135, v130, 0x3f4c422a
	v_mul_f32_e32 v141, v139, v141
	v_mul_f32_e32 v142, v132, v142
	v_mul_f32_e32 v143, v133, v143
	v_mul_f32_e32 v130, v135, v130
	v_mul_f32_e32 v141, 0xc038aa3b, v141
	v_mul_f32_e32 v142, 0xc038aa3b, v142
	v_mul_f32_e32 v143, 0xc038aa3b, v143
	v_mul_f32_e32 v130, 0xc038aa3b, v130
	v_exp_f32_e32 v141, v141
	v_exp_f32_e32 v142, v142
	v_exp_f32_e32 v143, v143
	v_exp_f32_e32 v130, v130
	v_add_f32_e32 v141, 1.0, v141
	v_add_f32_e32 v142, 1.0, v142
	v_add_f32_e32 v143, 1.0, v143
	v_add_f32_e32 v130, 1.0, v130
	v_rcp_f32_e32 v141, v141
	v_rcp_f32_e32 v142, v142
	v_rcp_f32_e32 v143, v143
	v_rcp_f32_e32 v145, v130
	v_pk_mul_f32 v[138:139], v[138:139], v[140:141]
	v_pk_mul_f32 v[132:133], v[132:133], v[142:143]
	v_pk_mul_f32 v[134:135], v[134:135], v[144:145]
.LBB0_141:
	v_add_u32_e32 v140, 0x80, v206
	v_mov_b64_e32 v[130:131], s[8:9]
	v_mad_i64_i32 v[130:131], s[2:3], v140, s59, v[130:131]
	v_mov_b32_e32 v142, v182
	v_mov_b32_e32 v143, v182
	v_lshl_add_u64 v[130:131], v[188:189], 1, v[130:131]
	v_cvt_pk_bf16_f32 v136, v136, v137
	v_cvt_pk_bf16_f32 v137, v132, v133
	v_cvt_pk_bf16_f32 v138, v138, v139
	v_cvt_pk_bf16_f32 v139, v134, v135
	v_mov_b32_e32 v134, v182
	v_mov_b32_e32 v135, v182
	ds_bpermute_b32 v226, v255, v136
	ds_bpermute_b32 v227, v255, v137
	ds_bpermute_b32 v228, v255, v138
	ds_bpermute_b32 v229, v255, v139
	v_lshl_add_u64 v[224:225], v[130:131], 0, v[242:243]
	s_waitcnt lgkmcnt(0)
	global_store_dwordx4 v[224:225], v[226:229], off
	v_pk_mul_f32 v[132:133], v[56:57], v[134:135]
	v_pk_mul_f32 v[134:135], v[52:53], v[134:135]
	v_pk_mul_f32 v[136:137], v[54:55], v[142:143]
	s_and_b64 vcc, exec, s[4:5]
	v_pk_mul_f32 v[138:139], v[50:51], v[142:143]
	s_cbranch_vccnz .LBB0_143
	v_mul_f32_e32 v141, 0x3d122279, v136
	v_fmaak_f32 v141, v136, v141, 0x3f4c422a
	v_mul_f32_e32 v141, v136, v141
	v_mul_f32_e32 v141, 0xc038aa3b, v141
	v_exp_f32_e32 v141, v141
	s_nop 0
	v_add_f32_e32 v141, 1.0, v141
	v_rcp_f32_e32 v142, v141
	v_mul_f32_e32 v141, 0x3d122279, v138
	v_fmaak_f32 v141, v138, v141, 0x3f4c422a
	v_mul_f32_e32 v141, v138, v141
	v_mul_f32_e32 v141, 0xc038aa3b, v141
	v_exp_f32_e32 v141, v141
	s_nop 0
	v_add_f32_e32 v141, 1.0, v141
	v_rcp_f32_e32 v144, v141
	v_mul_f32_e32 v141, 0x3d122279, v137
	v_fmaak_f32 v141, v137, v141, 0x3f4c422a
	v_mul_f32_e32 v141, v137, v141
	v_mul_f32_e32 v141, 0xc038aa3b, v141
	v_exp_f32_e32 v141, v141
	s_nop 0
	v_add_f32_e32 v141, 1.0, v141
	v_rcp_f32_e32 v143, v141
	v_mul_f32_e32 v141, 0x3d122279, v139
	v_fmaak_f32 v141, v139, v141, 0x3f4c422a
	v_mul_f32_e32 v141, v139, v141
	v_mul_f32_e32 v141, 0xc038aa3b, v141
	v_exp_f32_e32 v141, v141
	v_pk_mul_f32 v[136:137], v[136:137], v[142:143]
	v_add_f32_e32 v141, 1.0, v141
	v_rcp_f32_e32 v145, v141
	v_mul_f32_e32 v141, 0x3d122279, v132
	v_fmaak_f32 v141, v132, v141, 0x3f4c422a
	v_mul_f32_e32 v141, v132, v141
	v_mul_f32_e32 v141, 0xc038aa3b, v141
	v_exp_f32_e32 v141, v141
	v_pk_mul_f32 v[138:139], v[138:139], v[144:145]
	v_add_f32_e32 v141, 1.0, v141
	v_rcp_f32_e32 v146, v141
	v_mul_f32_e32 v141, 0x3d122279, v134
	v_fmaak_f32 v141, v134, v141, 0x3f4c422a
	v_mul_f32_e32 v141, v134, v141
	v_mul_f32_e32 v141, 0xc038aa3b, v141
	v_exp_f32_e32 v141, v141
	s_nop 0
	v_add_f32_e32 v141, 1.0, v141
	v_rcp_f32_e32 v148, v141
	v_mul_f32_e32 v141, 0x3d122279, v133
	v_fmaak_f32 v141, v133, v141, 0x3f4c422a
	v_mul_f32_e32 v141, v133, v141
	v_mul_f32_e32 v141, 0xc038aa3b, v141
	v_exp_f32_e32 v141, v141
	s_nop 0
	v_add_f32_e32 v141, 1.0, v141
	v_rcp_f32_e32 v147, v141
	v_mul_f32_e32 v141, 0x3d122279, v135
	v_fmaak_f32 v141, v135, v141, 0x3f4c422a
	v_mul_f32_e32 v141, v135, v141
	v_mul_f32_e32 v141, 0xc038aa3b, v141
	v_exp_f32_e32 v141, v141
	v_pk_mul_f32 v[132:133], v[132:133], v[146:147]
	v_add_f32_e32 v141, 1.0, v141
	v_rcp_f32_e32 v149, v141
	s_nop 0
	v_pk_mul_f32 v[134:135], v[134:135], v[148:149]
; __device__ __forceinline__ unsigned cvt_pk_bf16(float lo, float hi) { unsigned r; asm volatile("v_cvt_pk_bf16_f32 %0, %1, %2" : "=v"(r) : "v"(lo), "v"(hi)); return r; }
; #define EPI_FENCE() asm volatile("" ::: "memory")
; __device__ __forceinline__ float gelu_tanh(float x) {
;     const float y = x * (0.7978845608028654f + 0.7978845608028654f * 0.044715f * x * x);
;     const float e = __builtin_amdgcn_exp2f(-2.0f * 1.4426950408889634f * y);
;     return x * __builtin_amdgcn_rcpf(1.0f + e);
; }
;     __device__ __forceinline__ void operator()(const f32x4 (&acc)[2][2][4][2], const Unit& u, int wr, int wc, int fr, int fq) const {
;     ...
;         } else {
;             EPI_FENCE();
; #pragma unroll
;             for (int i = 0; i < 8; ++i) {
;                 const int ai = i >> 2, m = i & 3; bf16_t* rowp = Z + (size_t)(row0 + ai * HALF + m * 16) * 5120 + col0;
; #pragma unroll
;                 for (int bj = 0; bj < 2; ++bj) {
;                     f32x4 v0 = acc[ai][bj][m][0] * rs[i], v1 = acc[ai][bj][m][1] * rs[i];
;                     if (kind == 2) {
; #pragma unroll
;                         for (int e = 0; e < 4; ++e) { v0[e] = gelu_tanh(v0[e]); v1[e] = gelu_tanh(v1[e]); }
;                     }
;                     u32x4 w; w.x = cvt_pk_bf16(v0[0], v0[1]); w.y = cvt_pk_bf16(v0[2], v0[3]); w.z = cvt_pk_bf16(v1[0], v1[1]); w.w = cvt_pk_bf16(v1[2], v1[3]);
;                     *(u32x4*)(rowp + bj * HALF) = w;
.LBB0_143:
	v_cvt_pk_bf16_f32 v136, v136, v137
	v_cvt_pk_bf16_f32 v137, v132, v133
	v_cvt_pk_bf16_f32 v138, v138, v139
	s_nop 0
	v_cvt_pk_bf16_f32 v139, v134, v135
	ds_bpermute_b32 v226, v255, v136
	ds_bpermute_b32 v227, v255, v137
	ds_bpermute_b32 v228, v255, v138
	ds_bpermute_b32 v229, v255, v139
	v_lshl_add_u64 v[224:225], v[130:131], 0, v[242:243]
	s_waitcnt lgkmcnt(0)
	global_store_dwordx4 v[224:225], v[226:229], off offset:256
	v_mov_b32_e32 v130, v183
	v_pk_mul_f32 v[132:133], v[48:49], v[130:131] op_sel_hi:[1,0]
	v_pk_mul_f32 v[136:137], v[46:47], v[130:131] op_sel_hi:[1,0]
	v_pk_mul_f32 v[134:135], v[44:45], v[130:131] op_sel_hi:[1,0]
	s_and_b64 vcc, exec, s[4:5]
	v_pk_mul_f32 v[138:139], v[42:43], v[130:131] op_sel_hi:[1,0]
	s_cbranch_vccnz .LBB0_145
	v_mul_f32_e32 v141, 0x3d122279, v139
	v_fmaak_f32 v141, v139, v141, 0x3f4c422a
	v_mul_f32_e32 v141, v139, v141
	v_mul_f32_e32 v141, 0xc038aa3b, v141
	v_exp_f32_e32 v141, v141
	v_mul_f32_e32 v131, 0x3d122279, v138
	v_fmaak_f32 v131, v138, v131, 0x3f4c422a
	v_mul_f32_e32 v131, v138, v131
	v_mul_f32_e32 v131, 0xc038aa3b, v131
	v_add_f32_e32 v141, 1.0, v141
	v_exp_f32_e32 v131, v131
	v_rcp_f32_e32 v143, v141
	v_mul_f32_e32 v141, 0x3d122279, v132
	v_fmaak_f32 v141, v132, v141, 0x3f4c422a
	v_mul_f32_e32 v141, v132, v141
	v_mul_f32_e32 v141, 0xc038aa3b, v141
	v_add_f32_e32 v131, 1.0, v131
	v_exp_f32_e32 v141, v141
	v_mul_f32_e32 v130, 0x3d122279, v136
	v_rcp_f32_e32 v142, v131
	v_mul_f32_e32 v131, 0x3d122279, v137
	v_fmaak_f32 v130, v136, v130, 0x3f4c422a
	v_fmaak_f32 v131, v137, v131, 0x3f4c422a
	v_mul_f32_e32 v130, v136, v130
	v_mul_f32_e32 v131, v137, v131
	v_mul_f32_e32 v130, 0xc038aa3b, v130
	v_mul_f32_e32 v131, 0xc038aa3b, v131
	v_add_f32_e32 v141, 1.0, v141
	v_exp_f32_e32 v130, v130
	v_exp_f32_e32 v131, v131
	v_rcp_f32_e32 v144, v141
	v_mul_f32_e32 v141, 0x3d122279, v134
	v_fmaak_f32 v141, v134, v141, 0x3f4c422a
	v_mul_f32_e32 v141, v134, v141
	v_mul_f32_e32 v141, 0xc038aa3b, v141
	v_add_f32_e32 v130, 1.0, v130
	v_add_f32_e32 v131, 1.0, v131
	v_exp_f32_e32 v141, v141
	v_rcp_f32_e32 v130, v130
	v_rcp_f32_e32 v131, v131
	v_pk_mul_f32 v[138:139], v[138:139], v[142:143]
	v_add_f32_e32 v141, 1.0, v141
	v_rcp_f32_e32 v146, v141
	v_mul_f32_e32 v141, 0x3d122279, v133
	v_pk_mul_f32 v[136:137], v[136:137], v[130:131]
	v_mul_f32_e32 v130, 0x3d122279, v135
	v_fmaak_f32 v141, v133, v141, 0x3f4c422a
	v_fmaak_f32 v130, v135, v130, 0x3f4c422a
	v_mul_f32_e32 v141, v133, v141
	v_mul_f32_e32 v130, v135, v130
	v_mul_f32_e32 v141, 0xc038aa3b, v141
	v_mul_f32_e32 v130, 0xc038aa3b, v130
	v_exp_f32_e32 v141, v141
	v_exp_f32_e32 v130, v130
	v_add_f32_e32 v141, 1.0, v141
	v_add_f32_e32 v130, 1.0, v130
	v_rcp_f32_e32 v145, v141
	v_rcp_f32_e32 v147, v130
	v_pk_mul_f32 v[132:133], v[132:133], v[144:145]
	v_pk_mul_f32 v[134:135], v[134:135], v[146:147]
.LBB0_145:
	v_or_b32_e32 v141, 16, v140
	v_mov_b64_e32 v[130:131], s[8:9]
	v_mad_i64_i32 v[130:131], s[2:3], v141, s59, v[130:131]
	v_mov_b32_e32 v142, v183
	v_mov_b32_e32 v143, v183
	v_lshl_add_u64 v[130:131], v[188:189], 1, v[130:131]
	v_cvt_pk_bf16_f32 v136, v136, v137
	v_cvt_pk_bf16_f32 v137, v132, v133
	v_cvt_pk_bf16_f32 v138, v138, v139
	v_cvt_pk_bf16_f32 v139, v134, v135
	v_mov_b32_e32 v134, v183
	v_mov_b32_e32 v135, v183
	ds_bpermute_b32 v226, v255, v136
	ds_bpermute_b32 v227, v255, v137
	ds_bpermute_b32 v228, v255, v138
	ds_bpermute_b32 v229, v255, v139
	v_lshl_add_u64 v[224:225], v[130:131], 0, v[242:243]
	s_waitcnt lgkmcnt(0)
	global_store_dwordx4 v[224:225], v[226:229], off
	v_pk_mul_f32 v[132:133], v[40:41], v[134:135]
	v_pk_mul_f32 v[134:135], v[36:37], v[134:135]
	v_pk_mul_f32 v[136:137], v[38:39], v[142:143]
	s_and_b64 vcc, exec, s[4:5]
	v_pk_mul_f32 v[138:139], v[34:35], v[142:143]
	s_cbranch_vccnz .LBB0_147
	v_mul_f32_e32 v141, 0x3d122279, v136
	v_fmaak_f32 v141, v136, v141, 0x3f4c422a
	v_mul_f32_e32 v141, v136, v141
	v_mul_f32_e32 v141, 0xc038aa3b, v141
	v_exp_f32_e32 v141, v141
	s_nop 0
	v_add_f32_e32 v141, 1.0, v141
	v_rcp_f32_e32 v142, v141
	v_mul_f32_e32 v141, 0x3d122279, v138
	v_fmaak_f32 v141, v138, v141, 0x3f4c422a
	v_mul_f32_e32 v141, v138, v141
	v_mul_f32_e32 v141, 0xc038aa3b, v141
	v_exp_f32_e32 v141, v141
	s_nop 0
	v_add_f32_e32 v141, 1.0, v141
	v_rcp_f32_e32 v144, v141
	v_mul_f32_e32 v141, 0x3d122279, v137
	v_fmaak_f32 v141, v137, v141, 0x3f4c422a
	v_mul_f32_e32 v141, v137, v141
	v_mul_f32_e32 v141, 0xc038aa3b, v141
	v_exp_f32_e32 v141, v141
	s_nop 0
	v_add_f32_e32 v141, 1.0, v141
	v_rcp_f32_e32 v143, v141
	v_mul_f32_e32 v141, 0x3d122279, v139
	v_fmaak_f32 v141, v139, v141, 0x3f4c422a
	v_mul_f32_e32 v141, v139, v141
	v_mul_f32_e32 v141, 0xc038aa3b, v141
	v_exp_f32_e32 v141, v141
	v_pk_mul_f32 v[136:137], v[136:137], v[142:143]
	v_add_f32_e32 v141, 1.0, v141
	v_rcp_f32_e32 v145, v141
	v_mul_f32_e32 v141, 0x3d122279, v132
	v_fmaak_f32 v141, v132, v141, 0x3f4c422a
	v_mul_f32_e32 v141, v132, v141
	v_mul_f32_e32 v141, 0xc038aa3b, v141
	v_exp_f32_e32 v141, v141
	v_pk_mul_f32 v[138:139], v[138:139], v[144:145]
	v_add_f32_e32 v141, 1.0, v141
	v_rcp_f32_e32 v146, v141
	v_mul_f32_e32 v141, 0x3d122279, v134
	v_fmaak_f32 v141, v134, v141, 0x3f4c422a
	v_mul_f32_e32 v141, v134, v141
	v_mul_f32_e32 v141, 0xc038aa3b, v141
	v_exp_f32_e32 v141, v141
	s_nop 0
	v_add_f32_e32 v141, 1.0, v141
	v_rcp_f32_e32 v148, v141
	v_mul_f32_e32 v141, 0x3d122279, v133
	v_fmaak_f32 v141, v133, v141, 0x3f4c422a
	v_mul_f32_e32 v141, v133, v141
	v_mul_f32_e32 v141, 0xc038aa3b, v141
	v_exp_f32_e32 v141, v141
	s_nop 0
	v_add_f32_e32 v141, 1.0, v141
	v_rcp_f32_e32 v147, v141
	v_mul_f32_e32 v141, 0x3d122279, v135
	v_fmaak_f32 v141, v135, v141, 0x3f4c422a
	v_mul_f32_e32 v141, v135, v141
	v_mul_f32_e32 v141, 0xc038aa3b, v141
	v_exp_f32_e32 v141, v141
	v_pk_mul_f32 v[132:133], v[132:133], v[146:147]
	v_add_f32_e32 v141, 1.0, v141
	v_rcp_f32_e32 v149, v141
	s_nop 0
	v_pk_mul_f32 v[134:135], v[134:135], v[148:149]
; __device__ __forceinline__ unsigned cvt_pk_bf16(float lo, float hi) { unsigned r; asm volatile("v_cvt_pk_bf16_f32 %0, %1, %2" : "=v"(r) : "v"(lo), "v"(hi)); return r; }
; #define EPI_FENCE() asm volatile("" ::: "memory")
; __device__ __forceinline__ float gelu_tanh(float x) {
;     const float y = x * (0.7978845608028654f + 0.7978845608028654f * 0.044715f * x * x);
;     const float e = __builtin_amdgcn_exp2f(-2.0f * 1.4426950408889634f * y);
;     return x * __builtin_amdgcn_rcpf(1.0f + e);
; }
;     __device__ __forceinline__ void operator()(const f32x4 (&acc)[2][2][4][2], const Unit& u, int wr, int wc, int fr, int fq) const {
;     ...
;         } else {
;             EPI_FENCE();
; #pragma unroll
;             for (int i = 0; i < 8; ++i) {
;                 const int ai = i >> 2, m = i & 3; bf16_t* rowp = Z + (size_t)(row0 + ai * HALF + m * 16) * 5120 + col0;
; #pragma unroll
;                 for (int bj = 0; bj < 2; ++bj) {
;                     f32x4 v0 = acc[ai][bj][m][0] * rs[i], v1 = acc[ai][bj][m][1] * rs[i];
;                     if (kind == 2) {
; #pragma unroll
;                         for (int e = 0; e < 4; ++e) { v0[e] = gelu_tanh(v0[e]); v1[e] = gelu_tanh(v1[e]); }
;                     }
;                     u32x4 w; w.x = cvt_pk_bf16(v0[0], v0[1]); w.y = cvt_pk_bf16(v0[2], v0[3]); w.z = cvt_pk_bf16(v1[0], v1[1]); w.w = cvt_pk_bf16(v1[2], v1[3]);
;                     *(u32x4*)(rowp + bj * HALF) = w;
.LBB0_147:
	v_cvt_pk_bf16_f32 v136, v136, v137
	v_cvt_pk_bf16_f32 v137, v132, v133
	v_cvt_pk_bf16_f32 v138, v138, v139
	s_nop 0
	v_cvt_pk_bf16_f32 v139, v134, v135
	ds_bpermute_b32 v226, v255, v136
	ds_bpermute_b32 v227, v255, v137
	ds_bpermute_b32 v228, v255, v138
	ds_bpermute_b32 v229, v255, v139
	v_lshl_add_u64 v[224:225], v[130:131], 0, v[242:243]
	s_waitcnt lgkmcnt(0)
	global_store_dwordx4 v[224:225], v[226:229], off offset:256
	v_pk_mul_f32 v[132:133], v[32:33], v[180:181] op_sel_hi:[1,0]
	v_pk_mul_f32 v[134:135], v[28:29], v[180:181] op_sel_hi:[1,0]
	v_pk_mul_f32 v[136:137], v[30:31], v[180:181] op_sel_hi:[1,0]
	s_and_b64 vcc, exec, s[4:5]
	v_pk_mul_f32 v[138:139], v[26:27], v[180:181] op_sel_hi:[1,0]
	s_cbranch_vccnz .LBB0_149
	v_mul_f32_e32 v141, 0x3d122279, v139
	v_fmaak_f32 v141, v139, v141, 0x3f4c422a
	v_mul_f32_e32 v141, v139, v141
	v_mul_f32_e32 v141, 0xc038aa3b, v141
	v_exp_f32_e32 v141, v141
	v_mul_f32_e32 v131, 0x3d122279, v138
	v_fmaak_f32 v131, v138, v131, 0x3f4c422a
	v_mul_f32_e32 v131, v138, v131
	v_mul_f32_e32 v131, 0xc038aa3b, v131
	v_add_f32_e32 v141, 1.0, v141
	v_exp_f32_e32 v131, v131
	v_rcp_f32_e32 v143, v141
	v_mul_f32_e32 v141, 0x3d122279, v132
	v_fmaak_f32 v141, v132, v141, 0x3f4c422a
	v_mul_f32_e32 v141, v132, v141
	v_mul_f32_e32 v141, 0xc038aa3b, v141
	v_add_f32_e32 v131, 1.0, v131
	v_exp_f32_e32 v141, v141
	v_mul_f32_e32 v130, 0x3d122279, v136
	v_rcp_f32_e32 v142, v131
	v_mul_f32_e32 v131, 0x3d122279, v137
	v_fmaak_f32 v130, v136, v130, 0x3f4c422a
	v_fmaak_f32 v131, v137, v131, 0x3f4c422a
	v_mul_f32_e32 v130, v136, v130
	v_mul_f32_e32 v131, v137, v131
	v_mul_f32_e32 v130, 0xc038aa3b, v130
	v_mul_f32_e32 v131, 0xc038aa3b, v131
	v_add_f32_e32 v141, 1.0, v141
	v_exp_f32_e32 v130, v130
	v_exp_f32_e32 v131, v131
	v_rcp_f32_e32 v144, v141
	v_mul_f32_e32 v141, 0x3d122279, v134
	v_fmaak_f32 v141, v134, v141, 0x3f4c422a
	v_mul_f32_e32 v141, v134, v141
	v_mul_f32_e32 v141, 0xc038aa3b, v141
	v_add_f32_e32 v130, 1.0, v130
	v_add_f32_e32 v131, 1.0, v131
	v_exp_f32_e32 v141, v141
	v_rcp_f32_e32 v130, v130
	v_rcp_f32_e32 v131, v131
	v_pk_mul_f32 v[138:139], v[138:139], v[142:143]
	v_add_f32_e32 v141, 1.0, v141
	v_rcp_f32_e32 v146, v141
	v_mul_f32_e32 v141, 0x3d122279, v133
	v_pk_mul_f32 v[136:137], v[136:137], v[130:131]
	v_mul_f32_e32 v130, 0x3d122279, v135
	v_fmaak_f32 v141, v133, v141, 0x3f4c422a
	v_fmaak_f32 v130, v135, v130, 0x3f4c422a
	v_mul_f32_e32 v141, v133, v141
	v_mul_f32_e32 v130, v135, v130
	v_mul_f32_e32 v141, 0xc038aa3b, v141
	v_mul_f32_e32 v130, 0xc038aa3b, v130
	v_exp_f32_e32 v141, v141
	v_exp_f32_e32 v130, v130
	v_add_f32_e32 v141, 1.0, v141
	v_add_f32_e32 v130, 1.0, v130
	v_rcp_f32_e32 v145, v141
	v_rcp_f32_e32 v147, v130
	v_pk_mul_f32 v[132:133], v[132:133], v[144:145]
	v_pk_mul_f32 v[134:135], v[134:135], v[146:147]
.LBB0_149:
	v_or_b32_e32 v141, 32, v140
	v_mov_b64_e32 v[130:131], s[8:9]
	v_mad_i64_i32 v[130:131], s[2:3], v141, s59, v[130:131]
	v_mov_b32_e32 v142, v180
	v_mov_b32_e32 v143, v180
	v_lshl_add_u64 v[130:131], v[188:189], 1, v[130:131]
	v_cvt_pk_bf16_f32 v136, v136, v137
	v_cvt_pk_bf16_f32 v137, v132, v133
	v_cvt_pk_bf16_f32 v138, v138, v139
	v_cvt_pk_bf16_f32 v139, v134, v135
	v_mov_b32_e32 v134, v180
	v_mov_b32_e32 v135, v180
	ds_bpermute_b32 v226, v255, v136
	ds_bpermute_b32 v227, v255, v137
	ds_bpermute_b32 v228, v255, v138
	ds_bpermute_b32 v229, v255, v139
	v_lshl_add_u64 v[224:225], v[130:131], 0, v[242:243]
	s_waitcnt lgkmcnt(0)
	global_store_dwordx4 v[224:225], v[226:229], off
	v_pk_mul_f32 v[132:133], v[24:25], v[134:135]
	v_pk_mul_f32 v[134:135], v[20:21], v[134:135]
	v_pk_mul_f32 v[136:137], v[22:23], v[142:143]
	s_and_b64 vcc, exec, s[4:5]
	v_pk_mul_f32 v[138:139], v[18:19], v[142:143]
	s_cbranch_vccnz .LBB0_151
	v_mul_f32_e32 v141, 0x3d122279, v136
	v_fmaak_f32 v141, v136, v141, 0x3f4c422a
	v_mul_f32_e32 v141, v136, v141
	v_mul_f32_e32 v141, 0xc038aa3b, v141
	v_exp_f32_e32 v141, v141
	s_nop 0
	v_add_f32_e32 v141, 1.0, v141
	v_rcp_f32_e32 v142, v141
	v_mul_f32_e32 v141, 0x3d122279, v138
	v_fmaak_f32 v141, v138, v141, 0x3f4c422a
	v_mul_f32_e32 v141, v138, v141
	v_mul_f32_e32 v141, 0xc038aa3b, v141
	v_exp_f32_e32 v141, v141
	s_nop 0
	v_add_f32_e32 v141, 1.0, v141
	v_rcp_f32_e32 v144, v141
	v_mul_f32_e32 v141, 0x3d122279, v137
	v_fmaak_f32 v141, v137, v141, 0x3f4c422a
	v_mul_f32_e32 v141, v137, v141
	v_mul_f32_e32 v141, 0xc038aa3b, v141
	v_exp_f32_e32 v141, v141
	s_nop 0
	v_add_f32_e32 v141, 1.0, v141
	v_rcp_f32_e32 v143, v141
	v_mul_f32_e32 v141, 0x3d122279, v139
	v_fmaak_f32 v141, v139, v141, 0x3f4c422a
	v_mul_f32_e32 v141, v139, v141
	v_mul_f32_e32 v141, 0xc038aa3b, v141
	v_exp_f32_e32 v141, v141
	v_pk_mul_f32 v[136:137], v[136:137], v[142:143]
	v_add_f32_e32 v141, 1.0, v141
	v_rcp_f32_e32 v145, v141
	v_mul_f32_e32 v141, 0x3d122279, v132
	v_fmaak_f32 v141, v132, v141, 0x3f4c422a
	v_mul_f32_e32 v141, v132, v141
	v_mul_f32_e32 v141, 0xc038aa3b, v141
	v_exp_f32_e32 v141, v141
	v_pk_mul_f32 v[138:139], v[138:139], v[144:145]
	v_add_f32_e32 v141, 1.0, v141
	v_rcp_f32_e32 v146, v141
	v_mul_f32_e32 v141, 0x3d122279, v134
	v_fmaak_f32 v141, v134, v141, 0x3f4c422a
	v_mul_f32_e32 v141, v134, v141
	v_mul_f32_e32 v141, 0xc038aa3b, v141
	v_exp_f32_e32 v141, v141
	s_nop 0
	v_add_f32_e32 v141, 1.0, v141
	v_rcp_f32_e32 v148, v141
	v_mul_f32_e32 v141, 0x3d122279, v133
	v_fmaak_f32 v141, v133, v141, 0x3f4c422a
	v_mul_f32_e32 v141, v133, v141
	v_mul_f32_e32 v141, 0xc038aa3b, v141
	v_exp_f32_e32 v141, v141
	s_nop 0
	v_add_f32_e32 v141, 1.0, v141
	v_rcp_f32_e32 v147, v141
	v_mul_f32_e32 v141, 0x3d122279, v135
	v_fmaak_f32 v141, v135, v141, 0x3f4c422a
	v_mul_f32_e32 v141, v135, v141
	v_mul_f32_e32 v141, 0xc038aa3b, v141
	v_exp_f32_e32 v141, v141
	v_pk_mul_f32 v[132:133], v[132:133], v[146:147]
	v_add_f32_e32 v141, 1.0, v141
	v_rcp_f32_e32 v149, v141
	s_nop 0
	v_pk_mul_f32 v[134:135], v[134:135], v[148:149]
; __device__ __forceinline__ unsigned cvt_pk_bf16(float lo, float hi) { unsigned r; asm volatile("v_cvt_pk_bf16_f32 %0, %1, %2" : "=v"(r) : "v"(lo), "v"(hi)); return r; }
; #define EPI_FENCE() asm volatile("" ::: "memory")
; __device__ __forceinline__ float gelu_tanh(float x) {
;     const float y = x * (0.7978845608028654f + 0.7978845608028654f * 0.044715f * x * x);
;     const float e = __builtin_amdgcn_exp2f(-2.0f * 1.4426950408889634f * y);
;     return x * __builtin_amdgcn_rcpf(1.0f + e);
; }
;     __device__ __forceinline__ void operator()(const f32x4 (&acc)[2][2][4][2], const Unit& u, int wr, int wc, int fr, int fq) const {
;     ...
;         } else {
;             EPI_FENCE();
; #pragma unroll
;             for (int i = 0; i < 8; ++i) {
;                 const int ai = i >> 2, m = i & 3; bf16_t* rowp = Z + (size_t)(row0 + ai * HALF + m * 16) * 5120 + col0;
; #pragma unroll
;                 for (int bj = 0; bj < 2; ++bj) {
;                     f32x4 v0 = acc[ai][bj][m][0] * rs[i], v1 = acc[ai][bj][m][1] * rs[i];
;                     if (kind == 2) {
; #pragma unroll
;                         for (int e = 0; e < 4; ++e) { v0[e] = gelu_tanh(v0[e]); v1[e] = gelu_tanh(v1[e]); }
;                     }
;                     u32x4 w; w.x = cvt_pk_bf16(v0[0], v0[1]); w.y = cvt_pk_bf16(v0[2], v0[3]); w.z = cvt_pk_bf16(v1[0], v1[1]); w.w = cvt_pk_bf16(v1[2], v1[3]);
;                     *(u32x4*)(rowp + bj * HALF) = w;
.LBB0_151:
	v_cvt_pk_bf16_f32 v136, v136, v137
	v_cvt_pk_bf16_f32 v137, v132, v133
	v_cvt_pk_bf16_f32 v138, v138, v139
	s_nop 0
	v_cvt_pk_bf16_f32 v139, v134, v135
	ds_bpermute_b32 v226, v255, v136
	ds_bpermute_b32 v227, v255, v137
	ds_bpermute_b32 v228, v255, v138
	ds_bpermute_b32 v229, v255, v139
	v_lshl_add_u64 v[224:225], v[130:131], 0, v[242:243]
	s_waitcnt lgkmcnt(0)
	global_store_dwordx4 v[224:225], v[226:229], off offset:256
	v_mov_b32_e32 v130, v181
	v_pk_mul_f32 v[132:133], v[16:17], v[130:131] op_sel_hi:[1,0]
	v_pk_mul_f32 v[136:137], v[14:15], v[130:131] op_sel_hi:[1,0]
	v_pk_mul_f32 v[134:135], v[12:13], v[130:131] op_sel_hi:[1,0]
	s_and_b64 vcc, exec, s[4:5]
	v_pk_mul_f32 v[138:139], v[10:11], v[130:131] op_sel_hi:[1,0]
	s_cbranch_vccnz .LBB0_153
	v_mul_f32_e32 v141, 0x3d122279, v139
	v_fmaak_f32 v141, v139, v141, 0x3f4c422a
	v_mul_f32_e32 v141, v139, v141
	v_mul_f32_e32 v141, 0xc038aa3b, v141
	v_exp_f32_e32 v141, v141
	v_mul_f32_e32 v131, 0x3d122279, v138
	v_fmaak_f32 v131, v138, v131, 0x3f4c422a
	v_mul_f32_e32 v131, v138, v131
	v_mul_f32_e32 v131, 0xc038aa3b, v131
	v_add_f32_e32 v141, 1.0, v141
	v_exp_f32_e32 v131, v131
	v_rcp_f32_e32 v143, v141
	v_mul_f32_e32 v141, 0x3d122279, v132
	v_fmaak_f32 v141, v132, v141, 0x3f4c422a
	v_mul_f32_e32 v141, v132, v141
	v_mul_f32_e32 v141, 0xc038aa3b, v141
	v_add_f32_e32 v131, 1.0, v131
	v_exp_f32_e32 v141, v141
	v_mul_f32_e32 v130, 0x3d122279, v136
	v_rcp_f32_e32 v142, v131
	v_mul_f32_e32 v131, 0x3d122279, v137
	v_fmaak_f32 v130, v136, v130, 0x3f4c422a
	v_fmaak_f32 v131, v137, v131, 0x3f4c422a
	v_mul_f32_e32 v130, v136, v130
	v_mul_f32_e32 v131, v137, v131
	v_mul_f32_e32 v130, 0xc038aa3b, v130
	v_mul_f32_e32 v131, 0xc038aa3b, v131
	v_add_f32_e32 v141, 1.0, v141
	v_exp_f32_e32 v130, v130
	v_exp_f32_e32 v131, v131
	v_rcp_f32_e32 v144, v141
	v_mul_f32_e32 v141, 0x3d122279, v134
	v_fmaak_f32 v141, v134, v141, 0x3f4c422a
	v_mul_f32_e32 v141, v134, v141
	v_mul_f32_e32 v141, 0xc038aa3b, v141
	v_add_f32_e32 v130, 1.0, v130
	v_add_f32_e32 v131, 1.0, v131
	v_exp_f32_e32 v141, v141
	v_rcp_f32_e32 v130, v130
	v_rcp_f32_e32 v131, v131
	v_pk_mul_f32 v[138:139], v[138:139], v[142:143]
	v_add_f32_e32 v141, 1.0, v141
	v_rcp_f32_e32 v146, v141
	v_mul_f32_e32 v141, 0x3d122279, v133
	v_pk_mul_f32 v[136:137], v[136:137], v[130:131]
	v_mul_f32_e32 v130, 0x3d122279, v135
	v_fmaak_f32 v141, v133, v141, 0x3f4c422a
	v_fmaak_f32 v130, v135, v130, 0x3f4c422a
	v_mul_f32_e32 v141, v133, v141
	v_mul_f32_e32 v130, v135, v130
	v_mul_f32_e32 v141, 0xc038aa3b, v141
	v_mul_f32_e32 v130, 0xc038aa3b, v130
	v_exp_f32_e32 v141, v141
	v_exp_f32_e32 v130, v130
	v_add_f32_e32 v141, 1.0, v141
	v_add_f32_e32 v130, 1.0, v130
	v_rcp_f32_e32 v145, v141
	v_rcp_f32_e32 v147, v130
	v_pk_mul_f32 v[132:133], v[132:133], v[144:145]
	v_pk_mul_f32 v[134:135], v[134:135], v[146:147]
.LBB0_153:
	v_or_b32_e32 v140, 48, v140
	v_mov_b64_e32 v[130:131], s[8:9]
	v_mad_i64_i32 v[130:131], s[2:3], v140, s59, v[130:131]
	v_mov_b32_e32 v142, v181
	v_mov_b32_e32 v143, v181
	v_lshl_add_u64 v[130:131], v[188:189], 1, v[130:131]
	v_cvt_pk_bf16_f32 v136, v136, v137
	v_cvt_pk_bf16_f32 v137, v132, v133
	v_cvt_pk_bf16_f32 v138, v138, v139
	v_cvt_pk_bf16_f32 v139, v134, v135
	v_mov_b32_e32 v134, v181
	v_mov_b32_e32 v135, v181
	ds_bpermute_b32 v226, v255, v136
	ds_bpermute_b32 v227, v255, v137
	ds_bpermute_b32 v228, v255, v138
	ds_bpermute_b32 v229, v255, v139
	v_lshl_add_u64 v[224:225], v[130:131], 0, v[242:243]
	s_waitcnt lgkmcnt(0)
	global_store_dwordx4 v[224:225], v[226:229], off
	v_pk_mul_f32 v[132:133], v[8:9], v[134:135]
	v_pk_mul_f32 v[134:135], v[4:5], v[134:135]
	v_pk_mul_f32 v[136:137], v[6:7], v[142:143]
	s_and_b64 vcc, exec, s[4:5]
	v_pk_mul_f32 v[138:139], v[2:3], v[142:143]
	s_cbranch_vccnz .LBB0_155
	v_mul_f32_e32 v141, 0x3d122279, v138
	v_fmaak_f32 v141, v138, v141, 0x3f4c422a
	v_mul_f32_e32 v141, v138, v141
	v_mul_f32_e32 v141, 0xc038aa3b, v141
	v_exp_f32_e32 v141, v141
	v_mul_f32_e32 v140, 0x3d122279, v136
	v_fmaak_f32 v140, v136, v140, 0x3f4c422a
	v_mul_f32_e32 v140, v136, v140
	v_add_f32_e32 v141, 1.0, v141
	v_rcp_f32_e32 v142, v141
	v_mul_f32_e32 v141, 0x3d122279, v137
	v_fmaak_f32 v141, v137, v141, 0x3f4c422a
	v_mul_f32_e32 v141, v137, v141
	v_mul_f32_e32 v140, 0xc038aa3b, v140
	v_mul_f32_e32 v141, 0xc038aa3b, v141
	v_exp_f32_e32 v140, v140
	v_exp_f32_e32 v141, v141
	v_mul_f32_e32 v145, 0x3d122279, v134
	v_fmaak_f32 v145, v134, v145, 0x3f4c422a
	v_mul_f32_e32 v145, v134, v145
	v_mul_f32_e32 v145, 0xc038aa3b, v145
	v_add_f32_e32 v140, 1.0, v140
	v_add_f32_e32 v141, 1.0, v141
	v_exp_f32_e32 v145, v145
	v_rcp_f32_e32 v140, v140
	v_rcp_f32_e32 v141, v141
	v_mul_f32_e32 v143, 0x3d122279, v139
	v_add_f32_e32 v145, 1.0, v145
	v_mul_f32_e32 v144, 0x3d122279, v132
	v_rcp_f32_e32 v146, v145
	v_mul_f32_e32 v145, 0x3d122279, v133
	v_pk_mul_f32 v[136:137], v[136:137], v[140:141]
	v_mul_f32_e32 v140, 0x3d122279, v135
	v_fmaak_f32 v143, v139, v143, 0x3f4c422a
	v_fmaak_f32 v144, v132, v144, 0x3f4c422a
	v_fmaak_f32 v145, v133, v145, 0x3f4c422a
	v_fmaak_f32 v140, v135, v140, 0x3f4c422a
	v_mul_f32_e32 v143, v139, v143
	v_mul_f32_e32 v144, v132, v144
	v_mul_f32_e32 v145, v133, v145
	v_mul_f32_e32 v140, v135, v140
	v_mul_f32_e32 v143, 0xc038aa3b, v143
	v_mul_f32_e32 v144, 0xc038aa3b, v144
	v_mul_f32_e32 v145, 0xc038aa3b, v145
	v_mul_f32_e32 v140, 0xc038aa3b, v140
	v_exp_f32_e32 v143, v143
	v_exp_f32_e32 v144, v144
	v_exp_f32_e32 v145, v145
	v_exp_f32_e32 v140, v140
	v_add_f32_e32 v143, 1.0, v143
	v_add_f32_e32 v144, 1.0, v144
	v_add_f32_e32 v145, 1.0, v145
	v_add_f32_e32 v140, 1.0, v140
	v_rcp_f32_e32 v143, v143
	v_rcp_f32_e32 v144, v144
	v_rcp_f32_e32 v145, v145
	v_rcp_f32_e32 v147, v140
	v_pk_mul_f32 v[138:139], v[138:139], v[142:143]
	v_pk_mul_f32 v[132:133], v[132:133], v[144:145]
	v_pk_mul_f32 v[134:135], v[134:135], v[146:147]
; __device__ __forceinline__ unsigned cvt_pk_bf16(float lo, float hi) { unsigned r; asm volatile("v_cvt_pk_bf16_f32 %0, %1, %2" : "=v"(r) : "v"(lo), "v"(hi)); return r; }
; #define EPI_FENCE() asm volatile("" ::: "memory")
;     __device__ __forceinline__ void operator()(const f32x4 (&acc)[2][2][4][2], const Unit& u, int wr, int wc, int fr, int fq) const {
;     ...
;         if (kind == 0) {
; #pragma unroll
;             for (int ai = 0; ai < 2; ++ai) {
;                 f32x4 cs[4][2];
; #pragma unroll
;                 for (int m = 0; m < 4; ++m) { const int row = row0 + ai * HALF + m * 16; const f32x4* rp = (const f32x4*)(rope + ((size_t)(row & 4095) * 64 + j0) * 2); cs[m][0] = rp[0]; cs[m][1] = rp[1]; }
;                 EPI_FENCE();
; #pragma unroll
;                 for (int m = 0; m < 4; ++m) {
;                     bf16_t* rowp = Z + (size_t)(row0 + ai * HALF + m * 16) * 5120 + col0;
;                     const float sc = rs[4 * ai + m] * qs; const f32x4 c0 = cs[m][0] * sc, c1 = cs[m][1] * sc;
; #pragma unroll
;                     for (int bj = 0; bj < 2; ++bj) {
;                         const f32x4 v0 = acc[ai][bj][m][0], v1 = acc[ai][bj][m][1];
;                         u32x4 w;
;                         w.x = cvt_pk_bf16(v0[0] * c0[0] - v0[1] * c0[1], v0[1] * c0[0] + v0[0] * c0[1]);
;                         w.y = cvt_pk_bf16(v0[2] * c0[2] - v0[3] * c0[3], v0[3] * c0[2] + v0[2] * c0[3]);
;                         w.z = cvt_pk_bf16(v1[0] * c1[0] - v1[1] * c1[1], v1[1] * c1[0] + v1[0] * c1[1]);
;                         w.w = cvt_pk_bf16(v1[2] * c1[2] - v1[3] * c1[3], v1[3] * c1[2] + v1[2] * c1[3]);
;                         *(u32x4*)(rowp + bj * HALF) = w;
;                     }
;                 }
.LBB0_155:
	s_mov_b64 s[4:5], 0
	v_cvt_pk_bf16_f32 v136, v136, v137
	v_cvt_pk_bf16_f32 v137, v132, v133
	v_cvt_pk_bf16_f32 v138, v138, v139
	v_cvt_pk_bf16_f32 v139, v134, v135
	ds_bpermute_b32 v226, v255, v136
	ds_bpermute_b32 v227, v255, v137
	ds_bpermute_b32 v228, v255, v138
	ds_bpermute_b32 v229, v255, v139
	v_lshl_add_u64 v[224:225], v[130:131], 0, v[242:243]
	s_waitcnt lgkmcnt(0)
	global_store_dwordx4 v[224:225], v[226:229], off offset:256
.LBB0_156:
	s_and_b64 vcc, exec, s[4:5]
	v_readlane_b32 s50, v252, 33
	v_readlane_b32 s51, v252, 34
	s_cbranch_vccz .LBB0_158
	v_lshlrev_b32_e32 v208, 6, v206
	v_and_b32_e32 v130, 0x3f3c0, v208
	v_mov_b32_e32 v131, v0
	v_lshl_add_u64 v[132:133], v[130:131], 0, v[174:175]
	v_lshl_add_u64 v[132:133], v[132:133], 3, s[10:11]
	global_load_dwordx4 v[210:213], v[132:133], off offset:16
	global_load_dwordx4 v[214:217], v[132:133], off
	v_or_b32_e32 v132, 0x400, v130
	v_mov_b32_e32 v133, v0
	v_lshl_add_u64 v[132:133], v[132:133], 0, v[174:175]
	v_lshl_add_u64 v[132:133], v[132:133], 3, s[10:11]
	global_load_dwordx4 v[146:149], v[132:133], off offset:16
	global_load_dwordx4 v[150:153], v[132:133], off
	v_or_b32_e32 v132, 0x800, v130
	v_mov_b32_e32 v133, v0
	v_lshl_add_u64 v[132:133], v[132:133], 0, v[174:175]
	v_lshl_add_u64 v[132:133], v[132:133], 3, s[10:11]
	global_load_dwordx4 v[138:141], v[132:133], off offset:16
	global_load_dwordx4 v[142:145], v[132:133], off
	v_or_b32_e32 v130, 0xc00, v130
	v_lshl_add_u64 v[130:131], v[130:131], 0, v[174:175]
	v_lshl_add_u64 v[134:135], v[130:131], 3, s[10:11]
	global_load_dwordx4 v[130:133], v[134:135], off offset:16
	s_nop 0
	global_load_dwordx4 v[134:137], v[134:135], off
	s_cmp_gt_i32 s41, 7
	s_cselect_b64 vcc, -1, 0
	v_cndmask_b32_e32 v207, 1.0, v199, vcc
	s_waitcnt lgkmcnt(0)
	v_mul_f32_e32 v186, v207, v186
	v_mov_b64_e32 v[190:191], s[8:9]
	v_mad_i64_i32 v[218:219], s[2:3], v206, s59, v[190:191]
	v_lshlrev_b64 v[188:189], 1, v[188:189]
	v_lshl_add_u64 v[218:219], v[218:219], 0, v[188:189]
	s_waitcnt vmcnt(0)
	v_pk_mul_f32 v[210:211], v[186:187], v[210:211] op_sel_hi:[0,1]
	v_pk_mul_f32 v[214:215], v[186:187], v[214:215] op_sel_hi:[0,1]
	v_pk_mul_f32 v[216:217], v[186:187], v[216:217] op_sel_hi:[0,1]
	v_pk_mul_f32 v[220:221], v[128:129], v[216:217]
	v_pk_mul_f32 v[222:223], v[126:127], v[214:215]
	v_pk_mul_f32 v[126:127], v[126:127], v[214:215] op_sel:[1,0] op_sel_hi:[0,1]
	v_pk_mul_f32 v[128:129], v[128:129], v[216:217] op_sel:[1,0] op_sel_hi:[0,1]
	v_add_f32_e32 v126, v126, v127
	v_sub_f32_e32 v127, v220, v221
	v_add_f32_e32 v128, v128, v129
	v_pk_mul_f32 v[212:213], v[186:187], v[212:213] op_sel_hi:[0,1]
	v_sub_f32_e32 v186, v222, v223
	v_cvt_pk_bf16_f32 v126, v186, v126
	v_cvt_pk_bf16_f32 v127, v127, v128
	v_pk_mul_f32 v[128:129], v[122:123], v[210:211]
	v_pk_mul_f32 v[122:123], v[122:123], v[210:211] op_sel:[1,0] op_sel_hi:[0,1]
	v_sub_f32_e32 v128, v128, v129
	v_add_f32_e32 v122, v122, v123
	v_pk_mul_f32 v[220:221], v[124:125], v[212:213]
	v_cvt_pk_bf16_f32 v128, v128, v122
	v_pk_mul_f32 v[122:123], v[124:125], v[212:213] op_sel:[1,0] op_sel_hi:[0,1]
	v_sub_f32_e32 v129, v220, v221
	v_add_f32_e32 v122, v122, v123
	v_cvt_pk_bf16_f32 v129, v129, v122
	v_pk_mul_f32 v[122:123], v[120:121], v[216:217]
	v_pk_mul_f32 v[124:125], v[118:119], v[214:215]
	v_pk_mul_f32 v[118:119], v[118:119], v[214:215] op_sel:[1,0] op_sel_hi:[0,1]
	v_pk_mul_f32 v[120:121], v[120:121], v[216:217] op_sel:[1,0] op_sel_hi:[0,1]
	v_add_f32_e32 v118, v118, v119
	v_sub_f32_e32 v119, v122, v123
	v_add_f32_e32 v120, v120, v121
	ds_bpermute_b32 v226, v255, v126
	ds_bpermute_b32 v227, v255, v127
	ds_bpermute_b32 v228, v255, v128
	ds_bpermute_b32 v229, v255, v129
	v_lshl_add_u64 v[224:225], v[218:219], 0, v[242:243]
	s_waitcnt lgkmcnt(0)
	global_store_dwordx4 v[224:225], v[226:229], off
	v_sub_f32_e32 v124, v124, v125
	v_cvt_pk_bf16_f32 v118, v124, v118
	v_cvt_pk_bf16_f32 v119, v119, v120
	v_pk_mul_f32 v[120:121], v[114:115], v[210:211]
	v_pk_mul_f32 v[114:115], v[114:115], v[210:211] op_sel:[1,0] op_sel_hi:[0,1]
	v_pk_mul_f32 v[122:123], v[116:117], v[212:213]
	v_sub_f32_e32 v120, v120, v121
	v_add_f32_e32 v114, v114, v115
	v_cvt_pk_bf16_f32 v120, v120, v114
	v_sub_f32_e32 v121, v122, v123
	v_pk_mul_f32 v[114:115], v[116:117], v[212:213] op_sel:[1,0] op_sel_hi:[0,1]
	v_add_f32_e32 v114, v114, v115
	v_cvt_pk_bf16_f32 v121, v121, v114
	v_mul_f32_e32 v116, v207, v187
	ds_bpermute_b32 v226, v255, v118
	ds_bpermute_b32 v227, v255, v119
	ds_bpermute_b32 v228, v255, v120
	ds_bpermute_b32 v229, v255, v121
	v_lshl_add_u64 v[224:225], v[218:219], 0, v[242:243]
	s_waitcnt lgkmcnt(0)
	global_store_dwordx4 v[224:225], v[226:229], off offset:256
	v_pk_mul_f32 v[122:123], v[116:117], v[146:147] op_sel_hi:[0,1]
	v_or_b32_e32 v114, 16, v206
	v_pk_mul_f32 v[118:119], v[116:117], v[150:151] op_sel_hi:[0,1]
	v_pk_mul_f32 v[120:121], v[116:117], v[152:153] op_sel_hi:[0,1]
	v_pk_mul_f32 v[124:125], v[112:113], v[120:121]
	v_pk_mul_f32 v[126:127], v[110:111], v[118:119]
	v_pk_mul_f32 v[110:111], v[110:111], v[118:119] op_sel:[1,0] op_sel_hi:[0,1]
	v_pk_mul_f32 v[112:113], v[112:113], v[120:121] op_sel:[1,0] op_sel_hi:[0,1]
	v_add_f32_e32 v110, v110, v111
	v_sub_f32_e32 v111, v124, v125
	v_add_f32_e32 v112, v112, v113
	v_sub_f32_e32 v126, v126, v127
	v_cvt_pk_bf16_f32 v110, v126, v110
	v_cvt_pk_bf16_f32 v111, v111, v112
	v_pk_mul_f32 v[112:113], v[106:107], v[122:123]
	v_pk_mul_f32 v[106:107], v[106:107], v[122:123] op_sel:[1,0] op_sel_hi:[0,1]
	v_pk_mul_f32 v[116:117], v[116:117], v[148:149] op_sel_hi:[0,1]
	v_sub_f32_e32 v112, v112, v113
	v_add_f32_e32 v106, v106, v107
	v_pk_mul_f32 v[124:125], v[108:109], v[116:117]
	v_cvt_pk_bf16_f32 v112, v112, v106
	v_pk_mul_f32 v[106:107], v[108:109], v[116:117] op_sel:[1,0] op_sel_hi:[0,1]
	v_sub_f32_e32 v113, v124, v125
	v_add_f32_e32 v106, v106, v107
	v_mad_i64_i32 v[114:115], s[2:3], v114, s59, v[190:191]
	v_cvt_pk_bf16_f32 v113, v113, v106
	v_pk_mul_f32 v[106:107], v[104:105], v[120:121]
	v_pk_mul_f32 v[108:109], v[102:103], v[118:119]
	v_pk_mul_f32 v[102:103], v[102:103], v[118:119] op_sel:[1,0] op_sel_hi:[0,1]
	v_pk_mul_f32 v[104:105], v[104:105], v[120:121] op_sel:[1,0] op_sel_hi:[0,1]
	v_lshl_add_u64 v[114:115], v[114:115], 0, v[188:189]
	v_add_f32_e32 v102, v102, v103
	v_sub_f32_e32 v103, v106, v107
	v_add_f32_e32 v104, v104, v105
	ds_bpermute_b32 v226, v255, v110
	ds_bpermute_b32 v227, v255, v111
	ds_bpermute_b32 v228, v255, v112
	ds_bpermute_b32 v229, v255, v113
	v_lshl_add_u64 v[224:225], v[114:115], 0, v[242:243]
	s_waitcnt lgkmcnt(0)
; __device__ __forceinline__ unsigned cvt_pk_bf16(float lo, float hi) { unsigned r; asm volatile("v_cvt_pk_bf16_f32 %0, %1, %2" : "=v"(r) : "v"(lo), "v"(hi)); return r; }
;     __device__ __forceinline__ void operator()(const f32x4 (&acc)[2][2][4][2], const Unit& u, int wr, int wc, int fr, int fq) const {
;     ...
;                 for (int m = 0; m < 4; ++m) {
;                     bf16_t* rowp = Z + (size_t)(row0 + ai * HALF + m * 16) * 5120 + col0;
;                     const float sc = rs[4 * ai + m] * qs; const f32x4 c0 = cs[m][0] * sc, c1 = cs[m][1] * sc;
; #pragma unroll
;                     for (int bj = 0; bj < 2; ++bj) {
;                         const f32x4 v0 = acc[ai][bj][m][0], v1 = acc[ai][bj][m][1];
;                         u32x4 w;
;                         w.x = cvt_pk_bf16(v0[0] * c0[0] - v0[1] * c0[1], v0[1] * c0[0] + v0[0] * c0[1]);
;                         w.y = cvt_pk_bf16(v0[2] * c0[2] - v0[3] * c0[3], v0[3] * c0[2] + v0[2] * c0[3]);
;                         w.z = cvt_pk_bf16(v1[0] * c1[0] - v1[1] * c1[1], v1[1] * c1[0] + v1[0] * c1[1]);
;                         w.w = cvt_pk_bf16(v1[2] * c1[2] - v1[3] * c1[3], v1[3] * c1[2] + v1[2] * c1[3]);
;                         *(u32x4*)(rowp + bj * HALF) = w;
;                     }
;                 }
	global_store_dwordx4 v[224:225], v[226:229], off
	v_sub_f32_e32 v108, v108, v109
	v_cvt_pk_bf16_f32 v102, v108, v102
	v_cvt_pk_bf16_f32 v103, v103, v104
	v_pk_mul_f32 v[104:105], v[98:99], v[122:123]
	v_pk_mul_f32 v[98:99], v[98:99], v[122:123] op_sel:[1,0] op_sel_hi:[0,1]
	v_pk_mul_f32 v[106:107], v[100:101], v[116:117]
	v_sub_f32_e32 v104, v104, v105
	v_add_f32_e32 v98, v98, v99
	v_cvt_pk_bf16_f32 v104, v104, v98
	v_sub_f32_e32 v105, v106, v107
	v_pk_mul_f32 v[98:99], v[100:101], v[116:117] op_sel:[1,0] op_sel_hi:[0,1]
	v_add_f32_e32 v98, v98, v99
	v_cvt_pk_bf16_f32 v105, v105, v98
	v_mul_f32_e32 v100, v207, v184
	ds_bpermute_b32 v226, v255, v102
	ds_bpermute_b32 v227, v255, v103
	ds_bpermute_b32 v228, v255, v104
	ds_bpermute_b32 v229, v255, v105
	v_lshl_add_u64 v[224:225], v[114:115], 0, v[242:243]
	s_waitcnt lgkmcnt(0)
	global_store_dwordx4 v[224:225], v[226:229], off offset:256
	v_pk_mul_f32 v[106:107], v[100:101], v[138:139] op_sel_hi:[0,1]
	v_or_b32_e32 v98, 32, v206
	v_pk_mul_f32 v[102:103], v[100:101], v[142:143] op_sel_hi:[0,1]
	v_pk_mul_f32 v[104:105], v[100:101], v[144:145] op_sel_hi:[0,1]
	v_pk_mul_f32 v[108:109], v[96:97], v[104:105]
	v_pk_mul_f32 v[110:111], v[94:95], v[102:103]
	v_pk_mul_f32 v[94:95], v[94:95], v[102:103] op_sel:[1,0] op_sel_hi:[0,1]
	v_pk_mul_f32 v[96:97], v[96:97], v[104:105] op_sel:[1,0] op_sel_hi:[0,1]
	v_add_f32_e32 v94, v94, v95
	v_sub_f32_e32 v95, v108, v109
	v_add_f32_e32 v96, v96, v97
	v_sub_f32_e32 v110, v110, v111
	v_cvt_pk_bf16_f32 v94, v110, v94
	v_cvt_pk_bf16_f32 v95, v95, v96
	v_pk_mul_f32 v[96:97], v[90:91], v[106:107]
	v_pk_mul_f32 v[90:91], v[90:91], v[106:107] op_sel:[1,0] op_sel_hi:[0,1]
	v_pk_mul_f32 v[100:101], v[100:101], v[140:141] op_sel_hi:[0,1]
	v_sub_f32_e32 v96, v96, v97
	v_add_f32_e32 v90, v90, v91
	v_pk_mul_f32 v[108:109], v[92:93], v[100:101]
	v_cvt_pk_bf16_f32 v96, v96, v90
	v_pk_mul_f32 v[90:91], v[92:93], v[100:101] op_sel:[1,0] op_sel_hi:[0,1]
	v_sub_f32_e32 v97, v108, v109
	v_add_f32_e32 v90, v90, v91
	v_mad_i64_i32 v[98:99], s[2:3], v98, s59, v[190:191]
	v_cvt_pk_bf16_f32 v97, v97, v90
	v_pk_mul_f32 v[90:91], v[88:89], v[104:105]
	v_pk_mul_f32 v[92:93], v[86:87], v[102:103]
	v_pk_mul_f32 v[86:87], v[86:87], v[102:103] op_sel:[1,0] op_sel_hi:[0,1]
	v_pk_mul_f32 v[88:89], v[88:89], v[104:105] op_sel:[1,0] op_sel_hi:[0,1]
	v_lshl_add_u64 v[98:99], v[98:99], 0, v[188:189]
	v_add_f32_e32 v86, v86, v87
	v_sub_f32_e32 v87, v90, v91
	v_add_f32_e32 v88, v88, v89
	ds_bpermute_b32 v226, v255, v94
	ds_bpermute_b32 v227, v255, v95
	ds_bpermute_b32 v228, v255, v96
	ds_bpermute_b32 v229, v255, v97
	v_lshl_add_u64 v[224:225], v[98:99], 0, v[242:243]
	s_waitcnt lgkmcnt(0)
	global_store_dwordx4 v[224:225], v[226:229], off
	v_sub_f32_e32 v92, v92, v93
	v_cvt_pk_bf16_f32 v86, v92, v86
	v_cvt_pk_bf16_f32 v87, v87, v88
	v_pk_mul_f32 v[88:89], v[82:83], v[106:107]
	v_pk_mul_f32 v[82:83], v[82:83], v[106:107] op_sel:[1,0] op_sel_hi:[0,1]
	v_pk_mul_f32 v[90:91], v[84:85], v[100:101]
	v_sub_f32_e32 v88, v88, v89
	v_add_f32_e32 v82, v82, v83
	v_cvt_pk_bf16_f32 v88, v88, v82
	v_sub_f32_e32 v89, v90, v91
	v_pk_mul_f32 v[82:83], v[84:85], v[100:101] op_sel:[1,0] op_sel_hi:[0,1]
	v_add_f32_e32 v82, v82, v83
	v_cvt_pk_bf16_f32 v89, v89, v82
	v_mul_f32_e32 v84, v207, v185
	ds_bpermute_b32 v226, v255, v86
	ds_bpermute_b32 v227, v255, v87
	ds_bpermute_b32 v228, v255, v88
	ds_bpermute_b32 v229, v255, v89
	v_lshl_add_u64 v[224:225], v[98:99], 0, v[242:243]
	s_waitcnt lgkmcnt(0)
	global_store_dwordx4 v[224:225], v[226:229], off offset:256
	v_pk_mul_f32 v[90:91], v[84:85], v[130:131] op_sel_hi:[0,1]
	v_or_b32_e32 v82, 48, v206
	v_pk_mul_f32 v[86:87], v[84:85], v[134:135] op_sel_hi:[0,1]
	v_pk_mul_f32 v[88:89], v[84:85], v[136:137] op_sel_hi:[0,1]
	v_pk_mul_f32 v[92:93], v[80:81], v[88:89]
	v_pk_mul_f32 v[94:95], v[78:79], v[86:87]
	v_pk_mul_f32 v[78:79], v[78:79], v[86:87] op_sel:[1,0] op_sel_hi:[0,1]
	v_pk_mul_f32 v[80:81], v[80:81], v[88:89] op_sel:[1,0] op_sel_hi:[0,1]
	v_add_f32_e32 v78, v78, v79
	v_sub_f32_e32 v79, v92, v93
	v_add_f32_e32 v80, v80, v81
	v_sub_f32_e32 v94, v94, v95
	v_cvt_pk_bf16_f32 v78, v94, v78
	v_cvt_pk_bf16_f32 v79, v79, v80
	v_pk_mul_f32 v[80:81], v[74:75], v[90:91]
	v_pk_mul_f32 v[74:75], v[74:75], v[90:91] op_sel:[1,0] op_sel_hi:[0,1]
	v_pk_mul_f32 v[84:85], v[84:85], v[132:133] op_sel_hi:[0,1]
	v_sub_f32_e32 v80, v80, v81
	v_add_f32_e32 v74, v74, v75
	v_pk_mul_f32 v[92:93], v[76:77], v[84:85]
	v_cvt_pk_bf16_f32 v80, v80, v74
	v_pk_mul_f32 v[74:75], v[76:77], v[84:85] op_sel:[1,0] op_sel_hi:[0,1]
	v_sub_f32_e32 v81, v92, v93
	v_add_f32_e32 v74, v74, v75
	v_mad_i64_i32 v[82:83], s[2:3], v82, s59, v[190:191]
	v_cvt_pk_bf16_f32 v81, v81, v74
	v_pk_mul_f32 v[74:75], v[72:73], v[88:89]
	v_pk_mul_f32 v[76:77], v[70:71], v[86:87]
	v_pk_mul_f32 v[70:71], v[70:71], v[86:87] op_sel:[1,0] op_sel_hi:[0,1]
	v_pk_mul_f32 v[72:73], v[72:73], v[88:89] op_sel:[1,0] op_sel_hi:[0,1]
	v_lshl_add_u64 v[82:83], v[82:83], 0, v[188:189]
	v_add_f32_e32 v70, v70, v71
	v_sub_f32_e32 v71, v74, v75
	v_add_f32_e32 v72, v72, v73
	ds_bpermute_b32 v226, v255, v78
	ds_bpermute_b32 v227, v255, v79
	ds_bpermute_b32 v228, v255, v80
	ds_bpermute_b32 v229, v255, v81
	v_lshl_add_u64 v[224:225], v[82:83], 0, v[242:243]
	s_waitcnt lgkmcnt(0)
; __device__ __forceinline__ unsigned cvt_pk_bf16(float lo, float hi) { unsigned r; asm volatile("v_cvt_pk_bf16_f32 %0, %1, %2" : "=v"(r) : "v"(lo), "v"(hi)); return r; }
; #define EPI_FENCE() asm volatile("" ::: "memory")
;     __device__ __forceinline__ void operator()(const f32x4 (&acc)[2][2][4][2], const Unit& u, int wr, int wc, int fr, int fq) const {
;     ...
;             for (int ai = 0; ai < 2; ++ai) {
;                 f32x4 cs[4][2];
; #pragma unroll
;                 for (int m = 0; m < 4; ++m) { const int row = row0 + ai * HALF + m * 16; const f32x4* rp = (const f32x4*)(rope + ((size_t)(row & 4095) * 64 + j0) * 2); cs[m][0] = rp[0]; cs[m][1] = rp[1]; }
;                 EPI_FENCE();
; #pragma unroll
;                 for (int m = 0; m < 4; ++m) {
;                     bf16_t* rowp = Z + (size_t)(row0 + ai * HALF + m * 16) * 5120 + col0;
;                     const float sc = rs[4 * ai + m] * qs; const f32x4 c0 = cs[m][0] * sc, c1 = cs[m][1] * sc;
; #pragma unroll
;                     for (int bj = 0; bj < 2; ++bj) {
;                         const f32x4 v0 = acc[ai][bj][m][0], v1 = acc[ai][bj][m][1];
;                         u32x4 w;
;                         w.x = cvt_pk_bf16(v0[0] * c0[0] - v0[1] * c0[1], v0[1] * c0[0] + v0[0] * c0[1]);
;                         w.y = cvt_pk_bf16(v0[2] * c0[2] - v0[3] * c0[3], v0[3] * c0[2] + v0[2] * c0[3]);
;                         w.z = cvt_pk_bf16(v1[0] * c1[0] - v1[1] * c1[1], v1[1] * c1[0] + v1[0] * c1[1]);
;                         w.w = cvt_pk_bf16(v1[2] * c1[2] - v1[3] * c1[3], v1[3] * c1[2] + v1[2] * c1[3]);
;                         *(u32x4*)(rowp + bj * HALF) = w;
;                     }
;                 }
	global_store_dwordx4 v[224:225], v[226:229], off
	v_sub_f32_e32 v76, v76, v77
	v_cvt_pk_bf16_f32 v70, v76, v70
	v_cvt_pk_bf16_f32 v71, v71, v72
	v_pk_mul_f32 v[72:73], v[66:67], v[90:91]
	v_pk_mul_f32 v[66:67], v[66:67], v[90:91] op_sel:[1,0] op_sel_hi:[0,1]
	v_sub_f32_e32 v72, v72, v73
	v_add_f32_e32 v66, v66, v67
	v_pk_mul_f32 v[74:75], v[68:69], v[84:85]
	v_cvt_pk_bf16_f32 v72, v72, v66
	v_pk_mul_f32 v[66:67], v[68:69], v[84:85] op_sel:[1,0] op_sel_hi:[0,1]
	v_sub_f32_e32 v73, v74, v75
	v_add_f32_e32 v66, v66, v67
	v_cvt_pk_bf16_f32 v73, v73, v66
	v_add_u32_e32 v66, 0x2000, v208
	v_and_b32_e32 v66, 0x3f3c0, v66
	v_mov_b32_e32 v67, v0
	ds_bpermute_b32 v226, v255, v70
	ds_bpermute_b32 v227, v255, v71
	ds_bpermute_b32 v228, v255, v72
	ds_bpermute_b32 v229, v255, v73
	v_lshl_add_u64 v[224:225], v[82:83], 0, v[242:243]
	s_waitcnt lgkmcnt(0)
	global_store_dwordx4 v[224:225], v[226:229], off offset:256
	v_lshl_add_u64 v[68:69], v[66:67], 0, v[174:175]
	v_lshl_add_u64 v[68:69], v[68:69], 3, s[10:11]
	global_load_dwordx4 v[70:73], v[68:69], off offset:16
	global_load_dwordx4 v[74:77], v[68:69], off
	v_or_b32_e32 v68, 0x400, v66
	v_mov_b32_e32 v69, v0
	v_lshl_add_u64 v[68:69], v[68:69], 0, v[174:175]
	v_lshl_add_u64 v[68:69], v[68:69], 3, s[10:11]
	global_load_dwordx4 v[78:81], v[68:69], off offset:16
	global_load_dwordx4 v[82:85], v[68:69], off
	v_or_b32_e32 v68, 0x800, v66
	v_mov_b32_e32 v69, v0
	v_lshl_add_u64 v[68:69], v[68:69], 0, v[174:175]
	v_lshl_add_u64 v[68:69], v[68:69], 3, s[10:11]
	global_load_dwordx4 v[86:89], v[68:69], off offset:16
	global_load_dwordx4 v[90:93], v[68:69], off
	v_or_b32_e32 v66, 0xc00, v66
	v_lshl_add_u64 v[66:67], v[66:67], 0, v[174:175]
	v_lshl_add_u64 v[94:95], v[66:67], 3, s[10:11]
	global_load_dwordx4 v[66:69], v[94:95], off offset:16
	s_nop 0
	global_load_dwordx4 v[94:97], v[94:95], off
	v_mul_f32_e32 v100, v207, v182
	v_add_u32_e32 v98, 0x80, v206
	v_mad_i64_i32 v[98:99], s[2:3], v98, s59, v[190:191]
	v_lshl_add_u64 v[98:99], v[98:99], 0, v[188:189]
	s_waitcnt vmcnt(7)
	v_pk_mul_f32 v[70:71], v[100:101], v[70:71] op_sel_hi:[0,1]
	s_waitcnt vmcnt(6)
	v_pk_mul_f32 v[74:75], v[100:101], v[74:75] op_sel_hi:[0,1]
	v_pk_mul_f32 v[76:77], v[100:101], v[76:77] op_sel_hi:[0,1]
	v_pk_mul_f32 v[72:73], v[100:101], v[72:73] op_sel_hi:[0,1]
	v_pk_mul_f32 v[100:101], v[64:65], v[76:77]
	v_pk_mul_f32 v[102:103], v[62:63], v[74:75]
	v_pk_mul_f32 v[62:63], v[62:63], v[74:75] op_sel:[1,0] op_sel_hi:[0,1]
	v_pk_mul_f32 v[64:65], v[64:65], v[76:77] op_sel:[1,0] op_sel_hi:[0,1]
	v_add_f32_e32 v62, v62, v63
	v_sub_f32_e32 v63, v100, v101
	v_add_f32_e32 v64, v64, v65
	v_sub_f32_e32 v102, v102, v103
	v_cvt_pk_bf16_f32 v62, v102, v62
	v_cvt_pk_bf16_f32 v63, v63, v64
	v_pk_mul_f32 v[64:65], v[58:59], v[70:71]
	v_pk_mul_f32 v[58:59], v[58:59], v[70:71] op_sel:[1,0] op_sel_hi:[0,1]
	v_sub_f32_e32 v64, v64, v65
	v_add_f32_e32 v58, v58, v59
	v_pk_mul_f32 v[100:101], v[60:61], v[72:73]
	v_cvt_pk_bf16_f32 v64, v64, v58
	v_pk_mul_f32 v[58:59], v[60:61], v[72:73] op_sel:[1,0] op_sel_hi:[0,1]
	v_sub_f32_e32 v65, v100, v101
	v_add_f32_e32 v58, v58, v59
	v_cvt_pk_bf16_f32 v65, v65, v58
	v_pk_mul_f32 v[58:59], v[56:57], v[76:77]
	v_pk_mul_f32 v[60:61], v[54:55], v[74:75]
	v_pk_mul_f32 v[54:55], v[54:55], v[74:75] op_sel:[1,0] op_sel_hi:[0,1]
	v_pk_mul_f32 v[56:57], v[56:57], v[76:77] op_sel:[1,0] op_sel_hi:[0,1]
	v_add_f32_e32 v54, v54, v55
	v_sub_f32_e32 v55, v58, v59
	v_add_f32_e32 v56, v56, v57
	ds_bpermute_b32 v226, v255, v62
	ds_bpermute_b32 v227, v255, v63
	ds_bpermute_b32 v228, v255, v64
	ds_bpermute_b32 v229, v255, v65
	v_lshl_add_u64 v[224:225], v[98:99], 0, v[242:243]
	s_waitcnt lgkmcnt(0)
	global_store_dwordx4 v[224:225], v[226:229], off
	v_sub_f32_e32 v60, v60, v61
	v_cvt_pk_bf16_f32 v54, v60, v54
	v_cvt_pk_bf16_f32 v55, v55, v56
	v_pk_mul_f32 v[56:57], v[50:51], v[70:71]
	v_pk_mul_f32 v[50:51], v[50:51], v[70:71] op_sel:[1,0] op_sel_hi:[0,1]
	v_pk_mul_f32 v[58:59], v[52:53], v[72:73]
	v_sub_f32_e32 v56, v56, v57
	v_add_f32_e32 v50, v50, v51
	v_cvt_pk_bf16_f32 v56, v56, v50
	v_sub_f32_e32 v57, v58, v59
	v_pk_mul_f32 v[50:51], v[52:53], v[72:73] op_sel:[1,0] op_sel_hi:[0,1]
	v_add_f32_e32 v50, v50, v51
	v_cvt_pk_bf16_f32 v57, v57, v50
	v_mul_f32_e32 v52, v207, v183
	ds_bpermute_b32 v226, v255, v54
	ds_bpermute_b32 v227, v255, v55
	ds_bpermute_b32 v228, v255, v56
	ds_bpermute_b32 v229, v255, v57
	v_lshl_add_u64 v[224:225], v[98:99], 0, v[242:243]
	s_waitcnt lgkmcnt(0)
	global_store_dwordx4 v[224:225], v[226:229], off offset:256
	s_waitcnt vmcnt(7)
	v_pk_mul_f32 v[58:59], v[52:53], v[78:79] op_sel_hi:[0,1]
	v_add_u32_e32 v50, 0x90, v206
	s_waitcnt vmcnt(6)
	v_pk_mul_f32 v[54:55], v[52:53], v[82:83] op_sel_hi:[0,1]
	v_pk_mul_f32 v[56:57], v[52:53], v[84:85] op_sel_hi:[0,1]
	v_pk_mul_f32 v[60:61], v[48:49], v[56:57]
	v_pk_mul_f32 v[62:63], v[46:47], v[54:55]
	v_pk_mul_f32 v[46:47], v[46:47], v[54:55] op_sel:[1,0] op_sel_hi:[0,1]
	v_pk_mul_f32 v[48:49], v[48:49], v[56:57] op_sel:[1,0] op_sel_hi:[0,1]
	v_add_f32_e32 v46, v46, v47
	v_sub_f32_e32 v47, v60, v61
	v_add_f32_e32 v48, v48, v49
	v_sub_f32_e32 v62, v62, v63
	v_cvt_pk_bf16_f32 v46, v62, v46
	v_cvt_pk_bf16_f32 v47, v47, v48
	v_pk_mul_f32 v[48:49], v[42:43], v[58:59]
	v_pk_mul_f32 v[42:43], v[42:43], v[58:59] op_sel:[1,0] op_sel_hi:[0,1]
	v_pk_mul_f32 v[52:53], v[52:53], v[80:81] op_sel_hi:[0,1]
	v_sub_f32_e32 v48, v48, v49
	v_add_f32_e32 v42, v42, v43
	v_pk_mul_f32 v[60:61], v[44:45], v[52:53]
	v_cvt_pk_bf16_f32 v48, v48, v42
	v_pk_mul_f32 v[42:43], v[44:45], v[52:53] op_sel:[1,0] op_sel_hi:[0,1]
	v_sub_f32_e32 v49, v60, v61
	v_add_f32_e32 v42, v42, v43
	v_mad_i64_i32 v[50:51], s[2:3], v50, s59, v[190:191]
	v_cvt_pk_bf16_f32 v49, v49, v42
	v_pk_mul_f32 v[42:43], v[40:41], v[56:57]
	v_pk_mul_f32 v[44:45], v[38:39], v[54:55]
	v_pk_mul_f32 v[38:39], v[38:39], v[54:55] op_sel:[1,0] op_sel_hi:[0,1]
	v_pk_mul_f32 v[40:41], v[40:41], v[56:57] op_sel:[1,0] op_sel_hi:[0,1]
	v_lshl_add_u64 v[50:51], v[50:51], 0, v[188:189]
	v_add_f32_e32 v38, v38, v39
	v_sub_f32_e32 v39, v42, v43
	v_add_f32_e32 v40, v40, v41
	ds_bpermute_b32 v226, v255, v46
	ds_bpermute_b32 v227, v255, v47
	ds_bpermute_b32 v228, v255, v48
	ds_bpermute_b32 v229, v255, v49
	v_lshl_add_u64 v[224:225], v[50:51], 0, v[242:243]
	s_waitcnt lgkmcnt(0)
; __device__ __forceinline__ unsigned cvt_pk_bf16(float lo, float hi) { unsigned r; asm volatile("v_cvt_pk_bf16_f32 %0, %1, %2" : "=v"(r) : "v"(lo), "v"(hi)); return r; }
;     __device__ __forceinline__ void operator()(const f32x4 (&acc)[2][2][4][2], const Unit& u, int wr, int wc, int fr, int fq) const {
;     ...
;                 for (int m = 0; m < 4; ++m) {
;                     bf16_t* rowp = Z + (size_t)(row0 + ai * HALF + m * 16) * 5120 + col0;
;                     const float sc = rs[4 * ai + m] * qs; const f32x4 c0 = cs[m][0] * sc, c1 = cs[m][1] * sc;
; #pragma unroll
;                     for (int bj = 0; bj < 2; ++bj) {
;                         const f32x4 v0 = acc[ai][bj][m][0], v1 = acc[ai][bj][m][1];
;                         u32x4 w;
;                         w.x = cvt_pk_bf16(v0[0] * c0[0] - v0[1] * c0[1], v0[1] * c0[0] + v0[0] * c0[1]);
;                         w.y = cvt_pk_bf16(v0[2] * c0[2] - v0[3] * c0[3], v0[3] * c0[2] + v0[2] * c0[3]);
;                         w.z = cvt_pk_bf16(v1[0] * c1[0] - v1[1] * c1[1], v1[1] * c1[0] + v1[0] * c1[1]);
;                         w.w = cvt_pk_bf16(v1[2] * c1[2] - v1[3] * c1[3], v1[3] * c1[2] + v1[2] * c1[3]);
;                         *(u32x4*)(rowp + bj * HALF) = w;
;                     }
;                 }
	global_store_dwordx4 v[224:225], v[226:229], off
	v_sub_f32_e32 v44, v44, v45
	v_cvt_pk_bf16_f32 v38, v44, v38
	v_cvt_pk_bf16_f32 v39, v39, v40
	v_pk_mul_f32 v[40:41], v[34:35], v[58:59]
	v_pk_mul_f32 v[34:35], v[34:35], v[58:59] op_sel:[1,0] op_sel_hi:[0,1]
	v_pk_mul_f32 v[42:43], v[36:37], v[52:53]
	v_sub_f32_e32 v40, v40, v41
	v_add_f32_e32 v34, v34, v35
	v_cvt_pk_bf16_f32 v40, v40, v34
	v_sub_f32_e32 v41, v42, v43
	v_pk_mul_f32 v[34:35], v[36:37], v[52:53] op_sel:[1,0] op_sel_hi:[0,1]
	v_add_f32_e32 v34, v34, v35
	v_cvt_pk_bf16_f32 v41, v41, v34
	v_mul_f32_e32 v36, v207, v180
	ds_bpermute_b32 v226, v255, v38
	ds_bpermute_b32 v227, v255, v39
	ds_bpermute_b32 v228, v255, v40
	ds_bpermute_b32 v229, v255, v41
	v_lshl_add_u64 v[224:225], v[50:51], 0, v[242:243]
	s_waitcnt lgkmcnt(0)
	global_store_dwordx4 v[224:225], v[226:229], off offset:256
	s_waitcnt vmcnt(7)
	v_pk_mul_f32 v[42:43], v[36:37], v[86:87] op_sel_hi:[0,1]
	v_add_u32_e32 v34, 0xa0, v206
	s_waitcnt vmcnt(6)
	v_pk_mul_f32 v[38:39], v[36:37], v[90:91] op_sel_hi:[0,1]
	v_pk_mul_f32 v[40:41], v[36:37], v[92:93] op_sel_hi:[0,1]
	v_pk_mul_f32 v[44:45], v[32:33], v[40:41]
	v_pk_mul_f32 v[46:47], v[30:31], v[38:39]
	v_pk_mul_f32 v[30:31], v[30:31], v[38:39] op_sel:[1,0] op_sel_hi:[0,1]
	v_pk_mul_f32 v[32:33], v[32:33], v[40:41] op_sel:[1,0] op_sel_hi:[0,1]
	v_add_f32_e32 v30, v30, v31
	v_sub_f32_e32 v31, v44, v45
	v_add_f32_e32 v32, v32, v33
	v_sub_f32_e32 v46, v46, v47
	v_cvt_pk_bf16_f32 v30, v46, v30
	v_cvt_pk_bf16_f32 v31, v31, v32
	v_pk_mul_f32 v[32:33], v[26:27], v[42:43]
	v_pk_mul_f32 v[26:27], v[26:27], v[42:43] op_sel:[1,0] op_sel_hi:[0,1]
	v_pk_mul_f32 v[36:37], v[36:37], v[88:89] op_sel_hi:[0,1]
	v_sub_f32_e32 v32, v32, v33
	v_add_f32_e32 v26, v26, v27
	v_pk_mul_f32 v[44:45], v[28:29], v[36:37]
	v_cvt_pk_bf16_f32 v32, v32, v26
	v_pk_mul_f32 v[26:27], v[28:29], v[36:37] op_sel:[1,0] op_sel_hi:[0,1]
	v_sub_f32_e32 v33, v44, v45
	v_add_f32_e32 v26, v26, v27
	v_mad_i64_i32 v[34:35], s[2:3], v34, s59, v[190:191]
	v_cvt_pk_bf16_f32 v33, v33, v26
	v_pk_mul_f32 v[26:27], v[24:25], v[40:41]
	v_pk_mul_f32 v[28:29], v[22:23], v[38:39]
	v_pk_mul_f32 v[22:23], v[22:23], v[38:39] op_sel:[1,0] op_sel_hi:[0,1]
	v_pk_mul_f32 v[24:25], v[24:25], v[40:41] op_sel:[1,0] op_sel_hi:[0,1]
	v_lshl_add_u64 v[34:35], v[34:35], 0, v[188:189]
	v_add_f32_e32 v22, v22, v23
	v_sub_f32_e32 v23, v26, v27
	v_add_f32_e32 v24, v24, v25
	ds_bpermute_b32 v226, v255, v30
	ds_bpermute_b32 v227, v255, v31
	ds_bpermute_b32 v228, v255, v32
	ds_bpermute_b32 v229, v255, v33
	v_lshl_add_u64 v[224:225], v[34:35], 0, v[242:243]
	s_waitcnt lgkmcnt(0)
	global_store_dwordx4 v[224:225], v[226:229], off
	v_sub_f32_e32 v28, v28, v29
	v_cvt_pk_bf16_f32 v22, v28, v22
	v_cvt_pk_bf16_f32 v23, v23, v24
	v_pk_mul_f32 v[24:25], v[18:19], v[42:43]
	v_pk_mul_f32 v[18:19], v[18:19], v[42:43] op_sel:[1,0] op_sel_hi:[0,1]
	v_pk_mul_f32 v[26:27], v[20:21], v[36:37]
	v_sub_f32_e32 v24, v24, v25
	v_add_f32_e32 v18, v18, v19
	v_cvt_pk_bf16_f32 v24, v24, v18
	v_sub_f32_e32 v25, v26, v27
	v_pk_mul_f32 v[18:19], v[20:21], v[36:37] op_sel:[1,0] op_sel_hi:[0,1]
	v_add_f32_e32 v18, v18, v19
	v_cvt_pk_bf16_f32 v25, v25, v18
	v_mul_f32_e32 v20, v207, v181
	ds_bpermute_b32 v226, v255, v22
	ds_bpermute_b32 v227, v255, v23
	ds_bpermute_b32 v228, v255, v24
	ds_bpermute_b32 v229, v255, v25
	v_lshl_add_u64 v[224:225], v[34:35], 0, v[242:243]
	s_waitcnt lgkmcnt(0)
	global_store_dwordx4 v[224:225], v[226:229], off offset:256
	s_waitcnt vmcnt(7)
	v_pk_mul_f32 v[26:27], v[20:21], v[66:67] op_sel_hi:[0,1]
	v_add_u32_e32 v18, 0xb0, v206
	s_waitcnt vmcnt(6)
	v_pk_mul_f32 v[22:23], v[20:21], v[94:95] op_sel_hi:[0,1]
	v_pk_mul_f32 v[24:25], v[20:21], v[96:97] op_sel_hi:[0,1]
	v_pk_mul_f32 v[28:29], v[16:17], v[24:25]
	v_pk_mul_f32 v[30:31], v[14:15], v[22:23]
	v_pk_mul_f32 v[14:15], v[14:15], v[22:23] op_sel:[1,0] op_sel_hi:[0,1]
	v_pk_mul_f32 v[16:17], v[16:17], v[24:25] op_sel:[1,0] op_sel_hi:[0,1]
	v_add_f32_e32 v14, v14, v15
	v_sub_f32_e32 v15, v28, v29
	v_add_f32_e32 v16, v16, v17
	v_sub_f32_e32 v30, v30, v31
	v_cvt_pk_bf16_f32 v14, v30, v14
	v_cvt_pk_bf16_f32 v15, v15, v16
	v_pk_mul_f32 v[16:17], v[10:11], v[26:27]
	v_pk_mul_f32 v[10:11], v[10:11], v[26:27] op_sel:[1,0] op_sel_hi:[0,1]
	v_pk_mul_f32 v[20:21], v[20:21], v[68:69] op_sel_hi:[0,1]
	v_sub_f32_e32 v16, v16, v17
	v_add_f32_e32 v10, v10, v11
	v_pk_mul_f32 v[28:29], v[12:13], v[20:21]
	v_cvt_pk_bf16_f32 v16, v16, v10
	v_pk_mul_f32 v[10:11], v[12:13], v[20:21] op_sel:[1,0] op_sel_hi:[0,1]
	v_sub_f32_e32 v17, v28, v29
	v_add_f32_e32 v10, v10, v11
	v_mad_i64_i32 v[18:19], s[2:3], v18, s59, v[190:191]
	v_cvt_pk_bf16_f32 v17, v17, v10
	v_pk_mul_f32 v[10:11], v[8:9], v[24:25]
	v_pk_mul_f32 v[12:13], v[6:7], v[22:23]
	v_pk_mul_f32 v[6:7], v[6:7], v[22:23] op_sel:[1,0] op_sel_hi:[0,1]
	v_pk_mul_f32 v[8:9], v[8:9], v[24:25] op_sel:[1,0] op_sel_hi:[0,1]
	v_lshl_add_u64 v[18:19], v[18:19], 0, v[188:189]
	v_add_f32_e32 v6, v6, v7
	v_sub_f32_e32 v7, v10, v11
	v_add_f32_e32 v8, v8, v9
	ds_bpermute_b32 v226, v255, v14
	ds_bpermute_b32 v227, v255, v15
	ds_bpermute_b32 v228, v255, v16
	ds_bpermute_b32 v229, v255, v17
	v_lshl_add_u64 v[224:225], v[18:19], 0, v[242:243]
	s_waitcnt lgkmcnt(0)
	global_store_dwordx4 v[224:225], v[226:229], off
	v_sub_f32_e32 v12, v12, v13
	v_cvt_pk_bf16_f32 v6, v12, v6
	v_cvt_pk_bf16_f32 v7, v7, v8
	v_pk_mul_f32 v[8:9], v[2:3], v[26:27]
	v_pk_mul_f32 v[2:3], v[2:3], v[26:27] op_sel:[1,0] op_sel_hi:[0,1]
	v_pk_mul_f32 v[10:11], v[4:5], v[20:21]
	v_sub_f32_e32 v8, v8, v9
	v_add_f32_e32 v2, v2, v3
	v_cvt_pk_bf16_f32 v8, v8, v2
	v_sub_f32_e32 v9, v10, v11
	v_pk_mul_f32 v[2:3], v[4:5], v[20:21] op_sel:[1,0] op_sel_hi:[0,1]
	v_add_f32_e32 v2, v2, v3
	v_cvt_pk_bf16_f32 v9, v9, v2
	ds_bpermute_b32 v226, v255, v6
	ds_bpermute_b32 v227, v255, v7
	ds_bpermute_b32 v228, v255, v8
	ds_bpermute_b32 v229, v255, v9
	v_lshl_add_u64 v[224:225], v[18:19], 0, v[242:243]
	s_waitcnt lgkmcnt(0)
	global_store_dwordx4 v[224:225], v[226:229], off offset:256

; __device__ __forceinline__ float sum_16_32(float v) { v += __shfl_xor(v, 16); v += __shfl_xor(v, 32); return v; }
; __device__ __forceinline__ unsigned cvt_pk_bf16(float lo, float hi) { unsigned r; asm volatile("v_cvt_pk_bf16_f32 %0, %1, %2" : "=v"(r) : "v"(lo), "v"(hi)); return r; }
;     __device__ __forceinline__ void operator()(const f32x4 (&acc)[2][2][4][2], const Unit& u, int wr, int wc, int fr, int fq) const {
;         const int row0 = u.pm * BM + wr * 64 + fr; const int col0 = u.pn * BM + wc * 32 + 8 * fq;
;         const unsigned ob0 = ((unsigned)row0 * LDC + (unsigned)col0) * 4u;
;         char* ob = (char*)out; char* xbb = (char*)xb;
; #pragma unroll
;         for (int ai = 0; ai < 2; ++ai) { float sm[4];
; #pragma unroll
;             for (int m = 0; m < 4; ++m) { const unsigned o = ob0 + (unsigned)((ai * HALF + m * 16) * LDC * 4); float s = 0.f;
; #pragma unroll
;                 for (int bj = 0; bj < 2; ++bj) {
;                     const f32x4 o0 = acc[ai][bj][m][0], o1 = acc[ai][bj][m][1];
;                     s += (o0[0] * o0[0] + o0[1] * o0[1]) + (o0[2] * o0[2] + o0[3] * o0[3]) + (o1[0] * o1[0] + o1[1] * o1[1]) + (o1[2] * o1[2] + o1[3] * o1[3]);
;                     if (wf32) { *(f32x4*)(ob + o + bj * HALF * 4) = o0; *(f32x4*)(ob + o + bj * HALF * 4 + 16) = o1; }
;                     else { u32x4 w; w.x = cvt_pk_bf16(o0[0], o0[1]); w.y = cvt_pk_bf16(o0[2], o0[3]); w.z = cvt_pk_bf16(o1[0], o1[1]); w.w = cvt_pk_bf16(o1[2], o1[3]);
;                            *(u32x4*)(xbb + (o >> 1) + bj * HALF * 2) = w; } }
;                 s = sum_16_32(s);
;                 sm[m] = s; }
.LBB0_378:
	v_mbcnt_lo_u32_b32 v182, -1, 0
	v_mbcnt_hi_u32_b32 v182, -1, v182
	v_lshrrev_b32_e32 v180, 2, v182
	v_and_b32_e32 v183, 15, v182
	v_sub_u32_e32 v180, v180, v183
	v_mov_b32_e32 v183, 0x1000
	v_mul_i32_i24_e32 v180, v180, v183
	v_and_b32_e32 v183, 3, v182
	v_lshrrev_b32_e32 v182, 4, v182
	v_sub_u32_e32 v183, v183, v182
	v_lshl_add_u32 v180, v183, 4, v180
	v_ashrrev_i32_e32 v181, 31, v180
	v_cvt_pk_bf16_f32 v166, v118, v119
	v_mov_b32_e32 v152, v118
	v_mov_b32_e32 v118, v119
	v_mov_b32_e32 v119, v123
	v_mov_b32_e32 v153, v122
	v_pk_mul_f32 v[118:119], v[118:119], v[118:119]
	v_cvt_pk_bf16_f32 v167, v120, v121
	v_cvt_pk_bf16_f32 v168, v114, v115
	v_cvt_pk_bf16_f32 v169, v116, v117
	s_lshl_b32 s0, s48, 8
	v_pk_fma_f32 v[118:119], v[152:153], v[152:153], v[118:119]
	v_mov_b32_e32 v152, v120
	v_mov_b32_e32 v120, v121
	v_mov_b32_e32 v121, v125
	v_mov_b32_e32 v153, v124
	v_pk_mul_f32 v[120:121], v[120:121], v[120:121]
	s_lshl_b32 s1, s33, 10
	v_pk_fma_f32 v[120:121], v[152:153], v[152:153], v[120:121]
	v_add_lshl_u32 v145, s0, v146, 13
	v_pk_add_f32 v[118:119], v[118:119], v[120:121]
	v_mov_b32_e32 v120, v114
	v_mov_b32_e32 v114, v115
	v_mov_b32_e32 v115, v127
	v_mov_b32_e32 v121, v126
	v_pk_mul_f32 v[114:115], v[114:115], v[114:115]
	v_add3_u32 v151, v148, s1, v145
	v_pk_fma_f32 v[114:115], v[120:121], v[120:121], v[114:115]
	v_lshrrev_b32_e32 v145, 1, v151
	v_pk_add_f32 v[114:115], v[118:119], v[114:115]
	v_mov_b32_e32 v118, v116
	v_mov_b32_e32 v116, v117
	v_mov_b32_e32 v117, v129
	v_mov_b32_e32 v119, v128
	v_pk_mul_f32 v[116:117], v[116:117], v[116:117]
	ds_bpermute_b32 v176, v255, v166
	ds_bpermute_b32 v177, v255, v167
	ds_bpermute_b32 v178, v255, v168
	ds_bpermute_b32 v179, v255, v169
	v_add_u32_e32 v174, v145, v180
	s_waitcnt lgkmcnt(0)
	global_store_dwordx4 v174, v[176:179], s[12:13]
	v_pk_fma_f32 v[116:117], v[118:119], v[118:119], v[116:117]
	v_readlane_b32 s50, v252, 33
	v_pk_add_f32 v[114:115], v[116:117], v[114:115]
	v_cmp_lt_i32_e32 vcc, 0, v1
	v_add_f32_e32 v118, v114, v115
	ds_bpermute_b32 v119, v172, v118
	v_cvt_pk_bf16_f32 v114, v122, v123
	v_cvt_pk_bf16_f32 v115, v124, v125
	v_cvt_pk_bf16_f32 v116, v126, v127
	v_cvt_pk_bf16_f32 v117, v128, v129
	ds_bpermute_b32 v176, v255, v114
	ds_bpermute_b32 v177, v255, v115
	ds_bpermute_b32 v178, v255, v116
	ds_bpermute_b32 v179, v255, v117
	v_add_u32_e32 v174, v145, v180
	s_waitcnt lgkmcnt(0)
	global_store_dwordx4 v174, v[176:179], s[12:13] offset:256
	s_mov_b64 s[2:3], 0
	v_readlane_b32 s51, v252, 34
	v_add_u32_e32 v116, 0x20000, v151
	v_mul_f32_e32 v117, v99, v99
	s_waitcnt lgkmcnt(0)
	v_add_f32_e32 v114, v118, v119
	v_lshrrev_b32_e32 v116, 1, v116
	v_fmac_f32_e32 v117, v98, v98
	v_mul_f32_e32 v118, v101, v101
	v_cvt_pk_bf16_f32 v98, v98, v99
	v_cvt_pk_bf16_f32 v99, v100, v101
	v_fmac_f32_e32 v118, v100, v100
	v_cvt_pk_bf16_f32 v100, v106, v107
	v_cvt_pk_bf16_f32 v101, v108, v109
	ds_bpermute_b32 v176, v255, v98
	ds_bpermute_b32 v177, v255, v99
	ds_bpermute_b32 v178, v255, v100
	ds_bpermute_b32 v179, v255, v101
	v_add_u32_e32 v174, v116, v180
	s_waitcnt lgkmcnt(0)
	global_store_dwordx4 v174, v[176:179], s[12:13]
	v_add_f32_e32 v117, v117, v118
	v_mul_f32_e32 v118, v107, v107
	v_mul_f32_e32 v98, v103, v103
	v_mul_f32_e32 v99, v105, v105
	v_fmac_f32_e32 v98, v102, v102
	v_fmac_f32_e32 v99, v104, v104
	v_add_f32_e32 v98, v98, v99
	v_mul_f32_e32 v99, v111, v111
	v_fmac_f32_e32 v118, v106, v106
	v_fmac_f32_e32 v99, v110, v110
	v_add_f32_e32 v117, v117, v118
	v_mul_f32_e32 v118, v109, v109
	v_add_f32_e32 v98, v98, v99
	v_mul_f32_e32 v99, v113, v113
	v_fmac_f32_e32 v118, v108, v108
	v_fmac_f32_e32 v99, v112, v112
	v_add_f32_e32 v117, v118, v117
	v_add_f32_e32 v98, v99, v98
	v_add_f32_e32 v106, v117, v98
	v_cvt_pk_bf16_f32 v98, v102, v103
	ds_bpermute_b32 v102, v172, v106
	v_cvt_pk_bf16_f32 v99, v104, v105
	v_cvt_pk_bf16_f32 v100, v110, v111
	v_cvt_pk_bf16_f32 v101, v112, v113
	ds_bpermute_b32 v176, v255, v98
	ds_bpermute_b32 v177, v255, v99
	ds_bpermute_b32 v178, v255, v100
	ds_bpermute_b32 v179, v255, v101
	v_add_u32_e32 v174, v116, v180
	s_waitcnt lgkmcnt(0)
; __device__ __forceinline__ float sum_16_32(float v) { v += __shfl_xor(v, 16); v += __shfl_xor(v, 32); return v; }
; __device__ __forceinline__ unsigned cvt_pk_bf16(float lo, float hi) { unsigned r; asm volatile("v_cvt_pk_bf16_f32 %0, %1, %2" : "=v"(r) : "v"(lo), "v"(hi)); return r; }
;     __device__ __forceinline__ void operator()(const f32x4 (&acc)[2][2][4][2], const Unit& u, int wr, int wc, int fr, int fq) const {
;     ...
;             for (int m = 0; m < 4; ++m) { const unsigned o = ob0 + (unsigned)((ai * HALF + m * 16) * LDC * 4); float s = 0.f;
; #pragma unroll
;                 for (int bj = 0; bj < 2; ++bj) {
;                     const f32x4 o0 = acc[ai][bj][m][0], o1 = acc[ai][bj][m][1];
;                     s += (o0[0] * o0[0] + o0[1] * o0[1]) + (o0[2] * o0[2] + o0[3] * o0[3]) + (o1[0] * o1[0] + o1[1] * o1[1]) + (o1[2] * o1[2] + o1[3] * o1[3]);
;                     if (wf32) { *(f32x4*)(ob + o + bj * HALF * 4) = o0; *(f32x4*)(ob + o + bj * HALF * 4 + 16) = o1; }
;                     else { u32x4 w; w.x = cvt_pk_bf16(o0[0], o0[1]); w.y = cvt_pk_bf16(o0[2], o0[3]); w.z = cvt_pk_bf16(o1[0], o1[1]); w.w = cvt_pk_bf16(o1[2], o1[3]);
;                            *(u32x4*)(xbb + (o >> 1) + bj * HALF * 2) = w; } }
;                 s = sum_16_32(s);
;                 sm[m] = s; }
;             ss[(size_t)(4 * u.pn + wc) * 16384 + u.pm * BM + wr * 64 + ai * HALF + 16 * fq + fr] = fq == 0 ? sm[0] : (fq == 1 ? sm[1] : (fq == 2 ? sm[2] : sm[3])); }
	global_store_dwordx4 v174, v[176:179], s[12:13] offset:256
	ds_bpermute_b32 v115, v173, v114
	s_nop 0
	v_add_u32_e32 v100, 0x40000, v151
	v_mul_f32_e32 v101, v83, v83
	s_waitcnt lgkmcnt(0)
	v_add_f32_e32 v98, v106, v102
	v_lshrrev_b32_e32 v100, 1, v100
	v_fmac_f32_e32 v101, v82, v82
	v_mul_f32_e32 v102, v85, v85
	v_cvt_pk_bf16_f32 v82, v82, v83
	v_cvt_pk_bf16_f32 v83, v84, v85
	v_fmac_f32_e32 v102, v84, v84
	v_cvt_pk_bf16_f32 v84, v90, v91
	v_cvt_pk_bf16_f32 v85, v92, v93
	ds_bpermute_b32 v176, v255, v82
	ds_bpermute_b32 v177, v255, v83
	ds_bpermute_b32 v178, v255, v84
	ds_bpermute_b32 v179, v255, v85
	v_add_u32_e32 v174, v100, v180
	s_waitcnt lgkmcnt(0)
	global_store_dwordx4 v174, v[176:179], s[12:13]
	v_add_f32_e32 v101, v101, v102
	v_mul_f32_e32 v102, v91, v91
	v_mul_f32_e32 v82, v87, v87
	v_mul_f32_e32 v83, v89, v89
	v_fmac_f32_e32 v82, v86, v86
	v_fmac_f32_e32 v83, v88, v88
	v_add_f32_e32 v82, v82, v83
	v_mul_f32_e32 v83, v95, v95
	v_fmac_f32_e32 v102, v90, v90
	v_fmac_f32_e32 v83, v94, v94
	v_add_f32_e32 v101, v101, v102
	v_mul_f32_e32 v102, v93, v93
	v_add_f32_e32 v82, v82, v83
	v_mul_f32_e32 v83, v97, v97
	v_fmac_f32_e32 v102, v92, v92
	v_fmac_f32_e32 v83, v96, v96
	v_add_f32_e32 v101, v102, v101
	v_add_f32_e32 v82, v83, v82
	v_add_f32_e32 v90, v101, v82
	v_cvt_pk_bf16_f32 v82, v86, v87
	ds_bpermute_b32 v86, v172, v90
	v_cvt_pk_bf16_f32 v83, v88, v89
	v_cvt_pk_bf16_f32 v84, v94, v95
	v_cvt_pk_bf16_f32 v85, v96, v97
	ds_bpermute_b32 v176, v255, v82
	ds_bpermute_b32 v177, v255, v83
	ds_bpermute_b32 v178, v255, v84
	ds_bpermute_b32 v179, v255, v85
	v_add_u32_e32 v174, v100, v180
	s_waitcnt lgkmcnt(0)
	global_store_dwordx4 v174, v[176:179], s[12:13] offset:256
	ds_bpermute_b32 v99, v173, v98
	s_waitcnt lgkmcnt(0)
	v_add_f32_e32 v82, v90, v86
	v_mul_f32_e32 v85, v75, v75
	v_mul_f32_e32 v86, v77, v77
	v_fmac_f32_e32 v85, v74, v74
	v_fmac_f32_e32 v86, v76, v76
	v_cvt_pk_bf16_f32 v74, v74, v75
	v_cvt_pk_bf16_f32 v75, v76, v77
	v_mul_f32_e32 v76, v71, v71
	v_mul_f32_e32 v77, v73, v73
	v_fmac_f32_e32 v76, v70, v70
	v_fmac_f32_e32 v77, v72, v72
	v_add_f32_e32 v85, v85, v86
	v_mul_f32_e32 v86, v67, v67
	v_add_f32_e32 v76, v76, v77
	v_mul_f32_e32 v77, v79, v79
	v_fmac_f32_e32 v86, v66, v66
	v_fmac_f32_e32 v77, v78, v78
	v_add_f32_e32 v85, v85, v86
	v_mul_f32_e32 v86, v69, v69
	v_add_f32_e32 v76, v76, v77
	v_mul_f32_e32 v77, v81, v81
	v_fmac_f32_e32 v86, v68, v68
	v_fmac_f32_e32 v77, v80, v80
	v_add_f32_e32 v85, v86, v85
	v_add_f32_e32 v76, v77, v76
	v_add_f32_e32 v85, v85, v76
	ds_bpermute_b32 v86, v172, v85
	v_cvt_pk_bf16_f32 v76, v66, v67
	ds_bpermute_b32 v83, v173, v82
	v_add_u32_e32 v84, 0x60000, v151
	v_lshrrev_b32_e32 v84, 1, v84
	s_waitcnt lgkmcnt(0)
	v_add_f32_e32 v66, v85, v86
	ds_bpermute_b32 v67, v173, v66
	v_cvt_pk_bf16_f32 v77, v68, v69
	ds_bpermute_b32 v176, v255, v74
	ds_bpermute_b32 v177, v255, v75
	ds_bpermute_b32 v178, v255, v76
	ds_bpermute_b32 v179, v255, v77
	v_add_u32_e32 v174, v84, v180
	s_waitcnt lgkmcnt(0)
	global_store_dwordx4 v174, v[176:179], s[12:13]
	v_cvt_pk_bf16_f32 v68, v70, v71
	v_cvt_pk_bf16_f32 v69, v72, v73
	v_cvt_pk_bf16_f32 v70, v78, v79
	v_cvt_pk_bf16_f32 v71, v80, v81
	ds_bpermute_b32 v176, v255, v68
	ds_bpermute_b32 v177, v255, v69
	ds_bpermute_b32 v178, v255, v70
	ds_bpermute_b32 v179, v255, v71
	v_add_u32_e32 v174, v84, v180
	s_waitcnt lgkmcnt(0)
	global_store_dwordx4 v174, v[176:179], s[12:13] offset:256
	s_and_saveexec_b64 s[10:11], vcc
	s_xor_b64 s[10:11], exec, s[10:11]
	s_cbranch_execz .LBB0_388
	v_cmp_eq_u32_e32 vcc, 1, v1
	s_mov_b64 s[2:3], -1
	s_and_saveexec_b64 s[26:27], vcc
	v_add_f32_e32 v68, v98, v99
	s_xor_b64 s[2:3], exec, -1
	s_or_b64 exec, exec, s[26:27]
	s_and_b64 s[2:3], s[2:3], exec
	s_or_saveexec_b64 s[10:11], s[10:11]
	v_cmp_ne_u32_e32 vcc, 0, v1
	s_xor_b64 exec, exec, s[10:11]
	s_cbranch_execnz .LBB0_389

; __device__ __forceinline__ unsigned cvt_pk_bf16(float lo, float hi) { unsigned r; asm volatile("v_cvt_pk_bf16_f32 %0, %1, %2" : "=v"(r) : "v"(lo), "v"(hi)); return r; }
;     __device__ __forceinline__ void operator()(const f32x4 (&acc)[2][2][4][2], const Unit& u, int wr, int wc, int fr, int fq) const {
;     ...
;         for (int ai = 0; ai < 2; ++ai) { float sm[4];
; #pragma unroll
;             for (int m = 0; m < 4; ++m) { const unsigned o = ob0 + (unsigned)((ai * HALF + m * 16) * LDC * 4); float s = 0.f;
; #pragma unroll
;                 for (int bj = 0; bj < 2; ++bj) {
;                     const f32x4 o0 = acc[ai][bj][m][0], o1 = acc[ai][bj][m][1];
;                     s += (o0[0] * o0[0] + o0[1] * o0[1]) + (o0[2] * o0[2] + o0[3] * o0[3]) + (o1[0] * o1[0] + o1[1] * o1[1]) + (o1[2] * o1[2] + o1[3] * o1[3]);
;                     if (wf32) { *(f32x4*)(ob + o + bj * HALF * 4) = o0; *(f32x4*)(ob + o + bj * HALF * 4 + 16) = o1; }
;                     else { u32x4 w; w.x = cvt_pk_bf16(o0[0], o0[1]); w.y = cvt_pk_bf16(o0[2], o0[3]); w.z = cvt_pk_bf16(o1[0], o1[1]); w.w = cvt_pk_bf16(o1[2], o1[3]);
;                            *(u32x4*)(xbb + (o >> 1) + bj * HALF * 2) = w; } }
;     ...
;             ss[(size_t)(4 * u.pn + wc) * 16384 + u.pm * BM + wr * 64 + ai * HALF + 16 * fq + fr] = fq == 0 ? sm[0] : (fq == 1 ? sm[1] : (fq == 2 ? sm[2] : sm[3])); }
.LBB0_384:
	s_or_b64 exec, exec, s[10:11]
	s_lshl_b32 s1, s33, 2
	s_or_b32 s2, s1, s36
	s_ashr_i32 s3, s2, 31
	s_ashr_i32 s1, s0, 31
	s_lshl_b64 s[2:3], s[2:3], 16
	s_add_u32 s2, s42, s2
	s_addc_u32 s3, s43, s3
	s_lshl_b64 s[0:1], s[0:1], 2
	s_add_u32 s0, s2, s0
	s_addc_u32 s1, s3, s1
	s_add_u32 s0, s0, s18
	s_addc_u32 s1, s1, s19
	s_waitcnt lgkmcnt(0)
	v_lshl_add_u64 v[66:67], v[138:139], 2, s[0:1]
	v_mov_b32_e32 v145, v0
	v_lshl_add_u64 v[66:67], v[66:67], 0, v[144:145]
	global_store_dword v[66:67], v68, off
	v_add_u32_e32 v68, 0x100000, v151
	v_mul_f32_e32 v69, v35, v35
	v_lshrrev_b32_e32 v68, 1, v68
	v_fmac_f32_e32 v69, v34, v34
	v_mul_f32_e32 v70, v37, v37
	v_cvt_pk_bf16_f32 v34, v34, v35
	v_cvt_pk_bf16_f32 v35, v36, v37
	v_fmac_f32_e32 v70, v36, v36
	v_cvt_pk_bf16_f32 v36, v46, v47
	v_cvt_pk_bf16_f32 v37, v48, v49
	ds_bpermute_b32 v176, v255, v34
	ds_bpermute_b32 v177, v255, v35
	ds_bpermute_b32 v178, v255, v36
	ds_bpermute_b32 v179, v255, v37
	v_add_u32_e32 v174, v68, v180
	s_waitcnt lgkmcnt(0)
	global_store_dwordx4 v174, v[176:179], s[12:13]
	v_add_f32_e32 v69, v69, v70
	v_mul_f32_e32 v70, v47, v47
	v_mul_f32_e32 v34, v39, v39
	v_mul_f32_e32 v35, v41, v41
	v_fmac_f32_e32 v34, v38, v38
	v_fmac_f32_e32 v35, v40, v40
	v_add_f32_e32 v34, v34, v35
	v_mul_f32_e32 v35, v55, v55
	v_fmac_f32_e32 v70, v46, v46
	v_fmac_f32_e32 v35, v54, v54
	v_add_f32_e32 v69, v69, v70
	v_mul_f32_e32 v70, v49, v49
	v_add_f32_e32 v34, v34, v35
	v_mul_f32_e32 v35, v57, v57
	v_fmac_f32_e32 v70, v48, v48
	v_fmac_f32_e32 v35, v56, v56
	v_add_f32_e32 v69, v70, v69
	v_add_f32_e32 v34, v35, v34
	v_add_f32_e32 v46, v69, v34
	v_cvt_pk_bf16_f32 v34, v38, v39
	ds_bpermute_b32 v38, v172, v46
	v_cvt_pk_bf16_f32 v35, v40, v41
	v_cvt_pk_bf16_f32 v36, v54, v55
	v_cvt_pk_bf16_f32 v37, v56, v57
	ds_bpermute_b32 v176, v255, v34
	ds_bpermute_b32 v177, v255, v35
	ds_bpermute_b32 v178, v255, v36
	ds_bpermute_b32 v179, v255, v37
	v_add_u32_e32 v174, v68, v180
	s_waitcnt lgkmcnt(0)
	global_store_dwordx4 v174, v[176:179], s[12:13] offset:256
	v_cmp_lt_i32_e64 s[10:11], 0, v1
	s_mov_b64 s[0:1], 0
	v_add_u32_e32 v36, 0x120000, v151
	v_lshrrev_b32_e32 v40, 1, v36
	v_cvt_pk_bf16_f32 v36, v10, v11
	s_waitcnt lgkmcnt(0)
	v_add_f32_e32 v34, v46, v38
	v_cvt_pk_bf16_f32 v37, v12, v13
	v_cvt_pk_bf16_f32 v38, v6, v7
	v_cvt_pk_bf16_f32 v39, v8, v9
	ds_bpermute_b32 v176, v255, v36
	ds_bpermute_b32 v177, v255, v37
	ds_bpermute_b32 v178, v255, v38
	ds_bpermute_b32 v179, v255, v39
	v_add_u32_e32 v174, v40, v180
	s_waitcnt lgkmcnt(0)
	global_store_dwordx4 v174, v[176:179], s[12:13]
	ds_bpermute_b32 v35, v173, v34
	s_mov_b64 s[2:3], 0
	v_mov_b32_e32 v36, v10
	v_mov_b32_e32 v10, v11
	v_mov_b32_e32 v11, v15
	v_mov_b32_e32 v37, v14
	v_pk_mul_f32 v[10:11], v[10:11], v[10:11]
	s_nop 0
	v_pk_fma_f32 v[10:11], v[36:37], v[36:37], v[10:11]
	v_mov_b32_e32 v36, v12
	v_mov_b32_e32 v12, v13
	v_mov_b32_e32 v13, v17
	v_mov_b32_e32 v37, v16
	v_pk_mul_f32 v[12:13], v[12:13], v[12:13]
	s_nop 0
	v_pk_fma_f32 v[12:13], v[36:37], v[36:37], v[12:13]
	s_nop 0
	v_pk_add_f32 v[10:11], v[10:11], v[12:13]
	v_mov_b32_e32 v12, v6
	v_mov_b32_e32 v6, v7
	v_mov_b32_e32 v7, v27
	v_mov_b32_e32 v13, v26
	v_pk_mul_f32 v[6:7], v[6:7], v[6:7]
	s_nop 0
	v_pk_fma_f32 v[6:7], v[12:13], v[12:13], v[6:7]
	s_nop 0
	v_pk_add_f32 v[6:7], v[10:11], v[6:7]
	v_mov_b32_e32 v10, v8
	v_mov_b32_e32 v8, v9
	v_mov_b32_e32 v9, v29
	v_mov_b32_e32 v11, v28
	v_pk_mul_f32 v[8:9], v[8:9], v[8:9]
	s_nop 0
	v_pk_fma_f32 v[8:9], v[10:11], v[10:11], v[8:9]
	s_nop 0
	v_pk_add_f32 v[6:7], v[8:9], v[6:7]
	s_nop 0
	v_add_f32_e32 v10, v6, v7
	v_cvt_pk_bf16_f32 v6, v14, v15
	v_cvt_pk_bf16_f32 v7, v16, v17
	v_cvt_pk_bf16_f32 v8, v26, v27
	v_cvt_pk_bf16_f32 v9, v28, v29
	ds_bpermute_b32 v176, v255, v6
	ds_bpermute_b32 v177, v255, v7
	ds_bpermute_b32 v178, v255, v8
	ds_bpermute_b32 v179, v255, v9
	v_add_u32_e32 v174, v40, v180
	s_waitcnt lgkmcnt(0)
; __device__ __forceinline__ float sum_16_32(float v) { v += __shfl_xor(v, 16); v += __shfl_xor(v, 32); return v; }
; __device__ __forceinline__ unsigned cvt_pk_bf16(float lo, float hi) { unsigned r; asm volatile("v_cvt_pk_bf16_f32 %0, %1, %2" : "=v"(r) : "v"(lo), "v"(hi)); return r; }
;     __device__ __forceinline__ void operator()(const f32x4 (&acc)[2][2][4][2], const Unit& u, int wr, int wc, int fr, int fq) const {
;     ...
;         for (int ai = 0; ai < 2; ++ai) { float sm[4];
; #pragma unroll
;             for (int m = 0; m < 4; ++m) { const unsigned o = ob0 + (unsigned)((ai * HALF + m * 16) * LDC * 4); float s = 0.f;
; #pragma unroll
;                 for (int bj = 0; bj < 2; ++bj) {
;                     const f32x4 o0 = acc[ai][bj][m][0], o1 = acc[ai][bj][m][1];
;                     s += (o0[0] * o0[0] + o0[1] * o0[1]) + (o0[2] * o0[2] + o0[3] * o0[3]) + (o1[0] * o1[0] + o1[1] * o1[1]) + (o1[2] * o1[2] + o1[3] * o1[3]);
;                     if (wf32) { *(f32x4*)(ob + o + bj * HALF * 4) = o0; *(f32x4*)(ob + o + bj * HALF * 4 + 16) = o1; }
;                     else { u32x4 w; w.x = cvt_pk_bf16(o0[0], o0[1]); w.y = cvt_pk_bf16(o0[2], o0[3]); w.z = cvt_pk_bf16(o1[0], o1[1]); w.w = cvt_pk_bf16(o1[2], o1[3]);
;                            *(u32x4*)(xbb + (o >> 1) + bj * HALF * 2) = w; } }
;                 s = sum_16_32(s);
;                 sm[m] = s; }
;             ss[(size_t)(4 * u.pn + wc) * 16384 + u.pm * BM + wr * 64 + ai * HALF + 16 * fq + fr] = fq == 0 ? sm[0] : (fq == 1 ? sm[1] : (fq == 2 ? sm[2] : sm[3])); }
	global_store_dwordx4 v174, v[176:179], s[12:13] offset:256
	ds_bpermute_b32 v11, v172, v10
	v_mul_f32_e32 v15, v21, v21
	v_add_u32_e32 v8, 0x140000, v151
	v_lshrrev_b32_e32 v12, 1, v8
	v_mul_f32_e32 v8, v43, v43
	v_mul_f32_e32 v9, v45, v45
	v_fmac_f32_e32 v8, v42, v42
	v_fmac_f32_e32 v9, v44, v44
	v_add_f32_e32 v8, v8, v9
	v_mul_f32_e32 v9, v59, v59
	v_fmac_f32_e32 v9, v58, v58
	v_add_f32_e32 v8, v8, v9
	v_mul_f32_e32 v9, v61, v61
	v_fmac_f32_e32 v9, v60, v60
	v_add_f32_e32 v13, v9, v8
	v_cvt_pk_bf16_f32 v8, v42, v43
	v_cvt_pk_bf16_f32 v9, v44, v45
	s_waitcnt lgkmcnt(0)
	v_add_f32_e32 v6, v10, v11
	v_cvt_pk_bf16_f32 v10, v58, v59
	v_cvt_pk_bf16_f32 v11, v60, v61
	ds_bpermute_b32 v176, v255, v8
	ds_bpermute_b32 v177, v255, v9
	ds_bpermute_b32 v178, v255, v10
	ds_bpermute_b32 v179, v255, v11
	v_add_u32_e32 v174, v12, v180
	s_waitcnt lgkmcnt(0)
	global_store_dwordx4 v174, v[176:179], s[12:13]
	v_fmac_f32_e32 v15, v20, v20
	ds_bpermute_b32 v7, v173, v6
	v_mul_f32_e32 v8, v51, v51
	v_mul_f32_e32 v9, v53, v53
	v_fmac_f32_e32 v8, v50, v50
	v_fmac_f32_e32 v9, v52, v52
	v_add_f32_e32 v8, v8, v9
	v_mul_f32_e32 v9, v63, v63
	v_fmac_f32_e32 v9, v62, v62
	v_add_f32_e32 v8, v8, v9
	v_mul_f32_e32 v9, v65, v65
	v_fmac_f32_e32 v9, v64, v64
	v_add_f32_e32 v8, v9, v8
	v_add_f32_e32 v13, v13, v8
	ds_bpermute_b32 v14, v172, v13
	v_cvt_pk_bf16_f32 v8, v50, v51
	v_cvt_pk_bf16_f32 v9, v52, v53
	v_cvt_pk_bf16_f32 v10, v62, v63
	v_cvt_pk_bf16_f32 v11, v64, v65
	ds_bpermute_b32 v176, v255, v8
	ds_bpermute_b32 v177, v255, v9
	ds_bpermute_b32 v178, v255, v10
	ds_bpermute_b32 v179, v255, v11
	v_add_u32_e32 v174, v12, v180
	s_waitcnt lgkmcnt(0)
	global_store_dwordx4 v174, v[176:179], s[12:13] offset:256
	s_nop 1
	v_add_u32_e32 v10, 0x160000, v151
	s_waitcnt lgkmcnt(0)
	v_add_f32_e32 v8, v13, v14
	v_lshrrev_b32_e32 v14, 1, v10
	v_mul_f32_e32 v10, v23, v23
	v_mul_f32_e32 v11, v25, v25
	v_mul_f32_e32 v13, v19, v19
	v_fmac_f32_e32 v10, v22, v22
	v_fmac_f32_e32 v11, v24, v24
	v_fmac_f32_e32 v13, v18, v18
	v_add_f32_e32 v10, v10, v11
	v_mul_f32_e32 v11, v3, v3
	v_add_f32_e32 v13, v13, v15
	v_mul_f32_e32 v15, v31, v31
	v_fmac_f32_e32 v11, v2, v2
	v_fmac_f32_e32 v15, v30, v30
	v_add_f32_e32 v10, v10, v11
	v_mul_f32_e32 v11, v5, v5
	v_add_f32_e32 v13, v13, v15
	v_mul_f32_e32 v15, v33, v33
	v_fmac_f32_e32 v11, v4, v4
	v_fmac_f32_e32 v15, v32, v32
	v_add_f32_e32 v12, v11, v10
	v_add_f32_e32 v13, v15, v13
	v_add_f32_e32 v15, v12, v13
	ds_bpermute_b32 v16, v172, v15
	v_cvt_pk_bf16_f32 v10, v22, v23
	v_cvt_pk_bf16_f32 v11, v24, v25
	v_cvt_pk_bf16_f32 v12, v2, v3
	ds_bpermute_b32 v9, v173, v8
	s_waitcnt lgkmcnt(0)
	v_add_f32_e32 v3, v15, v16
	v_cvt_pk_bf16_f32 v13, v4, v5
	ds_bpermute_b32 v4, v173, v3
	ds_bpermute_b32 v176, v255, v10
	ds_bpermute_b32 v177, v255, v11
	ds_bpermute_b32 v178, v255, v12
	ds_bpermute_b32 v179, v255, v13
	v_add_u32_e32 v174, v14, v180
	s_waitcnt lgkmcnt(0)
	global_store_dwordx4 v174, v[176:179], s[12:13]
	s_nop 1
	v_cvt_pk_bf16_f32 v10, v18, v19
	v_cvt_pk_bf16_f32 v11, v20, v21
	v_cvt_pk_bf16_f32 v12, v30, v31
	v_cvt_pk_bf16_f32 v13, v32, v33
	ds_bpermute_b32 v176, v255, v10
	ds_bpermute_b32 v177, v255, v11
	ds_bpermute_b32 v178, v255, v12
	ds_bpermute_b32 v179, v255, v13
	v_add_u32_e32 v174, v14, v180
	s_waitcnt lgkmcnt(0)
	global_store_dwordx4 v174, v[176:179], s[12:13] offset:256
	s_and_saveexec_b64 s[26:27], s[10:11]
	s_xor_b64 s[26:27], exec, s[26:27]
	s_cbranch_execz .LBB0_390
	v_cmp_ne_u32_e64 s[10:11], 1, v1
	v_add_f32_e32 v2, v6, v7
	s_and_b64 s[2:3], s[10:11], exec
	s_andn2_saveexec_b64 s[10:11], s[26:27]
	s_cbranch_execnz .LBB0_391

; __device__ __forceinline__ unsigned cvt_pk_bf16(float lo, float hi) { unsigned r; asm volatile("v_cvt_pk_bf16_f32 %0, %1, %2" : "=v"(r) : "v"(lo), "v"(hi)); return r; }
; #define EPI_FENCE() asm volatile("" ::: "memory")
; __device__ __forceinline__ void load_rs(float (&rs)[8], const RsTable& T, int pm, int lrow0) {
;     const int k = pm == T.pm[0] ? 0 : (pm == T.pm[1] ? 1 : (pm == T.pm[2] ? 2 : 3));
; #pragma unroll
;     for (int i = 0; i < 8; ++i) rs[i] = T.tab[k * 256 + lrow0 + (i >> 2) * HALF + (i & 3) * 16];
;     __device__ __forceinline__ void operator()(const f32x4 (&acc)[2][2][4][2], const Unit& u, int wr, int wc, int fr, int fq) const {
;         const int row0 = u.pm * BM + wr * 64 + fr; const int col0 = u.pn * BM + wc * 32 + 8 * fq;
;         float rs[8]; load_rs(rs, rst, u.pm, wr * 64 + fr);
;         EPI_FENCE();
; #pragma unroll
;         for (int i = 0; i < 8; ++i) { const int ai = i >> 2, m = i & 3; bf16_t* rowp = O + (size_t)(row0 + ai * HALF + m * 16) * ldc + col0;
; #pragma unroll
;             for (int bj = 0; bj < 2; ++bj) { f32x4 v0 = acc[ai][bj][m][0] * rs[i], v1 = acc[ai][bj][m][1] * rs[i];
; #pragma unroll
;                 for (int e = 0; e < 4; ++e) { const float a = fmaxf(v0[e], 0.f), b = fmaxf(v1[e], 0.f); v0[e] = a * a; v1[e] = b * b; }
;                 u32x4 w; w.x = cvt_pk_bf16(v0[0], v0[1]); w.y = cvt_pk_bf16(v0[2], v0[3]); w.z = cvt_pk_bf16(v1[0], v1[1]); w.w = cvt_pk_bf16(v1[2], v1[3]);
;                 *(u32x4*)(rowp + bj * HALF) = w; } }
.LBB0_487:
	v_mbcnt_lo_u32_b32 v182, -1, 0
	v_mbcnt_hi_u32_b32 v182, -1, v182
	v_lshrrev_b32_e32 v180, 2, v182
	v_and_b32_e32 v183, 15, v182
	v_sub_u32_e32 v180, v180, v183
	v_mov_b32_e32 v183, 0x4000
	v_mul_i32_i24_e32 v180, v180, v183
	v_and_b32_e32 v183, 3, v182
	v_lshrrev_b32_e32 v182, 4, v182
	v_sub_u32_e32 v183, v183, v182
	v_lshl_add_u32 v180, v183, 4, v180
	v_ashrrev_i32_e32 v181, 31, v180
	s_cmp_eq_u32 s43, s28
	s_cselect_b32 s0, 0x200, s56
	s_cmp_lg_u32 s43, s27
	s_cselect_b32 s0, s0, 0x100
	s_cmp_lg_u32 s43, s26
	s_cselect_b32 s0, s0, 0
	v_lshl_add_u32 v143, s0, 2, v166
	ds_read2_b32 v[168:169], v143 offset1:16
	ds_read2_b32 v[170:171], v143 offset0:32 offset1:48
	ds_read2_b32 v[148:149], v143 offset0:128 offset1:144
	ds_read2_b32 v[144:145], v143 offset0:160 offset1:176
	v_lshl_add_u32 v142, s43, 8, v1
	s_waitcnt lgkmcnt(0)
	v_pk_mul_f32 v[122:123], v[122:123], v[168:169] op_sel_hi:[1,0]
	v_lshl_add_u32 v146, s42, 8, v153
	v_ashrrev_i32_e32 v143, 31, v142
	v_pk_mul_f32 v[126:127], v[126:127], v[168:169] op_sel_hi:[1,0]
	v_pk_mul_f32 v[124:125], v[124:125], v[168:169] op_sel_hi:[1,0]
	v_max_f32_e32 v122, 0, v122
	v_ashrrev_i32_e32 v147, 31, v146
	v_lshlrev_b64 v[150:151], 14, v[142:143]
	v_pk_mul_f32 v[128:129], v[128:129], v[168:169] op_sel_hi:[1,0]
	v_mul_f32_e32 v143, v122, v122
	v_max_f32_e32 v122, 0, v127
	v_max_f32_e32 v123, 0, v123
	v_max_f32_e32 v124, 0, v124
	v_lshl_add_u64 v[150:151], s[12:13], 0, v[150:151]
	v_lshlrev_b64 v[146:147], 1, v[146:147]
	v_max_f32_e32 v126, 0, v126
	v_mul_f32_e32 v122, v122, v122
	v_mul_f32_e32 v127, v123, v123
	v_max_f32_e32 v123, 0, v128
	v_mul_f32_e32 v128, v124, v124
	v_max_f32_e32 v124, 0, v129
	v_max_f32_e32 v125, 0, v125
	v_pk_mul_f32 v[116:117], v[116:117], v[168:169] op_sel_hi:[1,0]
	v_pk_mul_f32 v[114:115], v[114:115], v[168:169] op_sel_hi:[1,0]
	v_lshl_add_u64 v[150:151], v[150:151], 0, v[146:147]
	v_mul_f32_e32 v126, v126, v126
	v_mul_f32_e32 v123, v123, v123
	v_mul_f32_e32 v124, v124, v124
	v_mul_f32_e32 v125, v125, v125
	v_cvt_pk_bf16_f32 v122, v126, v122
	v_pk_mul_f32 v[120:121], v[120:121], v[168:169] op_sel_hi:[1,0]
	v_pk_mul_f32 v[118:119], v[118:119], v[168:169] op_sel_hi:[1,0]
	v_max_f32_e32 v114, 0, v114
	v_max_f32_e32 v115, 0, v115
	v_max_f32_e32 v116, 0, v116
	v_cvt_pk_bf16_f32 v123, v123, v124
	v_cvt_pk_bf16_f32 v124, v143, v127
	v_cvt_pk_bf16_f32 v125, v128, v125
	ds_bpermute_b32 v176, v255, v122
	ds_bpermute_b32 v177, v255, v123
	ds_bpermute_b32 v178, v255, v124
	ds_bpermute_b32 v179, v255, v125
	v_lshl_add_u64 v[174:175], v[150:151], 0, v[180:181]
	s_waitcnt lgkmcnt(0)
	global_store_dwordx4 v[174:175], v[176:179], off
	v_max_f32_e32 v118, 0, v118
	v_max_f32_e32 v117, 0, v117
	v_mul_f32_e32 v122, v114, v114
	v_max_f32_e32 v114, 0, v119
	v_mul_f32_e32 v119, v115, v115
	v_max_f32_e32 v115, 0, v120
	v_mul_f32_e32 v120, v116, v116
	v_max_f32_e32 v116, 0, v121
	v_mul_f32_e32 v114, v114, v114
	v_mul_f32_e32 v115, v115, v115
	v_mul_f32_e32 v116, v116, v116
	v_mul_f32_e32 v118, v118, v118
	v_mul_f32_e32 v117, v117, v117
	v_cvt_pk_bf16_f32 v114, v118, v114
	v_cvt_pk_bf16_f32 v115, v115, v116
	v_cvt_pk_bf16_f32 v116, v122, v119
	v_cvt_pk_bf16_f32 v117, v120, v117
	ds_bpermute_b32 v176, v255, v114
	ds_bpermute_b32 v177, v255, v115
	ds_bpermute_b32 v178, v255, v116
	ds_bpermute_b32 v179, v255, v117
	v_lshl_add_u64 v[174:175], v[150:151], 0, v[180:181]
	s_waitcnt lgkmcnt(0)
	global_store_dwordx4 v[174:175], v[176:179], off offset:256
	v_pk_mul_f32 v[90:91], v[90:91], v[170:171] op_sel_hi:[1,0]
	v_pk_mul_f32 v[94:95], v[94:95], v[170:171] op_sel_hi:[1,0]
	v_mov_b32_e32 v116, v169
	v_or_b32_e32 v114, 16, v142
	v_pk_mul_f32 v[106:107], v[106:107], v[116:117] op_sel_hi:[1,0]
	v_ashrrev_i32_e32 v115, 31, v114
	v_pk_mul_f32 v[110:111], v[110:111], v[116:117] op_sel_hi:[1,0]
	v_pk_mul_f32 v[108:109], v[108:109], v[116:117] op_sel_hi:[1,0]
	v_max_f32_e32 v106, 0, v106
	v_lshlrev_b64 v[114:115], 14, v[114:115]
	v_pk_mul_f32 v[112:113], v[112:113], v[116:117] op_sel_hi:[1,0]
	v_mul_f32_e32 v117, v106, v106
	v_max_f32_e32 v106, 0, v111
	v_max_f32_e32 v107, 0, v107
	v_max_f32_e32 v108, 0, v108
	v_lshl_add_u64 v[114:115], s[12:13], 0, v[114:115]
	v_max_f32_e32 v110, 0, v110
	v_mul_f32_e32 v106, v106, v106
	v_mul_f32_e32 v111, v107, v107
	v_max_f32_e32 v107, 0, v112
	v_mul_f32_e32 v112, v108, v108
	v_max_f32_e32 v108, 0, v113
	v_max_f32_e32 v109, 0, v109
	v_pk_mul_f32 v[98:99], v[98:99], v[116:117] op_sel_hi:[1,0]
	v_lshl_add_u64 v[114:115], v[114:115], 0, v[146:147]
	v_mul_f32_e32 v110, v110, v110
	v_mul_f32_e32 v107, v107, v107
	v_mul_f32_e32 v108, v108, v108
	v_mul_f32_e32 v109, v109, v109
	v_cvt_pk_bf16_f32 v106, v110, v106
	v_pk_mul_f32 v[102:103], v[102:103], v[116:117] op_sel_hi:[1,0]
	v_pk_mul_f32 v[100:101], v[100:101], v[116:117] op_sel_hi:[1,0]
	v_max_f32_e32 v98, 0, v98
	v_cvt_pk_bf16_f32 v107, v107, v108
	v_cvt_pk_bf16_f32 v108, v117, v111
	v_cvt_pk_bf16_f32 v109, v112, v109
	ds_bpermute_b32 v176, v255, v106
	ds_bpermute_b32 v177, v255, v107
	ds_bpermute_b32 v178, v255, v108
	ds_bpermute_b32 v179, v255, v109
	v_lshl_add_u64 v[174:175], v[114:115], 0, v[180:181]
	s_waitcnt lgkmcnt(0)
	global_store_dwordx4 v[174:175], v[176:179], off
	v_pk_mul_f32 v[104:105], v[104:105], v[116:117] op_sel_hi:[1,0]
	v_max_f32_e32 v99, 0, v99
	v_mul_f32_e32 v106, v98, v98
	v_max_f32_e32 v98, 0, v103
	v_max_f32_e32 v100, 0, v100
	v_max_f32_e32 v102, 0, v102
	v_mul_f32_e32 v98, v98, v98
	v_mul_f32_e32 v103, v99, v99
	v_max_f32_e32 v99, 0, v104
	v_mul_f32_e32 v104, v100, v100
	v_max_f32_e32 v100, 0, v105
	v_max_f32_e32 v101, 0, v101
	v_mul_f32_e32 v102, v102, v102
	v_mul_f32_e32 v99, v99, v99
	v_mul_f32_e32 v100, v100, v100
	v_mul_f32_e32 v101, v101, v101
	v_cvt_pk_bf16_f32 v98, v102, v98
	v_cvt_pk_bf16_f32 v99, v99, v100
	v_cvt_pk_bf16_f32 v100, v106, v103
	v_cvt_pk_bf16_f32 v101, v104, v101
	ds_bpermute_b32 v176, v255, v98
	ds_bpermute_b32 v177, v255, v99
	ds_bpermute_b32 v178, v255, v100
	ds_bpermute_b32 v179, v255, v101
	v_lshl_add_u64 v[174:175], v[114:115], 0, v[180:181]
	s_waitcnt lgkmcnt(0)
; __device__ __forceinline__ unsigned cvt_pk_bf16(float lo, float hi) { unsigned r; asm volatile("v_cvt_pk_bf16_f32 %0, %1, %2" : "=v"(r) : "v"(lo), "v"(hi)); return r; }
;     __device__ __forceinline__ void operator()(const f32x4 (&acc)[2][2][4][2], const Unit& u, int wr, int wc, int fr, int fq) const {
;     ...
;         for (int i = 0; i < 8; ++i) { const int ai = i >> 2, m = i & 3; bf16_t* rowp = O + (size_t)(row0 + ai * HALF + m * 16) * ldc + col0;
; #pragma unroll
;             for (int bj = 0; bj < 2; ++bj) { f32x4 v0 = acc[ai][bj][m][0] * rs[i], v1 = acc[ai][bj][m][1] * rs[i];
; #pragma unroll
;                 for (int e = 0; e < 4; ++e) { const float a = fmaxf(v0[e], 0.f), b = fmaxf(v1[e], 0.f); v0[e] = a * a; v1[e] = b * b; }
;                 u32x4 w; w.x = cvt_pk_bf16(v0[0], v0[1]); w.y = cvt_pk_bf16(v0[2], v0[3]); w.z = cvt_pk_bf16(v1[0], v1[1]); w.w = cvt_pk_bf16(v1[2], v1[3]);
;                 *(u32x4*)(rowp + bj * HALF) = w; } }
	global_store_dwordx4 v[174:175], v[176:179], off offset:256
	v_pk_mul_f32 v[92:93], v[92:93], v[170:171] op_sel_hi:[1,0]
	v_max_f32_e32 v90, 0, v90
	v_or_b32_e32 v98, 32, v142
	v_ashrrev_i32_e32 v99, 31, v98
	v_lshlrev_b64 v[98:99], 14, v[98:99]
	v_pk_mul_f32 v[96:97], v[96:97], v[170:171] op_sel_hi:[1,0]
	v_mul_f32_e32 v100, v90, v90
	v_max_f32_e32 v90, 0, v95
	v_max_f32_e32 v91, 0, v91
	v_max_f32_e32 v92, 0, v92
	v_lshl_add_u64 v[98:99], s[12:13], 0, v[98:99]
	v_max_f32_e32 v94, 0, v94
	v_mul_f32_e32 v90, v90, v90
	v_mul_f32_e32 v95, v91, v91
	v_max_f32_e32 v91, 0, v96
	v_mul_f32_e32 v96, v92, v92
	v_max_f32_e32 v92, 0, v97
	v_max_f32_e32 v93, 0, v93
	v_pk_mul_f32 v[84:85], v[84:85], v[170:171] op_sel_hi:[1,0]
	v_pk_mul_f32 v[82:83], v[82:83], v[170:171] op_sel_hi:[1,0]
	v_lshl_add_u64 v[98:99], v[98:99], 0, v[146:147]
	v_mul_f32_e32 v94, v94, v94
	v_mul_f32_e32 v91, v91, v91
	v_mul_f32_e32 v92, v92, v92
	v_mul_f32_e32 v93, v93, v93
	v_cvt_pk_bf16_f32 v90, v94, v90
	v_pk_mul_f32 v[88:89], v[88:89], v[170:171] op_sel_hi:[1,0]
	v_pk_mul_f32 v[86:87], v[86:87], v[170:171] op_sel_hi:[1,0]
	v_max_f32_e32 v82, 0, v82
	v_max_f32_e32 v83, 0, v83
	v_max_f32_e32 v84, 0, v84
	v_cvt_pk_bf16_f32 v91, v91, v92
	v_cvt_pk_bf16_f32 v92, v100, v95
	v_cvt_pk_bf16_f32 v93, v96, v93
	ds_bpermute_b32 v176, v255, v90
	ds_bpermute_b32 v177, v255, v91
	ds_bpermute_b32 v178, v255, v92
	ds_bpermute_b32 v179, v255, v93
	v_lshl_add_u64 v[174:175], v[98:99], 0, v[180:181]
	s_waitcnt lgkmcnt(0)
	global_store_dwordx4 v[174:175], v[176:179], off
	v_max_f32_e32 v86, 0, v86
	v_max_f32_e32 v85, 0, v85
	v_mul_f32_e32 v90, v82, v82
	v_max_f32_e32 v82, 0, v87
	v_mul_f32_e32 v87, v83, v83
	v_max_f32_e32 v83, 0, v88
	v_mul_f32_e32 v88, v84, v84
	v_max_f32_e32 v84, 0, v89
	v_mul_f32_e32 v82, v82, v82
	v_mul_f32_e32 v83, v83, v83
	v_mul_f32_e32 v84, v84, v84
	v_mul_f32_e32 v86, v86, v86
	v_mul_f32_e32 v85, v85, v85
	v_cvt_pk_bf16_f32 v82, v86, v82
	v_cvt_pk_bf16_f32 v83, v83, v84
	v_cvt_pk_bf16_f32 v84, v90, v87
	v_cvt_pk_bf16_f32 v85, v88, v85
	ds_bpermute_b32 v176, v255, v82
	ds_bpermute_b32 v177, v255, v83
	ds_bpermute_b32 v178, v255, v84
	ds_bpermute_b32 v179, v255, v85
	v_lshl_add_u64 v[174:175], v[98:99], 0, v[180:181]
	s_waitcnt lgkmcnt(0)
	global_store_dwordx4 v[174:175], v[176:179], off offset:256
	v_pk_mul_f32 v[58:59], v[58:59], v[148:149] op_sel_hi:[1,0]
	v_pk_mul_f32 v[62:63], v[62:63], v[148:149] op_sel_hi:[1,0]
	v_mov_b32_e32 v84, v171
	v_or_b32_e32 v82, 48, v142
	v_pk_mul_f32 v[74:75], v[74:75], v[84:85] op_sel_hi:[1,0]
	v_ashrrev_i32_e32 v83, 31, v82
	v_pk_mul_f32 v[78:79], v[78:79], v[84:85] op_sel_hi:[1,0]
	v_pk_mul_f32 v[76:77], v[76:77], v[84:85] op_sel_hi:[1,0]
	v_max_f32_e32 v74, 0, v74
	v_lshlrev_b64 v[82:83], 14, v[82:83]
	v_pk_mul_f32 v[80:81], v[80:81], v[84:85] op_sel_hi:[1,0]
	v_mul_f32_e32 v85, v74, v74
	v_max_f32_e32 v74, 0, v79
	v_max_f32_e32 v75, 0, v75
	v_max_f32_e32 v76, 0, v76
	v_lshl_add_u64 v[82:83], s[12:13], 0, v[82:83]
	v_max_f32_e32 v78, 0, v78
	v_mul_f32_e32 v74, v74, v74
	v_mul_f32_e32 v79, v75, v75
	v_max_f32_e32 v75, 0, v80
	v_mul_f32_e32 v80, v76, v76
	v_max_f32_e32 v76, 0, v81
	v_max_f32_e32 v77, 0, v77
	v_pk_mul_f32 v[68:69], v[68:69], v[84:85] op_sel_hi:[1,0]
	v_pk_mul_f32 v[66:67], v[66:67], v[84:85] op_sel_hi:[1,0]
	v_lshl_add_u64 v[82:83], v[82:83], 0, v[146:147]
	v_mul_f32_e32 v78, v78, v78
	v_mul_f32_e32 v75, v75, v75
	v_mul_f32_e32 v76, v76, v76
	v_mul_f32_e32 v77, v77, v77
	v_cvt_pk_bf16_f32 v74, v78, v74
	v_pk_mul_f32 v[72:73], v[72:73], v[84:85] op_sel_hi:[1,0]
	v_pk_mul_f32 v[70:71], v[70:71], v[84:85] op_sel_hi:[1,0]
	v_max_f32_e32 v66, 0, v66
	v_max_f32_e32 v67, 0, v67
	v_max_f32_e32 v68, 0, v68
	v_cvt_pk_bf16_f32 v75, v75, v76
	v_cvt_pk_bf16_f32 v76, v85, v79
	v_cvt_pk_bf16_f32 v77, v80, v77
	ds_bpermute_b32 v176, v255, v74
	ds_bpermute_b32 v177, v255, v75
	ds_bpermute_b32 v178, v255, v76
	ds_bpermute_b32 v179, v255, v77
	v_lshl_add_u64 v[174:175], v[82:83], 0, v[180:181]
	s_waitcnt lgkmcnt(0)
	global_store_dwordx4 v[174:175], v[176:179], off
	v_max_f32_e32 v70, 0, v70
	v_max_f32_e32 v69, 0, v69
	v_mul_f32_e32 v74, v66, v66
	v_max_f32_e32 v66, 0, v71
	v_mul_f32_e32 v71, v67, v67
	v_max_f32_e32 v67, 0, v72
	v_mul_f32_e32 v72, v68, v68
	v_max_f32_e32 v68, 0, v73
	v_mul_f32_e32 v66, v66, v66
	v_mul_f32_e32 v67, v67, v67
	v_mul_f32_e32 v68, v68, v68
	v_mul_f32_e32 v70, v70, v70
	v_mul_f32_e32 v69, v69, v69
	v_cvt_pk_bf16_f32 v66, v70, v66
	v_cvt_pk_bf16_f32 v67, v67, v68
	v_cvt_pk_bf16_f32 v68, v74, v71
	v_pk_mul_f32 v[60:61], v[60:61], v[148:149] op_sel_hi:[1,0]
	v_max_f32_e32 v58, 0, v58
	v_cvt_pk_bf16_f32 v69, v72, v69
	ds_bpermute_b32 v176, v255, v66
	ds_bpermute_b32 v177, v255, v67
	ds_bpermute_b32 v178, v255, v68
	ds_bpermute_b32 v179, v255, v69
	v_lshl_add_u64 v[174:175], v[82:83], 0, v[180:181]
	s_waitcnt lgkmcnt(0)
	global_store_dwordx4 v[174:175], v[176:179], off offset:256
	s_mov_b64 s[0:1], 0x200000
	v_pk_mul_f32 v[64:65], v[64:65], v[148:149] op_sel_hi:[1,0]
	v_max_f32_e32 v62, 0, v62
	v_mul_f32_e32 v68, v58, v58
	v_max_f32_e32 v58, 0, v63
	v_max_f32_e32 v59, 0, v59
	v_max_f32_e32 v60, 0, v60
	v_lshl_add_u64 v[66:67], v[150:151], 0, s[0:1]
	v_mul_f32_e32 v62, v62, v62
	v_mul_f32_e32 v58, v58, v58
	v_mul_f32_e32 v63, v59, v59
	v_max_f32_e32 v59, 0, v64
	v_mul_f32_e32 v64, v60, v60
	v_max_f32_e32 v60, 0, v65
	s_mov_b32 s0, 0x200000
	v_mul_f32_e32 v59, v59, v59
	v_max_f32_e32 v61, 0, v61
	v_mul_f32_e32 v60, v60, v60
	v_cvt_pk_bf16_f32 v58, v62, v58
	v_add_co_u32_e32 v62, vcc, s0, v150
	v_pk_mul_f32 v[52:53], v[52:53], v[148:149] op_sel_hi:[1,0]
	v_pk_mul_f32 v[50:51], v[50:51], v[148:149] op_sel_hi:[1,0]
	v_mul_f32_e32 v61, v61, v61
	v_cvt_pk_bf16_f32 v59, v59, v60
	v_cvt_pk_bf16_f32 v60, v68, v63
	v_addc_co_u32_e32 v63, vcc, 0, v151, vcc
	v_pk_mul_f32 v[56:57], v[56:57], v[148:149] op_sel_hi:[1,0]
	v_pk_mul_f32 v[54:55], v[54:55], v[148:149] op_sel_hi:[1,0]
	v_max_f32_e32 v50, 0, v50
	v_max_f32_e32 v51, 0, v51
	v_max_f32_e32 v52, 0, v52
	v_cvt_pk_bf16_f32 v61, v64, v61
	ds_bpermute_b32 v176, v255, v58
	ds_bpermute_b32 v177, v255, v59
	ds_bpermute_b32 v178, v255, v60
	ds_bpermute_b32 v179, v255, v61
	v_lshl_add_u64 v[174:175], v[62:63], 0, v[180:181]
	s_waitcnt lgkmcnt(0)
; __device__ __forceinline__ unsigned cvt_pk_bf16(float lo, float hi) { unsigned r; asm volatile("v_cvt_pk_bf16_f32 %0, %1, %2" : "=v"(r) : "v"(lo), "v"(hi)); return r; }
;     __device__ __forceinline__ void operator()(const f32x4 (&acc)[2][2][4][2], const Unit& u, int wr, int wc, int fr, int fq) const {
;     ...
;         for (int i = 0; i < 8; ++i) { const int ai = i >> 2, m = i & 3; bf16_t* rowp = O + (size_t)(row0 + ai * HALF + m * 16) * ldc + col0;
; #pragma unroll
;             for (int bj = 0; bj < 2; ++bj) { f32x4 v0 = acc[ai][bj][m][0] * rs[i], v1 = acc[ai][bj][m][1] * rs[i];
; #pragma unroll
;                 for (int e = 0; e < 4; ++e) { const float a = fmaxf(v0[e], 0.f), b = fmaxf(v1[e], 0.f); v0[e] = a * a; v1[e] = b * b; }
;                 u32x4 w; w.x = cvt_pk_bf16(v0[0], v0[1]); w.y = cvt_pk_bf16(v0[2], v0[3]); w.z = cvt_pk_bf16(v1[0], v1[1]); w.w = cvt_pk_bf16(v1[2], v1[3]);
;                 *(u32x4*)(rowp + bj * HALF) = w; } }
	global_store_dwordx4 v[174:175], v[176:179], off
	v_max_f32_e32 v54, 0, v54
	v_max_f32_e32 v53, 0, v53
	v_mul_f32_e32 v58, v50, v50
	v_max_f32_e32 v50, 0, v55
	v_mul_f32_e32 v55, v51, v51
	v_max_f32_e32 v51, 0, v56
	v_mul_f32_e32 v56, v52, v52
	v_max_f32_e32 v52, 0, v57
	v_mul_f32_e32 v50, v50, v50
	v_mul_f32_e32 v51, v51, v51
	v_mul_f32_e32 v52, v52, v52
	v_mul_f32_e32 v54, v54, v54
	v_mul_f32_e32 v53, v53, v53
	v_cvt_pk_bf16_f32 v50, v54, v50
	v_cvt_pk_bf16_f32 v51, v51, v52
	v_cvt_pk_bf16_f32 v52, v58, v55
	v_cvt_pk_bf16_f32 v53, v56, v53
	ds_bpermute_b32 v176, v255, v50
	ds_bpermute_b32 v177, v255, v51
	ds_bpermute_b32 v178, v255, v52
	ds_bpermute_b32 v179, v255, v53
	v_lshl_add_u64 v[174:175], v[66:67], 0, v[180:181]
	s_waitcnt lgkmcnt(0)
	global_store_dwordx4 v[174:175], v[176:179], off offset:256
	v_pk_mul_f32 v[26:27], v[26:27], v[144:145] op_sel_hi:[1,0]
	v_pk_mul_f32 v[30:31], v[30:31], v[144:145] op_sel_hi:[1,0]
	v_mov_b32_e32 v52, v149
	v_add_u32_e32 v50, 0x90, v142
	v_pk_mul_f32 v[42:43], v[42:43], v[52:53] op_sel_hi:[1,0]
	v_ashrrev_i32_e32 v51, 31, v50
	v_pk_mul_f32 v[46:47], v[46:47], v[52:53] op_sel_hi:[1,0]
	v_pk_mul_f32 v[44:45], v[44:45], v[52:53] op_sel_hi:[1,0]
	v_max_f32_e32 v42, 0, v42
	v_lshlrev_b64 v[50:51], 14, v[50:51]
	v_pk_mul_f32 v[48:49], v[48:49], v[52:53] op_sel_hi:[1,0]
	v_mul_f32_e32 v53, v42, v42
	v_max_f32_e32 v42, 0, v47
	v_max_f32_e32 v43, 0, v43
	v_max_f32_e32 v44, 0, v44
	v_lshl_add_u64 v[50:51], s[12:13], 0, v[50:51]
	v_max_f32_e32 v46, 0, v46
	v_mul_f32_e32 v42, v42, v42
	v_mul_f32_e32 v47, v43, v43
	v_max_f32_e32 v43, 0, v48
	v_mul_f32_e32 v48, v44, v44
	v_max_f32_e32 v44, 0, v49
	v_max_f32_e32 v45, 0, v45
	v_pk_mul_f32 v[34:35], v[34:35], v[52:53] op_sel_hi:[1,0]
	v_lshl_add_u64 v[50:51], v[50:51], 0, v[146:147]
	v_mul_f32_e32 v46, v46, v46
	v_mul_f32_e32 v43, v43, v43
	v_mul_f32_e32 v44, v44, v44
	v_mul_f32_e32 v45, v45, v45
	v_cvt_pk_bf16_f32 v42, v46, v42
	v_pk_mul_f32 v[38:39], v[38:39], v[52:53] op_sel_hi:[1,0]
	v_pk_mul_f32 v[36:37], v[36:37], v[52:53] op_sel_hi:[1,0]
	v_max_f32_e32 v34, 0, v34
	v_cvt_pk_bf16_f32 v43, v43, v44
	v_cvt_pk_bf16_f32 v44, v53, v47
	v_cvt_pk_bf16_f32 v45, v48, v45
	ds_bpermute_b32 v176, v255, v42
	ds_bpermute_b32 v177, v255, v43
	ds_bpermute_b32 v178, v255, v44
	ds_bpermute_b32 v179, v255, v45
	v_lshl_add_u64 v[174:175], v[50:51], 0, v[180:181]
	s_waitcnt lgkmcnt(0)
	global_store_dwordx4 v[174:175], v[176:179], off
	v_pk_mul_f32 v[40:41], v[40:41], v[52:53] op_sel_hi:[1,0]
	v_max_f32_e32 v35, 0, v35
	v_mul_f32_e32 v42, v34, v34
	v_max_f32_e32 v34, 0, v39
	v_max_f32_e32 v36, 0, v36
	v_max_f32_e32 v38, 0, v38
	v_mul_f32_e32 v34, v34, v34
	v_mul_f32_e32 v39, v35, v35
	v_max_f32_e32 v35, 0, v40
	v_mul_f32_e32 v40, v36, v36
	v_max_f32_e32 v36, 0, v41
	v_max_f32_e32 v37, 0, v37
	v_mul_f32_e32 v38, v38, v38
	v_mul_f32_e32 v35, v35, v35
	v_mul_f32_e32 v36, v36, v36
	v_mul_f32_e32 v37, v37, v37
	v_cvt_pk_bf16_f32 v34, v38, v34
	v_cvt_pk_bf16_f32 v35, v35, v36
	v_cvt_pk_bf16_f32 v36, v42, v39
	v_cvt_pk_bf16_f32 v37, v40, v37
	ds_bpermute_b32 v176, v255, v34
	ds_bpermute_b32 v177, v255, v35
	ds_bpermute_b32 v178, v255, v36
	ds_bpermute_b32 v179, v255, v37
	v_lshl_add_u64 v[174:175], v[50:51], 0, v[180:181]
	s_waitcnt lgkmcnt(0)
	global_store_dwordx4 v[174:175], v[176:179], off offset:256
	v_pk_mul_f32 v[28:29], v[28:29], v[144:145] op_sel_hi:[1,0]
	v_max_f32_e32 v26, 0, v26
	v_add_u32_e32 v34, 0xa0, v142
	v_ashrrev_i32_e32 v35, 31, v34
	v_lshlrev_b64 v[34:35], 14, v[34:35]
	v_pk_mul_f32 v[32:33], v[32:33], v[144:145] op_sel_hi:[1,0]
	v_mul_f32_e32 v36, v26, v26
	v_max_f32_e32 v26, 0, v31
	v_max_f32_e32 v27, 0, v27
	v_max_f32_e32 v28, 0, v28
	v_lshl_add_u64 v[34:35], s[12:13], 0, v[34:35]
	v_max_f32_e32 v30, 0, v30
	v_mul_f32_e32 v26, v26, v26
	v_mul_f32_e32 v31, v27, v27
	v_max_f32_e32 v27, 0, v32
	v_mul_f32_e32 v32, v28, v28
	v_max_f32_e32 v28, 0, v33
	v_max_f32_e32 v29, 0, v29
	v_pk_mul_f32 v[20:21], v[20:21], v[144:145] op_sel_hi:[1,0]
	v_pk_mul_f32 v[18:19], v[18:19], v[144:145] op_sel_hi:[1,0]
	v_lshl_add_u64 v[34:35], v[34:35], 0, v[146:147]
	v_mul_f32_e32 v30, v30, v30
	v_mul_f32_e32 v27, v27, v27
	v_mul_f32_e32 v28, v28, v28
	v_mul_f32_e32 v29, v29, v29
	v_cvt_pk_bf16_f32 v26, v30, v26
	v_pk_mul_f32 v[24:25], v[24:25], v[144:145] op_sel_hi:[1,0]
	v_pk_mul_f32 v[22:23], v[22:23], v[144:145] op_sel_hi:[1,0]
	v_max_f32_e32 v18, 0, v18
	v_max_f32_e32 v19, 0, v19
	v_max_f32_e32 v20, 0, v20
	v_cvt_pk_bf16_f32 v27, v27, v28
	v_cvt_pk_bf16_f32 v28, v36, v31
	v_cvt_pk_bf16_f32 v29, v32, v29
	ds_bpermute_b32 v176, v255, v26
	ds_bpermute_b32 v177, v255, v27
	ds_bpermute_b32 v178, v255, v28
	ds_bpermute_b32 v179, v255, v29
	v_lshl_add_u64 v[174:175], v[34:35], 0, v[180:181]
	s_waitcnt lgkmcnt(0)
; __device__ __forceinline__ unsigned cvt_pk_bf16(float lo, float hi) { unsigned r; asm volatile("v_cvt_pk_bf16_f32 %0, %1, %2" : "=v"(r) : "v"(lo), "v"(hi)); return r; }
;     __device__ __forceinline__ void operator()(const f32x4 (&acc)[2][2][4][2], const Unit& u, int wr, int wc, int fr, int fq) const {
;     ...
;         for (int i = 0; i < 8; ++i) { const int ai = i >> 2, m = i & 3; bf16_t* rowp = O + (size_t)(row0 + ai * HALF + m * 16) * ldc + col0;
; #pragma unroll
;             for (int bj = 0; bj < 2; ++bj) { f32x4 v0 = acc[ai][bj][m][0] * rs[i], v1 = acc[ai][bj][m][1] * rs[i];
; #pragma unroll
;                 for (int e = 0; e < 4; ++e) { const float a = fmaxf(v0[e], 0.f), b = fmaxf(v1[e], 0.f); v0[e] = a * a; v1[e] = b * b; }
;                 u32x4 w; w.x = cvt_pk_bf16(v0[0], v0[1]); w.y = cvt_pk_bf16(v0[2], v0[3]); w.z = cvt_pk_bf16(v1[0], v1[1]); w.w = cvt_pk_bf16(v1[2], v1[3]);
;                 *(u32x4*)(rowp + bj * HALF) = w; } }
	global_store_dwordx4 v[174:175], v[176:179], off
	v_max_f32_e32 v22, 0, v22
	v_max_f32_e32 v21, 0, v21
	v_mul_f32_e32 v26, v18, v18
	v_max_f32_e32 v18, 0, v23
	v_mul_f32_e32 v23, v19, v19
	v_max_f32_e32 v19, 0, v24
	v_mul_f32_e32 v24, v20, v20
	v_max_f32_e32 v20, 0, v25
	v_mul_f32_e32 v18, v18, v18
	v_mul_f32_e32 v19, v19, v19
	v_mul_f32_e32 v20, v20, v20
	v_mul_f32_e32 v22, v22, v22
	v_mul_f32_e32 v21, v21, v21
	v_cvt_pk_bf16_f32 v18, v22, v18
	v_cvt_pk_bf16_f32 v19, v19, v20
	v_cvt_pk_bf16_f32 v20, v26, v23
	v_cvt_pk_bf16_f32 v21, v24, v21
	ds_bpermute_b32 v176, v255, v18
	ds_bpermute_b32 v177, v255, v19
	ds_bpermute_b32 v178, v255, v20
	ds_bpermute_b32 v179, v255, v21
	v_lshl_add_u64 v[174:175], v[34:35], 0, v[180:181]
	s_waitcnt lgkmcnt(0)
	global_store_dwordx4 v[174:175], v[176:179], off offset:256
	s_andn2_b64 vcc, exec, s[6:7]
	s_mov_b64 s[0:1], -1
	v_mov_b32_e32 v20, v145
	v_add_u32_e32 v18, 0xb0, v142
	v_pk_mul_f32 v[10:11], v[10:11], v[20:21] op_sel_hi:[1,0]
	v_ashrrev_i32_e32 v19, 31, v18
	v_pk_mul_f32 v[14:15], v[14:15], v[20:21] op_sel_hi:[1,0]
	v_pk_mul_f32 v[12:13], v[12:13], v[20:21] op_sel_hi:[1,0]
	v_max_f32_e32 v10, 0, v10
	v_lshlrev_b64 v[18:19], 14, v[18:19]
	v_pk_mul_f32 v[16:17], v[16:17], v[20:21] op_sel_hi:[1,0]
	v_mul_f32_e32 v21, v10, v10
	v_max_f32_e32 v10, 0, v15
	v_max_f32_e32 v11, 0, v11
	v_max_f32_e32 v12, 0, v12
	v_lshl_add_u64 v[18:19], s[12:13], 0, v[18:19]
	v_max_f32_e32 v14, 0, v14
	v_mul_f32_e32 v10, v10, v10
	v_mul_f32_e32 v15, v11, v11
	v_max_f32_e32 v11, 0, v16
	v_mul_f32_e32 v16, v12, v12
	v_max_f32_e32 v12, 0, v17
	v_max_f32_e32 v13, 0, v13
	v_pk_mul_f32 v[4:5], v[4:5], v[20:21] op_sel_hi:[1,0]
	v_pk_mul_f32 v[2:3], v[2:3], v[20:21] op_sel_hi:[1,0]
	v_lshl_add_u64 v[18:19], v[18:19], 0, v[146:147]
	v_mul_f32_e32 v14, v14, v14
	v_mul_f32_e32 v11, v11, v11
	v_mul_f32_e32 v12, v12, v12
	v_mul_f32_e32 v13, v13, v13
	v_cvt_pk_bf16_f32 v10, v14, v10
	v_pk_mul_f32 v[8:9], v[8:9], v[20:21] op_sel_hi:[1,0]
	v_pk_mul_f32 v[6:7], v[6:7], v[20:21] op_sel_hi:[1,0]
	v_max_f32_e32 v2, 0, v2
	v_max_f32_e32 v3, 0, v3
	v_max_f32_e32 v4, 0, v4
	v_cvt_pk_bf16_f32 v11, v11, v12
	v_cvt_pk_bf16_f32 v12, v21, v15
	v_cvt_pk_bf16_f32 v13, v16, v13
	ds_bpermute_b32 v176, v255, v10
	ds_bpermute_b32 v177, v255, v11
	ds_bpermute_b32 v178, v255, v12
	ds_bpermute_b32 v179, v255, v13
	v_lshl_add_u64 v[174:175], v[18:19], 0, v[180:181]
	s_waitcnt lgkmcnt(0)
	global_store_dwordx4 v[174:175], v[176:179], off
	v_max_f32_e32 v5, 0, v5
	v_max_f32_e32 v6, 0, v6
	v_mul_f32_e32 v10, v2, v2
	v_max_f32_e32 v2, 0, v7
	v_mul_f32_e32 v7, v3, v3
	v_max_f32_e32 v3, 0, v8
	v_mul_f32_e32 v8, v4, v4
	v_max_f32_e32 v4, 0, v9
	v_mul_f32_e32 v2, v2, v2
	v_mul_f32_e32 v3, v3, v3
	v_mul_f32_e32 v4, v4, v4
	v_mul_f32_e32 v5, v5, v5
	v_readlane_b32 s50, v252, 33
	v_mul_f32_e32 v6, v6, v6
	v_cvt_pk_bf16_f32 v2, v6, v2
	v_cvt_pk_bf16_f32 v3, v3, v4
	v_cvt_pk_bf16_f32 v4, v10, v7
	v_cvt_pk_bf16_f32 v5, v8, v5
	ds_bpermute_b32 v176, v255, v2
	ds_bpermute_b32 v177, v255, v3
	ds_bpermute_b32 v178, v255, v4
	ds_bpermute_b32 v179, v255, v5
	v_lshl_add_u64 v[174:175], v[18:19], 0, v[180:181]
	s_waitcnt lgkmcnt(0)
	global_store_dwordx4 v[174:175], v[176:179], off offset:256
	v_readlane_b32 s51, v252, 34
	s_cbranch_vccnz .LBB0_476
	s_andn2_b64 vcc, exec, s[10:11]
	s_cbranch_vccnz .LBB0_475
	s_barrier
	s_branch .LBB0_475

; __device__ __forceinline__ float sum_16_32(float v) { v += __shfl_xor(v, 16); v += __shfl_xor(v, 32); return v; }
; __device__ __forceinline__ unsigned cvt_pk_bf16(float lo, float hi) { unsigned r; asm volatile("v_cvt_pk_bf16_f32 %0, %1, %2" : "=v"(r) : "v"(lo), "v"(hi)); return r; }
;     __device__ __forceinline__ void operator()(const f32x4 (&acc)[2][2][4][2], const Unit& u, int wr, int wc, int fr, int fq) const {
;         const int row0 = u.pm * BM + wr * 64 + fr; const int col0 = u.pn * BM + wc * 32 + 8 * fq;
;         const unsigned ob0 = ((unsigned)row0 * LDC + (unsigned)col0) * 4u;
;         char* ob = (char*)out; char* xbb = (char*)xb;
; #pragma unroll
;         for (int ai = 0; ai < 2; ++ai) { float sm[4];
; #pragma unroll
;             for (int m = 0; m < 4; ++m) { const unsigned o = ob0 + (unsigned)((ai * HALF + m * 16) * LDC * 4); float s = 0.f;
; #pragma unroll
;                 for (int bj = 0; bj < 2; ++bj) {
;                     const f32x4 o0 = acc[ai][bj][m][0], o1 = acc[ai][bj][m][1];
;                     s += (o0[0] * o0[0] + o0[1] * o0[1]) + (o0[2] * o0[2] + o0[3] * o0[3]) + (o1[0] * o1[0] + o1[1] * o1[1]) + (o1[2] * o1[2] + o1[3] * o1[3]);
;                     if (wf32) { *(f32x4*)(ob + o + bj * HALF * 4) = o0; *(f32x4*)(ob + o + bj * HALF * 4 + 16) = o1; }
;                     else { u32x4 w; w.x = cvt_pk_bf16(o0[0], o0[1]); w.y = cvt_pk_bf16(o0[2], o0[3]); w.z = cvt_pk_bf16(o1[0], o1[1]); w.w = cvt_pk_bf16(o1[2], o1[3]);
;                            *(u32x4*)(xbb + (o >> 1) + bj * HALF * 2) = w; } }
;                 s = sum_16_32(s);
;                 sm[m] = s; }
.LBB0_548:
	v_mbcnt_lo_u32_b32 v182, -1, 0
	v_mbcnt_hi_u32_b32 v182, -1, v182
	v_lshrrev_b32_e32 v180, 2, v182
	v_and_b32_e32 v183, 15, v182
	v_sub_u32_e32 v180, v180, v183
	v_mov_b32_e32 v183, 0x1000
	v_mul_i32_i24_e32 v180, v180, v183
	v_and_b32_e32 v183, 3, v182
	v_lshrrev_b32_e32 v182, 4, v182
	v_sub_u32_e32 v183, v183, v182
	v_lshl_add_u32 v180, v183, 4, v180
	v_ashrrev_i32_e32 v181, 31, v180
	v_cvt_pk_bf16_f32 v166, v118, v119
	v_mov_b32_e32 v152, v118
	v_mov_b32_e32 v118, v119
	v_mov_b32_e32 v119, v123
	v_mov_b32_e32 v153, v122
	v_pk_mul_f32 v[118:119], v[118:119], v[118:119]
	v_cvt_pk_bf16_f32 v167, v120, v121
	v_cvt_pk_bf16_f32 v168, v114, v115
	v_cvt_pk_bf16_f32 v169, v116, v117
	s_lshl_b32 s0, s45, 8
	v_pk_fma_f32 v[118:119], v[152:153], v[152:153], v[118:119]
	v_mov_b32_e32 v152, v120
	v_mov_b32_e32 v120, v121
	v_mov_b32_e32 v121, v125
	v_mov_b32_e32 v153, v124
	v_pk_mul_f32 v[120:121], v[120:121], v[120:121]
	s_lshl_b32 s1, s33, 10
	v_pk_fma_f32 v[120:121], v[152:153], v[152:153], v[120:121]
	v_add_lshl_u32 v145, s0, v146, 13
	v_pk_add_f32 v[118:119], v[118:119], v[120:121]
	v_mov_b32_e32 v120, v114
	v_mov_b32_e32 v114, v115
	v_mov_b32_e32 v115, v127
	v_mov_b32_e32 v121, v126
	v_pk_mul_f32 v[114:115], v[114:115], v[114:115]
	v_add3_u32 v151, v148, s1, v145
	v_pk_fma_f32 v[114:115], v[120:121], v[120:121], v[114:115]
	v_lshrrev_b32_e32 v145, 1, v151
	v_pk_add_f32 v[114:115], v[118:119], v[114:115]
	v_mov_b32_e32 v118, v116
	v_mov_b32_e32 v116, v117
	v_mov_b32_e32 v117, v129
	v_mov_b32_e32 v119, v128
	v_pk_mul_f32 v[116:117], v[116:117], v[116:117]
	ds_bpermute_b32 v176, v255, v166
	ds_bpermute_b32 v177, v255, v167
	ds_bpermute_b32 v178, v255, v168
	ds_bpermute_b32 v179, v255, v169
	v_add_u32_e32 v174, v145, v180
	s_waitcnt lgkmcnt(0)
	global_store_dwordx4 v174, v[176:179], s[10:11]
	v_pk_fma_f32 v[116:117], v[118:119], v[118:119], v[116:117]
	v_cmp_lt_i32_e32 vcc, 0, v1
	v_pk_add_f32 v[114:115], v[116:117], v[114:115]
	s_mov_b64 s[2:3], 0
	v_add_f32_e32 v118, v114, v115
	ds_bpermute_b32 v119, v172, v118
	v_cvt_pk_bf16_f32 v114, v122, v123
	v_cvt_pk_bf16_f32 v115, v124, v125
	v_cvt_pk_bf16_f32 v116, v126, v127
	v_cvt_pk_bf16_f32 v117, v128, v129
	ds_bpermute_b32 v176, v255, v114
	ds_bpermute_b32 v177, v255, v115
	ds_bpermute_b32 v178, v255, v116
	ds_bpermute_b32 v179, v255, v117
	v_add_u32_e32 v174, v145, v180
	s_waitcnt lgkmcnt(0)
	global_store_dwordx4 v174, v[176:179], s[10:11] offset:256
	s_nop 1
	v_add_u32_e32 v116, 0x20000, v151
	v_mul_f32_e32 v117, v99, v99
	s_waitcnt lgkmcnt(0)
	v_add_f32_e32 v114, v118, v119
	v_lshrrev_b32_e32 v116, 1, v116
	v_fmac_f32_e32 v117, v98, v98
	v_mul_f32_e32 v118, v101, v101
	v_cvt_pk_bf16_f32 v98, v98, v99
	v_cvt_pk_bf16_f32 v99, v100, v101
	v_fmac_f32_e32 v118, v100, v100
	v_cvt_pk_bf16_f32 v100, v106, v107
	v_cvt_pk_bf16_f32 v101, v108, v109
	ds_bpermute_b32 v176, v255, v98
	ds_bpermute_b32 v177, v255, v99
	ds_bpermute_b32 v178, v255, v100
	ds_bpermute_b32 v179, v255, v101
	v_add_u32_e32 v174, v116, v180
	s_waitcnt lgkmcnt(0)
	global_store_dwordx4 v174, v[176:179], s[10:11]
	v_add_f32_e32 v117, v117, v118
	v_mul_f32_e32 v118, v107, v107
	v_mul_f32_e32 v98, v103, v103
	v_mul_f32_e32 v99, v105, v105
	v_fmac_f32_e32 v98, v102, v102
	v_fmac_f32_e32 v99, v104, v104
	v_add_f32_e32 v98, v98, v99
	v_mul_f32_e32 v99, v111, v111
	v_fmac_f32_e32 v118, v106, v106
	v_fmac_f32_e32 v99, v110, v110
	v_add_f32_e32 v117, v117, v118
	v_mul_f32_e32 v118, v109, v109
	v_add_f32_e32 v98, v98, v99
	v_mul_f32_e32 v99, v113, v113
	v_fmac_f32_e32 v118, v108, v108
	v_fmac_f32_e32 v99, v112, v112
	v_add_f32_e32 v117, v118, v117
	v_add_f32_e32 v98, v99, v98
	v_add_f32_e32 v106, v117, v98
	v_cvt_pk_bf16_f32 v98, v102, v103
	ds_bpermute_b32 v102, v172, v106
	v_cvt_pk_bf16_f32 v99, v104, v105
	v_cvt_pk_bf16_f32 v100, v110, v111
	v_cvt_pk_bf16_f32 v101, v112, v113
	ds_bpermute_b32 v176, v255, v98
	ds_bpermute_b32 v177, v255, v99
	ds_bpermute_b32 v178, v255, v100
	ds_bpermute_b32 v179, v255, v101
	v_add_u32_e32 v174, v116, v180
	s_waitcnt lgkmcnt(0)
; __device__ __forceinline__ float sum_16_32(float v) { v += __shfl_xor(v, 16); v += __shfl_xor(v, 32); return v; }
; __device__ __forceinline__ unsigned cvt_pk_bf16(float lo, float hi) { unsigned r; asm volatile("v_cvt_pk_bf16_f32 %0, %1, %2" : "=v"(r) : "v"(lo), "v"(hi)); return r; }
;     __device__ __forceinline__ void operator()(const f32x4 (&acc)[2][2][4][2], const Unit& u, int wr, int wc, int fr, int fq) const {
;     ...
;             for (int m = 0; m < 4; ++m) { const unsigned o = ob0 + (unsigned)((ai * HALF + m * 16) * LDC * 4); float s = 0.f;
; #pragma unroll
;                 for (int bj = 0; bj < 2; ++bj) {
;                     const f32x4 o0 = acc[ai][bj][m][0], o1 = acc[ai][bj][m][1];
;                     s += (o0[0] * o0[0] + o0[1] * o0[1]) + (o0[2] * o0[2] + o0[3] * o0[3]) + (o1[0] * o1[0] + o1[1] * o1[1]) + (o1[2] * o1[2] + o1[3] * o1[3]);
;                     if (wf32) { *(f32x4*)(ob + o + bj * HALF * 4) = o0; *(f32x4*)(ob + o + bj * HALF * 4 + 16) = o1; }
;                     else { u32x4 w; w.x = cvt_pk_bf16(o0[0], o0[1]); w.y = cvt_pk_bf16(o0[2], o0[3]); w.z = cvt_pk_bf16(o1[0], o1[1]); w.w = cvt_pk_bf16(o1[2], o1[3]);
;                            *(u32x4*)(xbb + (o >> 1) + bj * HALF * 2) = w; } }
;                 s = sum_16_32(s);
;                 sm[m] = s; }
;             ss[(size_t)(4 * u.pn + wc) * 16384 + u.pm * BM + wr * 64 + ai * HALF + 16 * fq + fr] = fq == 0 ? sm[0] : (fq == 1 ? sm[1] : (fq == 2 ? sm[2] : sm[3])); }
	global_store_dwordx4 v174, v[176:179], s[10:11] offset:256
	ds_bpermute_b32 v115, v173, v114
	s_nop 0
	v_add_u32_e32 v100, 0x40000, v151
	v_mul_f32_e32 v101, v83, v83
	s_waitcnt lgkmcnt(0)
	v_add_f32_e32 v98, v106, v102
	v_lshrrev_b32_e32 v100, 1, v100
	v_fmac_f32_e32 v101, v82, v82
	v_mul_f32_e32 v102, v85, v85
	v_cvt_pk_bf16_f32 v82, v82, v83
	v_cvt_pk_bf16_f32 v83, v84, v85
	v_fmac_f32_e32 v102, v84, v84
	v_cvt_pk_bf16_f32 v84, v90, v91
	v_cvt_pk_bf16_f32 v85, v92, v93
	ds_bpermute_b32 v176, v255, v82
	ds_bpermute_b32 v177, v255, v83
	ds_bpermute_b32 v178, v255, v84
	ds_bpermute_b32 v179, v255, v85
	v_add_u32_e32 v174, v100, v180
	s_waitcnt lgkmcnt(0)
	global_store_dwordx4 v174, v[176:179], s[10:11]
	v_add_f32_e32 v101, v101, v102
	v_mul_f32_e32 v102, v91, v91
	v_mul_f32_e32 v82, v87, v87
	v_mul_f32_e32 v83, v89, v89
	v_fmac_f32_e32 v82, v86, v86
	v_fmac_f32_e32 v83, v88, v88
	v_add_f32_e32 v82, v82, v83
	v_mul_f32_e32 v83, v95, v95
	v_fmac_f32_e32 v102, v90, v90
	v_fmac_f32_e32 v83, v94, v94
	v_add_f32_e32 v101, v101, v102
	v_mul_f32_e32 v102, v93, v93
	v_add_f32_e32 v82, v82, v83
	v_mul_f32_e32 v83, v97, v97
	v_fmac_f32_e32 v102, v92, v92
	v_fmac_f32_e32 v83, v96, v96
	v_add_f32_e32 v101, v102, v101
	v_add_f32_e32 v82, v83, v82
	v_add_f32_e32 v90, v101, v82
	v_cvt_pk_bf16_f32 v82, v86, v87
	ds_bpermute_b32 v86, v172, v90
	v_cvt_pk_bf16_f32 v83, v88, v89
	v_cvt_pk_bf16_f32 v84, v94, v95
	v_cvt_pk_bf16_f32 v85, v96, v97
	ds_bpermute_b32 v176, v255, v82
	ds_bpermute_b32 v177, v255, v83
	ds_bpermute_b32 v178, v255, v84
	ds_bpermute_b32 v179, v255, v85
	v_add_u32_e32 v174, v100, v180
	s_waitcnt lgkmcnt(0)
	global_store_dwordx4 v174, v[176:179], s[10:11] offset:256
	ds_bpermute_b32 v99, v173, v98
	s_waitcnt lgkmcnt(0)
	v_add_f32_e32 v82, v90, v86
	v_mul_f32_e32 v85, v75, v75
	v_mul_f32_e32 v86, v77, v77
	v_fmac_f32_e32 v85, v74, v74
	v_fmac_f32_e32 v86, v76, v76
	v_cvt_pk_bf16_f32 v74, v74, v75
	v_cvt_pk_bf16_f32 v75, v76, v77
	v_mul_f32_e32 v76, v71, v71
	v_mul_f32_e32 v77, v73, v73
	v_fmac_f32_e32 v76, v70, v70
	v_fmac_f32_e32 v77, v72, v72
	v_add_f32_e32 v85, v85, v86
	v_mul_f32_e32 v86, v67, v67
	v_add_f32_e32 v76, v76, v77
	v_mul_f32_e32 v77, v79, v79
	v_fmac_f32_e32 v86, v66, v66
	v_fmac_f32_e32 v77, v78, v78
	v_add_f32_e32 v85, v85, v86
	v_mul_f32_e32 v86, v69, v69
	v_add_f32_e32 v76, v76, v77
	v_mul_f32_e32 v77, v81, v81
	v_fmac_f32_e32 v86, v68, v68
	v_fmac_f32_e32 v77, v80, v80
	v_add_f32_e32 v85, v86, v85
	v_add_f32_e32 v76, v77, v76
	v_add_f32_e32 v85, v85, v76
	ds_bpermute_b32 v86, v172, v85
	v_cvt_pk_bf16_f32 v76, v66, v67
	ds_bpermute_b32 v83, v173, v82
	v_add_u32_e32 v84, 0x60000, v151
	v_lshrrev_b32_e32 v84, 1, v84
	s_waitcnt lgkmcnt(0)
	v_add_f32_e32 v66, v85, v86
	ds_bpermute_b32 v67, v173, v66
	v_cvt_pk_bf16_f32 v77, v68, v69
	ds_bpermute_b32 v176, v255, v74
	ds_bpermute_b32 v177, v255, v75
	ds_bpermute_b32 v178, v255, v76
	ds_bpermute_b32 v179, v255, v77
	v_add_u32_e32 v174, v84, v180
	s_waitcnt lgkmcnt(0)
	global_store_dwordx4 v174, v[176:179], s[10:11]
	v_cvt_pk_bf16_f32 v68, v70, v71
	v_cvt_pk_bf16_f32 v69, v72, v73
	v_cvt_pk_bf16_f32 v70, v78, v79
	v_cvt_pk_bf16_f32 v71, v80, v81
	ds_bpermute_b32 v176, v255, v68
	ds_bpermute_b32 v177, v255, v69
	ds_bpermute_b32 v178, v255, v70
	ds_bpermute_b32 v179, v255, v71
	v_add_u32_e32 v174, v84, v180
	s_waitcnt lgkmcnt(0)
	global_store_dwordx4 v174, v[176:179], s[10:11] offset:256
	s_and_saveexec_b64 s[8:9], vcc
	s_xor_b64 s[8:9], exec, s[8:9]
	v_readlane_b32 s50, v252, 33
	v_readlane_b32 s51, v252, 34
	s_cbranch_execz .LBB0_558
	v_cmp_eq_u32_e32 vcc, 1, v1
	s_mov_b64 s[2:3], -1
	s_and_saveexec_b64 s[26:27], vcc
	v_add_f32_e32 v68, v98, v99
	s_xor_b64 s[2:3], exec, -1
	s_or_b64 exec, exec, s[26:27]
	s_and_b64 s[2:3], s[2:3], exec
	s_or_saveexec_b64 s[8:9], s[8:9]
	v_cmp_ne_u32_e32 vcc, 0, v1
	s_xor_b64 exec, exec, s[8:9]
	s_cbranch_execnz .LBB0_559

; __device__ __forceinline__ unsigned cvt_pk_bf16(float lo, float hi) { unsigned r; asm volatile("v_cvt_pk_bf16_f32 %0, %1, %2" : "=v"(r) : "v"(lo), "v"(hi)); return r; }
;     __device__ __forceinline__ void operator()(const f32x4 (&acc)[2][2][4][2], const Unit& u, int wr, int wc, int fr, int fq) const {
;     ...
;         for (int ai = 0; ai < 2; ++ai) { float sm[4];
; #pragma unroll
;             for (int m = 0; m < 4; ++m) { const unsigned o = ob0 + (unsigned)((ai * HALF + m * 16) * LDC * 4); float s = 0.f;
; #pragma unroll
;                 for (int bj = 0; bj < 2; ++bj) {
;                     const f32x4 o0 = acc[ai][bj][m][0], o1 = acc[ai][bj][m][1];
;                     s += (o0[0] * o0[0] + o0[1] * o0[1]) + (o0[2] * o0[2] + o0[3] * o0[3]) + (o1[0] * o1[0] + o1[1] * o1[1]) + (o1[2] * o1[2] + o1[3] * o1[3]);
;                     if (wf32) { *(f32x4*)(ob + o + bj * HALF * 4) = o0; *(f32x4*)(ob + o + bj * HALF * 4 + 16) = o1; }
;                     else { u32x4 w; w.x = cvt_pk_bf16(o0[0], o0[1]); w.y = cvt_pk_bf16(o0[2], o0[3]); w.z = cvt_pk_bf16(o1[0], o1[1]); w.w = cvt_pk_bf16(o1[2], o1[3]);
;                            *(u32x4*)(xbb + (o >> 1) + bj * HALF * 2) = w; } }
;     ...
;             ss[(size_t)(4 * u.pn + wc) * 16384 + u.pm * BM + wr * 64 + ai * HALF + 16 * fq + fr] = fq == 0 ? sm[0] : (fq == 1 ? sm[1] : (fq == 2 ? sm[2] : sm[3])); }
.LBB0_554:
	s_or_b64 exec, exec, s[8:9]
	s_lshl_b32 s1, s33, 2
	s_or_b32 s2, s1, s34
	s_ashr_i32 s3, s2, 31
	s_ashr_i32 s1, s0, 31
	s_lshl_b64 s[2:3], s[2:3], 16
	s_add_u32 s2, s40, s2
	s_addc_u32 s3, s41, s3
	s_lshl_b64 s[0:1], s[0:1], 2
	s_add_u32 s0, s2, s0
	s_addc_u32 s1, s3, s1
	s_add_u32 s0, s0, s16
	s_addc_u32 s1, s1, s17
	s_waitcnt lgkmcnt(0)
	v_lshl_add_u64 v[66:67], v[138:139], 2, s[0:1]
	v_mov_b32_e32 v145, v0
	v_lshl_add_u64 v[66:67], v[66:67], 0, v[144:145]
	global_store_dword v[66:67], v68, off
	v_add_u32_e32 v68, 0x100000, v151
	v_mul_f32_e32 v69, v35, v35
	v_lshrrev_b32_e32 v68, 1, v68
	v_fmac_f32_e32 v69, v34, v34
	v_mul_f32_e32 v70, v37, v37
	v_cvt_pk_bf16_f32 v34, v34, v35
	v_cvt_pk_bf16_f32 v35, v36, v37
	v_fmac_f32_e32 v70, v36, v36
	v_cvt_pk_bf16_f32 v36, v46, v47
	v_cvt_pk_bf16_f32 v37, v48, v49
	ds_bpermute_b32 v176, v255, v34
	ds_bpermute_b32 v177, v255, v35
	ds_bpermute_b32 v178, v255, v36
	ds_bpermute_b32 v179, v255, v37
	v_add_u32_e32 v174, v68, v180
	s_waitcnt lgkmcnt(0)
	global_store_dwordx4 v174, v[176:179], s[10:11]
	v_add_f32_e32 v69, v69, v70
	v_mul_f32_e32 v70, v47, v47
	v_mul_f32_e32 v34, v39, v39
	v_mul_f32_e32 v35, v41, v41
	v_fmac_f32_e32 v34, v38, v38
	v_fmac_f32_e32 v35, v40, v40
	v_add_f32_e32 v34, v34, v35
	v_mul_f32_e32 v35, v55, v55
	v_fmac_f32_e32 v70, v46, v46
	v_fmac_f32_e32 v35, v54, v54
	v_add_f32_e32 v69, v69, v70
	v_mul_f32_e32 v70, v49, v49
	v_add_f32_e32 v34, v34, v35
	v_mul_f32_e32 v35, v57, v57
	v_fmac_f32_e32 v70, v48, v48
	v_fmac_f32_e32 v35, v56, v56
	v_add_f32_e32 v69, v70, v69
	v_add_f32_e32 v34, v35, v34
	v_add_f32_e32 v46, v69, v34
	v_cvt_pk_bf16_f32 v34, v38, v39
	ds_bpermute_b32 v38, v172, v46
	v_cvt_pk_bf16_f32 v35, v40, v41
	v_cvt_pk_bf16_f32 v36, v54, v55
	v_cvt_pk_bf16_f32 v37, v56, v57
	ds_bpermute_b32 v176, v255, v34
	ds_bpermute_b32 v177, v255, v35
	ds_bpermute_b32 v178, v255, v36
	ds_bpermute_b32 v179, v255, v37
	v_add_u32_e32 v174, v68, v180
	s_waitcnt lgkmcnt(0)
	global_store_dwordx4 v174, v[176:179], s[10:11] offset:256
	v_cmp_lt_i32_e64 s[8:9], 0, v1
	s_mov_b64 s[0:1], 0
	v_add_u32_e32 v36, 0x120000, v151
	v_lshrrev_b32_e32 v40, 1, v36
	v_cvt_pk_bf16_f32 v36, v10, v11
	s_waitcnt lgkmcnt(0)
	v_add_f32_e32 v34, v46, v38
	v_cvt_pk_bf16_f32 v37, v12, v13
	v_cvt_pk_bf16_f32 v38, v6, v7
	v_cvt_pk_bf16_f32 v39, v8, v9
	ds_bpermute_b32 v176, v255, v36
	ds_bpermute_b32 v177, v255, v37
	ds_bpermute_b32 v178, v255, v38
	ds_bpermute_b32 v179, v255, v39
	v_add_u32_e32 v174, v40, v180
	s_waitcnt lgkmcnt(0)
	global_store_dwordx4 v174, v[176:179], s[10:11]
	ds_bpermute_b32 v35, v173, v34
	s_mov_b64 s[2:3], 0
	v_mov_b32_e32 v36, v10
	v_mov_b32_e32 v10, v11
	v_mov_b32_e32 v11, v15
	v_mov_b32_e32 v37, v14
	v_pk_mul_f32 v[10:11], v[10:11], v[10:11]
	s_nop 0
	v_pk_fma_f32 v[10:11], v[36:37], v[36:37], v[10:11]
	v_mov_b32_e32 v36, v12
	v_mov_b32_e32 v12, v13
	v_mov_b32_e32 v13, v17
	v_mov_b32_e32 v37, v16
	v_pk_mul_f32 v[12:13], v[12:13], v[12:13]
	s_nop 0
	v_pk_fma_f32 v[12:13], v[36:37], v[36:37], v[12:13]
	s_nop 0
	v_pk_add_f32 v[10:11], v[10:11], v[12:13]
	v_mov_b32_e32 v12, v6
	v_mov_b32_e32 v6, v7
	v_mov_b32_e32 v7, v27
	v_mov_b32_e32 v13, v26
	v_pk_mul_f32 v[6:7], v[6:7], v[6:7]
	s_nop 0
	v_pk_fma_f32 v[6:7], v[12:13], v[12:13], v[6:7]
	s_nop 0
	v_pk_add_f32 v[6:7], v[10:11], v[6:7]
	v_mov_b32_e32 v10, v8
	v_mov_b32_e32 v8, v9
	v_mov_b32_e32 v9, v29
	v_mov_b32_e32 v11, v28
	v_pk_mul_f32 v[8:9], v[8:9], v[8:9]
	s_nop 0
	v_pk_fma_f32 v[8:9], v[10:11], v[10:11], v[8:9]
	s_nop 0
	v_pk_add_f32 v[6:7], v[8:9], v[6:7]
	s_nop 0
	v_add_f32_e32 v10, v6, v7
	v_cvt_pk_bf16_f32 v6, v14, v15
	v_cvt_pk_bf16_f32 v7, v16, v17
	v_cvt_pk_bf16_f32 v8, v26, v27
	v_cvt_pk_bf16_f32 v9, v28, v29
	ds_bpermute_b32 v176, v255, v6
	ds_bpermute_b32 v177, v255, v7
	ds_bpermute_b32 v178, v255, v8
	ds_bpermute_b32 v179, v255, v9
	v_add_u32_e32 v174, v40, v180
	s_waitcnt lgkmcnt(0)
; __device__ __forceinline__ float sum_16_32(float v) { v += __shfl_xor(v, 16); v += __shfl_xor(v, 32); return v; }
; __device__ __forceinline__ unsigned cvt_pk_bf16(float lo, float hi) { unsigned r; asm volatile("v_cvt_pk_bf16_f32 %0, %1, %2" : "=v"(r) : "v"(lo), "v"(hi)); return r; }
;     __device__ __forceinline__ void operator()(const f32x4 (&acc)[2][2][4][2], const Unit& u, int wr, int wc, int fr, int fq) const {
;     ...
;         for (int ai = 0; ai < 2; ++ai) { float sm[4];
; #pragma unroll
;             for (int m = 0; m < 4; ++m) { const unsigned o = ob0 + (unsigned)((ai * HALF + m * 16) * LDC * 4); float s = 0.f;
; #pragma unroll
;                 for (int bj = 0; bj < 2; ++bj) {
;                     const f32x4 o0 = acc[ai][bj][m][0], o1 = acc[ai][bj][m][1];
;                     s += (o0[0] * o0[0] + o0[1] * o0[1]) + (o0[2] * o0[2] + o0[3] * o0[3]) + (o1[0] * o1[0] + o1[1] * o1[1]) + (o1[2] * o1[2] + o1[3] * o1[3]);
;                     if (wf32) { *(f32x4*)(ob + o + bj * HALF * 4) = o0; *(f32x4*)(ob + o + bj * HALF * 4 + 16) = o1; }
;                     else { u32x4 w; w.x = cvt_pk_bf16(o0[0], o0[1]); w.y = cvt_pk_bf16(o0[2], o0[3]); w.z = cvt_pk_bf16(o1[0], o1[1]); w.w = cvt_pk_bf16(o1[2], o1[3]);
;                            *(u32x4*)(xbb + (o >> 1) + bj * HALF * 2) = w; } }
;                 s = sum_16_32(s);
;                 sm[m] = s; }
;             ss[(size_t)(4 * u.pn + wc) * 16384 + u.pm * BM + wr * 64 + ai * HALF + 16 * fq + fr] = fq == 0 ? sm[0] : (fq == 1 ? sm[1] : (fq == 2 ? sm[2] : sm[3])); }
	global_store_dwordx4 v174, v[176:179], s[10:11] offset:256
	ds_bpermute_b32 v11, v172, v10
	v_mul_f32_e32 v15, v21, v21
	v_add_u32_e32 v8, 0x140000, v151
	v_lshrrev_b32_e32 v12, 1, v8
	v_mul_f32_e32 v8, v43, v43
	v_mul_f32_e32 v9, v45, v45
	v_fmac_f32_e32 v8, v42, v42
	v_fmac_f32_e32 v9, v44, v44
	v_add_f32_e32 v8, v8, v9
	v_mul_f32_e32 v9, v59, v59
	v_fmac_f32_e32 v9, v58, v58
	v_add_f32_e32 v8, v8, v9
	v_mul_f32_e32 v9, v61, v61
	v_fmac_f32_e32 v9, v60, v60
	v_add_f32_e32 v13, v9, v8
	v_cvt_pk_bf16_f32 v8, v42, v43
	v_cvt_pk_bf16_f32 v9, v44, v45
	s_waitcnt lgkmcnt(0)
	v_add_f32_e32 v6, v10, v11
	v_cvt_pk_bf16_f32 v10, v58, v59
	v_cvt_pk_bf16_f32 v11, v60, v61
	ds_bpermute_b32 v176, v255, v8
	ds_bpermute_b32 v177, v255, v9
	ds_bpermute_b32 v178, v255, v10
	ds_bpermute_b32 v179, v255, v11
	v_add_u32_e32 v174, v12, v180
	s_waitcnt lgkmcnt(0)
	global_store_dwordx4 v174, v[176:179], s[10:11]
	v_fmac_f32_e32 v15, v20, v20
	ds_bpermute_b32 v7, v173, v6
	v_mul_f32_e32 v8, v51, v51
	v_mul_f32_e32 v9, v53, v53
	v_fmac_f32_e32 v8, v50, v50
	v_fmac_f32_e32 v9, v52, v52
	v_add_f32_e32 v8, v8, v9
	v_mul_f32_e32 v9, v63, v63
	v_fmac_f32_e32 v9, v62, v62
	v_add_f32_e32 v8, v8, v9
	v_mul_f32_e32 v9, v65, v65
	v_fmac_f32_e32 v9, v64, v64
	v_add_f32_e32 v8, v9, v8
	v_add_f32_e32 v13, v13, v8
	ds_bpermute_b32 v14, v172, v13
	v_cvt_pk_bf16_f32 v8, v50, v51
	v_cvt_pk_bf16_f32 v9, v52, v53
	v_cvt_pk_bf16_f32 v10, v62, v63
	v_cvt_pk_bf16_f32 v11, v64, v65
	ds_bpermute_b32 v176, v255, v8
	ds_bpermute_b32 v177, v255, v9
	ds_bpermute_b32 v178, v255, v10
	ds_bpermute_b32 v179, v255, v11
	v_add_u32_e32 v174, v12, v180
	s_waitcnt lgkmcnt(0)
	global_store_dwordx4 v174, v[176:179], s[10:11] offset:256
	s_nop 1
	v_add_u32_e32 v10, 0x160000, v151
	s_waitcnt lgkmcnt(0)
	v_add_f32_e32 v8, v13, v14
	v_lshrrev_b32_e32 v14, 1, v10
	v_mul_f32_e32 v10, v23, v23
	v_mul_f32_e32 v11, v25, v25
	v_mul_f32_e32 v13, v19, v19
	v_fmac_f32_e32 v10, v22, v22
	v_fmac_f32_e32 v11, v24, v24
	v_fmac_f32_e32 v13, v18, v18
	v_add_f32_e32 v10, v10, v11
	v_mul_f32_e32 v11, v3, v3
	v_add_f32_e32 v13, v13, v15
	v_mul_f32_e32 v15, v31, v31
	v_fmac_f32_e32 v11, v2, v2
	v_fmac_f32_e32 v15, v30, v30
	v_add_f32_e32 v10, v10, v11
	v_mul_f32_e32 v11, v5, v5
	v_add_f32_e32 v13, v13, v15
	v_mul_f32_e32 v15, v33, v33
	v_fmac_f32_e32 v11, v4, v4
	v_fmac_f32_e32 v15, v32, v32
	v_add_f32_e32 v12, v11, v10
	v_add_f32_e32 v13, v15, v13
	v_add_f32_e32 v15, v12, v13
	ds_bpermute_b32 v16, v172, v15
	v_cvt_pk_bf16_f32 v10, v22, v23
	v_cvt_pk_bf16_f32 v11, v24, v25
	v_cvt_pk_bf16_f32 v12, v2, v3
	ds_bpermute_b32 v9, v173, v8
	s_waitcnt lgkmcnt(0)
	v_add_f32_e32 v3, v15, v16
	v_cvt_pk_bf16_f32 v13, v4, v5
	ds_bpermute_b32 v4, v173, v3
	ds_bpermute_b32 v176, v255, v10
	ds_bpermute_b32 v177, v255, v11
	ds_bpermute_b32 v178, v255, v12
	ds_bpermute_b32 v179, v255, v13
	v_add_u32_e32 v174, v14, v180
	s_waitcnt lgkmcnt(0)
	global_store_dwordx4 v174, v[176:179], s[10:11]
	s_nop 1
	v_cvt_pk_bf16_f32 v10, v18, v19
	v_cvt_pk_bf16_f32 v11, v20, v21
	v_cvt_pk_bf16_f32 v12, v30, v31
	v_cvt_pk_bf16_f32 v13, v32, v33
	ds_bpermute_b32 v176, v255, v10
	ds_bpermute_b32 v177, v255, v11
	ds_bpermute_b32 v178, v255, v12
	ds_bpermute_b32 v179, v255, v13
	v_add_u32_e32 v174, v14, v180
	s_waitcnt lgkmcnt(0)
	global_store_dwordx4 v174, v[176:179], s[10:11] offset:256
	s_and_saveexec_b64 s[26:27], s[8:9]
	s_xor_b64 s[26:27], exec, s[26:27]
	s_cbranch_execz .LBB0_560
	v_cmp_ne_u32_e64 s[8:9], 1, v1
	v_add_f32_e32 v2, v6, v7
	s_and_b64 s[2:3], s[8:9], exec
	s_andn2_saveexec_b64 s[8:9], s[26:27]
	s_cbranch_execnz .LBB0_561
